# S8 plus all GEMM main loops: LDS-DMA loads use scalar base + 32-bit vgpr offset (saddr form), 16 v_lshl_add_u64 per iteration removed
# speedup vs baseline: 1.0094x; 1.0094x over previous
; #define PG8_STAGE(bufoff, gbase, voff) do { _Pragma("unroll") for (int _i = 0; _i < 2; ++_i) \
;         __builtin_amdgcn_global_load_lds((const unsigned*)((const char*)(gbase) + (voff)[_i]), (LAS unsigned*)(lds + (bufoff) + ldsw + _i * 8192), 16, 0, 0); } while (0)
; #define PG8_LDA(dst, b, h) do { _Pragma("unroll") for (int m = 0; m < 4; ++m) _Pragma("unroll") for (int k = 0; k < 2; ++k) dst[m][k] = *(const LAS bf16x8*)(lds + PG8_SA(b, h) + aoff + m * 2048 + k * 1024); } while (0)
; #define PG8_LDB(dst, b, h) do { _Pragma("unroll") for (int n = 0; n < 2; ++n) _Pragma("unroll") for (int k = 0; k < 2; ++k) dst[n][k] = *(const LAS bf16x8*)(lds + PG8_SB(b, h) + boff + n * 2048 + k * 1024); } while (0)
; #define PG8_WAIT_V(n) asm volatile("s_waitcnt vmcnt(" #n ")" ::: "memory")
; template <int K, int LDA, int LDB, class Epi, class Sched>
; __device__ __forceinline__ void gemm_phase(LAS unsigned char* lds, const Gemm g, const Sched& S, const Epi& E, int wv) {
;     ...
;         for (int t = 0; t < nt; t += 2) {
;             const bool last = (t == nt - 2);
;             const char* a1 = cA + (size_t)(t + 1) * kstep;
;             const char* a2 = last ? nA : cA + (size_t)(t + 2) * kstep; const char* b2 = last ? nB : cB + (size_t)(t + 2) * kstep;
;             const char* a3 = a2 + kstep; const char* b3 = b2 + kstep;
;             PG8_LDB(B0, 0, 0); PG8_LDB(B1, 0, 1); PG8_SCHED; PG8_LDA(At, 0, 0); PG8_STAGE(PG8_SA(1, 1), a1 + hstepA, voffA);
;             PG8_WAIT_V(8); PG8_WAIT_L(0); PG8_BAR; PG8_MMA(0, 0, At, B0); PG8_MMA(0, 1, At, B1); PG8_BAR; PG8_SCHED;
;             PG8_LDA(At, 0, 1); PG8_STAGE(PG8_SB(0, 0), b2, voffB); PG8_STAGE(PG8_SB(0, 1), b2 + hstepB, voffB); PG8_STAGE(PG8_SA(0, 0), a2, voffA);
;             PG8_WAIT_V(8); PG8_WAIT_L(0); PG8_BAR; PG8_MMA(1, 0, At, B0); PG8_MMA(1, 1, At, B1); PG8_BAR; PG8_SCHED;
;             PG8_LDB(B0, 1, 0); PG8_LDB(B1, 1, 1); PG8_SCHED; PG8_LDA(At, 1, 0); PG8_STAGE(PG8_SA(0, 1), a2 + hstepA, voffA);
;             PG8_WAIT_V(8); PG8_WAIT_L(0); PG8_BAR; PG8_MMA(0, 0, At, B0); PG8_MMA(0, 1, At, B1); PG8_BAR; PG8_SCHED;
;             PG8_LDA(At, 1, 1); PG8_STAGE(PG8_SB(1, 0), b3, voffB); PG8_STAGE(PG8_SB(1, 1), b3 + hstepB, voffB); PG8_STAGE(PG8_SA(1, 0), a3, voffA);
;             PG8_WAIT_V(8); PG8_WAIT_L(0); PG8_BAR; PG8_MMA(1, 0, At, B0); PG8_MMA(1, 1, At, B1); PG8_BAR; PG8_SCHED;
.LBB0_273:
	s_waitcnt lgkmcnt(0)
	ds_read_b128 v[152:155], v163
	ds_read_b128 v[156:159], v163 offset:1024
	ds_read_b128 v[166:169], v163 offset:2048
	ds_read_b128 v[170:173], v163 offset:3072
	ds_read_b128 v[174:177], v164
	ds_read_b128 v[178:181], v164 offset:1024
	ds_read_b128 v[182:185], v164 offset:2048
	ds_read_b128 v[186:189], v164 offset:3072
	s_add_u32 s14, s74, 0xfff80080
	s_addc_u32 s15, s75, -1
	s_cmp_eq_u32 s89, 28
	s_cselect_b32 s79, s65, s15
	s_cselect_b32 s78, s71, s14
	s_cselect_b32 s77, s63, s88
	s_cselect_b32 s76, s80, s84
	s_add_i32 m0, s41, 0xc000
	ds_read_b128 v[190:193], v165
	ds_read_b128 v[194:197], v165 offset:1024
	ds_read_b128 v[198:201], v165 offset:2048
	ds_read_b128 v[202:205], v165 offset:3072
	ds_read_b128 v[206:209], v165 offset:4096
	ds_read_b128 v[210:213], v165 offset:5120
	ds_read_b128 v[214:217], v165 offset:6144
	ds_read_b128 v[218:221], v165 offset:7168
	global_load_lds_dwordx4 v144, s[74:75]
	s_add_i32 m0, s41, 0xe000
	s_nop 0
	global_load_lds_dwordx4 v146, s[74:75]
	s_waitcnt vmcnt(8)
	s_waitcnt lgkmcnt(0)
	s_barrier
	s_setprio 1
	s_waitcnt lgkmcnt(0)
	v_mfma_f32_16x16x32_bf16 v[60:63], v[152:155], v[190:193], v[60:63]
	v_mfma_f32_16x16x32_bf16 v[56:59], v[166:169], v[190:193], v[56:59]
	v_mfma_f32_16x16x32_bf16 v[52:55], v[152:155], v[198:201], v[52:55]
	v_mfma_f32_16x16x32_bf16 v[48:51], v[166:169], v[198:201], v[48:51]
	v_mfma_f32_16x16x32_bf16 v[44:47], v[152:155], v[206:209], v[44:47]
	v_mfma_f32_16x16x32_bf16 v[40:43], v[166:169], v[206:209], v[40:43]
	v_mfma_f32_16x16x32_bf16 v[36:39], v[152:155], v[214:217], v[36:39]
	v_mfma_f32_16x16x32_bf16 v[32:35], v[166:169], v[214:217], v[32:35]
	v_mfma_f32_16x16x32_bf16 v[60:63], v[156:159], v[194:197], v[60:63]
	v_mfma_f32_16x16x32_bf16 v[56:59], v[170:173], v[194:197], v[56:59]
	v_mfma_f32_16x16x32_bf16 v[52:55], v[156:159], v[202:205], v[52:55]
	v_mfma_f32_16x16x32_bf16 v[48:51], v[170:173], v[202:205], v[48:51]
	v_mfma_f32_16x16x32_bf16 v[44:47], v[156:159], v[210:213], v[44:47]
	v_mfma_f32_16x16x32_bf16 v[40:43], v[170:173], v[210:213], v[40:43]
	v_mfma_f32_16x16x32_bf16 v[36:39], v[156:159], v[218:221], v[36:39]
	v_mfma_f32_16x16x32_bf16 v[32:35], v[170:173], v[218:221], v[32:35]
	s_setprio 0
	s_setprio 1
	v_mfma_f32_16x16x32_bf16 v[124:127], v[174:177], v[190:193], v[124:127]
	v_mfma_f32_16x16x32_bf16 v[120:123], v[182:185], v[190:193], v[120:123]
	v_mfma_f32_16x16x32_bf16 v[116:119], v[174:177], v[198:201], v[116:119]
	v_mfma_f32_16x16x32_bf16 v[112:115], v[182:185], v[198:201], v[112:115]
	v_mfma_f32_16x16x32_bf16 v[108:111], v[174:177], v[206:209], v[108:111]
	v_mfma_f32_16x16x32_bf16 v[104:107], v[182:185], v[206:209], v[104:107]
	v_mfma_f32_16x16x32_bf16 v[100:103], v[174:177], v[214:217], v[100:103]
	v_mfma_f32_16x16x32_bf16 v[96:99], v[182:185], v[214:217], v[96:99]
	v_mfma_f32_16x16x32_bf16 v[124:127], v[178:181], v[194:197], v[124:127]
	v_mfma_f32_16x16x32_bf16 v[120:123], v[186:189], v[194:197], v[120:123]
	v_mfma_f32_16x16x32_bf16 v[116:119], v[178:181], v[202:205], v[116:119]
	v_mfma_f32_16x16x32_bf16 v[112:115], v[186:189], v[202:205], v[112:115]
	v_mfma_f32_16x16x32_bf16 v[108:111], v[178:181], v[210:213], v[108:111]
	v_mfma_f32_16x16x32_bf16 v[104:107], v[186:189], v[210:213], v[104:107]
	v_mfma_f32_16x16x32_bf16 v[100:103], v[178:181], v[218:221], v[100:103]
	v_mfma_f32_16x16x32_bf16 v[96:99], v[186:189], v[218:221], v[96:99]
	s_setprio 0
	s_barrier
	s_add_i32 s14, s82, s24
	s_mov_b32 m0, s14
	ds_read_b128 v[190:193], v165 offset:16384
	ds_read_b128 v[194:197], v165 offset:17408
	ds_read_b128 v[198:201], v165 offset:18432
	ds_read_b128 v[202:205], v165 offset:19456
	ds_read_b128 v[206:209], v165 offset:20480
	ds_read_b128 v[210:213], v165 offset:21504
	ds_read_b128 v[214:217], v165 offset:22528
	ds_read_b128 v[218:221], v165 offset:23552
	global_load_lds_dwordx4 v130, s[76:77]
	s_add_i32 m0, s14, 0x2000
	s_add_u32 s14, s76, 0x80000
	s_addc_u32 s15, s77, 0
	s_add_i32 s34, s83, s24
	global_load_lds_dwordx4 v134, s[76:77]
	s_mov_b32 m0, s34
	s_nop 0
	global_load_lds_dwordx4 v130, s[14:15]
	s_add_i32 m0, s34, 0x2000
	s_nop 0
	global_load_lds_dwordx4 v134, s[14:15]
	s_mov_b32 m0, s41
	s_nop 0
	global_load_lds_dwordx4 v128, s[78:79]
	s_mov_b32 m0, s43
	s_nop 0
	global_load_lds_dwordx4 v132, s[78:79]
	s_waitcnt vmcnt(8)
	s_waitcnt lgkmcnt(0)
	s_barrier
	s_setprio 1
	s_waitcnt lgkmcnt(0)
	v_mfma_f32_16x16x32_bf16 v[28:31], v[152:155], v[190:193], v[28:31]
	v_mfma_f32_16x16x32_bf16 v[24:27], v[166:169], v[190:193], v[24:27]
	v_mfma_f32_16x16x32_bf16 v[20:23], v[152:155], v[198:201], v[20:23]
	v_mfma_f32_16x16x32_bf16 v[16:19], v[166:169], v[198:201], v[16:19]
	v_mfma_f32_16x16x32_bf16 v[12:15], v[152:155], v[206:209], v[12:15]
	v_mfma_f32_16x16x32_bf16 v[8:11], v[166:169], v[206:209], v[8:11]
	v_mfma_f32_16x16x32_bf16 v[4:7], v[152:155], v[214:217], v[4:7]
	v_mfma_f32_16x16x32_bf16 v[0:3], v[166:169], v[214:217], v[0:3]
	v_mfma_f32_16x16x32_bf16 v[28:31], v[156:159], v[194:197], v[28:31]
	v_mfma_f32_16x16x32_bf16 v[24:27], v[170:173], v[194:197], v[24:27]
	v_mfma_f32_16x16x32_bf16 v[20:23], v[156:159], v[202:205], v[20:23]
	v_mfma_f32_16x16x32_bf16 v[16:19], v[170:173], v[202:205], v[16:19]
	v_mfma_f32_16x16x32_bf16 v[12:15], v[156:159], v[210:213], v[12:15]
	v_mfma_f32_16x16x32_bf16 v[8:11], v[170:173], v[210:213], v[8:11]
	v_mfma_f32_16x16x32_bf16 v[4:7], v[156:159], v[218:221], v[4:7]
	v_mfma_f32_16x16x32_bf16 v[0:3], v[170:173], v[218:221], v[0:3]
	s_setprio 0
	s_setprio 1
	v_mfma_f32_16x16x32_bf16 v[92:95], v[174:177], v[190:193], v[92:95]
	v_mfma_f32_16x16x32_bf16 v[88:91], v[182:185], v[190:193], v[88:91]
	v_mfma_f32_16x16x32_bf16 v[84:87], v[174:177], v[198:201], v[84:87]
	v_mfma_f32_16x16x32_bf16 v[80:83], v[182:185], v[198:201], v[80:83]
	v_mfma_f32_16x16x32_bf16 v[76:79], v[174:177], v[206:209], v[76:79]
	v_mfma_f32_16x16x32_bf16 v[72:75], v[182:185], v[206:209], v[72:75]
	v_mfma_f32_16x16x32_bf16 v[68:71], v[174:177], v[214:217], v[68:71]
	v_mfma_f32_16x16x32_bf16 v[64:67], v[182:185], v[214:217], v[64:67]
	v_mfma_f32_16x16x32_bf16 v[92:95], v[178:181], v[194:197], v[92:95]
	v_mfma_f32_16x16x32_bf16 v[88:91], v[186:189], v[194:197], v[88:91]
	v_mfma_f32_16x16x32_bf16 v[84:87], v[178:181], v[202:205], v[84:87]
	v_mfma_f32_16x16x32_bf16 v[80:83], v[186:189], v[202:205], v[80:83]
	v_mfma_f32_16x16x32_bf16 v[76:79], v[178:181], v[210:213], v[76:79]
	v_mfma_f32_16x16x32_bf16 v[72:75], v[186:189], v[210:213], v[72:75]
	v_mfma_f32_16x16x32_bf16 v[68:71], v[178:181], v[218:221], v[68:71]
	v_mfma_f32_16x16x32_bf16 v[64:67], v[186:189], v[218:221], v[64:67]
	s_setprio 0
	s_barrier
; #define PG8_STAGE(bufoff, gbase, voff) do { _Pragma("unroll") for (int _i = 0; _i < 2; ++_i) \
;         __builtin_amdgcn_global_load_lds((const unsigned*)((const char*)(gbase) + (voff)[_i]), (LAS unsigned*)(lds + (bufoff) + ldsw + _i * 8192), 16, 0, 0); } while (0)
; #define PG8_LDA(dst, b, h) do { _Pragma("unroll") for (int m = 0; m < 4; ++m) _Pragma("unroll") for (int k = 0; k < 2; ++k) dst[m][k] = *(const LAS bf16x8*)(lds + PG8_SA(b, h) + aoff + m * 2048 + k * 1024); } while (0)
; #define PG8_LDB(dst, b, h) do { _Pragma("unroll") for (int n = 0; n < 2; ++n) _Pragma("unroll") for (int k = 0; k < 2; ++k) dst[n][k] = *(const LAS bf16x8*)(lds + PG8_SB(b, h) + boff + n * 2048 + k * 1024); } while (0)
; #define PG8_WAIT_V(n) asm volatile("s_waitcnt vmcnt(" #n ")" ::: "memory")
; template <int K, int LDA, int LDB, class Epi, class Sched>
; __device__ __forceinline__ void gemm_phase(LAS unsigned char* lds, const Gemm g, const Sched& S, const Epi& E, int wv) {
;     ...
;         for (int t = 0; t < nt; t += 2) {
;             const bool last = (t == nt - 2);
;             const char* a1 = cA + (size_t)(t + 1) * kstep;
;             const char* a2 = last ? nA : cA + (size_t)(t + 2) * kstep; const char* b2 = last ? nB : cB + (size_t)(t + 2) * kstep;
;             const char* a3 = a2 + kstep; const char* b3 = b2 + kstep;
;             PG8_LDB(B0, 0, 0); PG8_LDB(B1, 0, 1); PG8_SCHED; PG8_LDA(At, 0, 0); PG8_STAGE(PG8_SA(1, 1), a1 + hstepA, voffA);
;             PG8_WAIT_V(8); PG8_WAIT_L(0); PG8_BAR; PG8_MMA(0, 0, At, B0); PG8_MMA(0, 1, At, B1); PG8_BAR; PG8_SCHED;
;             PG8_LDA(At, 0, 1); PG8_STAGE(PG8_SB(0, 0), b2, voffB); PG8_STAGE(PG8_SB(0, 1), b2 + hstepB, voffB); PG8_STAGE(PG8_SA(0, 0), a2, voffA);
;             PG8_WAIT_V(8); PG8_WAIT_L(0); PG8_BAR; PG8_MMA(1, 0, At, B0); PG8_MMA(1, 1, At, B1); PG8_BAR; PG8_SCHED;
;             PG8_LDB(B0, 1, 0); PG8_LDB(B1, 1, 1); PG8_SCHED; PG8_LDA(At, 1, 0); PG8_STAGE(PG8_SA(0, 1), a2 + hstepA, voffA);
;             PG8_WAIT_V(8); PG8_WAIT_L(0); PG8_BAR; PG8_MMA(0, 0, At, B0); PG8_MMA(0, 1, At, B1); PG8_BAR; PG8_SCHED;
;             PG8_LDA(At, 1, 1); PG8_STAGE(PG8_SB(1, 0), b3, voffB); PG8_STAGE(PG8_SB(1, 1), b3 + hstepB, voffB); PG8_STAGE(PG8_SA(1, 0), a3, voffA);
;             PG8_WAIT_V(8); PG8_WAIT_L(0); PG8_BAR; PG8_MMA(1, 0, At, B0); PG8_MMA(1, 1, At, B1); PG8_BAR; PG8_SCHED;
	s_add_i32 s34, 0, 0x18000
	v_add_u32_e32 v136, s34, v161
	s_add_i32 s35, 0, 0x1c000
	ds_read_b128 v[152:155], v136
	ds_read_b128 v[156:159], v136 offset:1024
	ds_read_b128 v[166:169], v136 offset:2048
	ds_read_b128 v[170:173], v136 offset:3072
	v_add_u32_e32 v136, s35, v161
	ds_read_b128 v[174:177], v136
	ds_read_b128 v[178:181], v136 offset:1024
	ds_read_b128 v[182:185], v136 offset:2048
	ds_read_b128 v[186:189], v136 offset:3072
	s_add_u32 s14, s78, 0x80000
	s_addc_u32 s15, s79, 0
	s_mov_b32 m0, s51
	ds_read_b128 v[190:193], v165 offset:32768
	ds_read_b128 v[194:197], v165 offset:33792
	ds_read_b128 v[198:201], v165 offset:34816
	ds_read_b128 v[202:205], v165 offset:35840
	ds_read_b128 v[206:209], v165 offset:36864
	ds_read_b128 v[210:213], v165 offset:37888
	ds_read_b128 v[214:217], v165 offset:38912
	ds_read_b128 v[218:221], v165 offset:39936
	global_load_lds_dwordx4 v128, s[14:15]
	s_mov_b32 m0, s59
	s_nop 0
	global_load_lds_dwordx4 v132, s[14:15]
	s_waitcnt vmcnt(8)
	s_waitcnt lgkmcnt(0)
	s_barrier
	s_setprio 1
	s_waitcnt lgkmcnt(0)
	v_mfma_f32_16x16x32_bf16 v[60:63], v[152:155], v[190:193], v[60:63]
	v_mfma_f32_16x16x32_bf16 v[56:59], v[166:169], v[190:193], v[56:59]
	v_mfma_f32_16x16x32_bf16 v[52:55], v[152:155], v[198:201], v[52:55]
	v_mfma_f32_16x16x32_bf16 v[48:51], v[166:169], v[198:201], v[48:51]
	v_mfma_f32_16x16x32_bf16 v[44:47], v[152:155], v[206:209], v[44:47]
	v_mfma_f32_16x16x32_bf16 v[40:43], v[166:169], v[206:209], v[40:43]
	v_mfma_f32_16x16x32_bf16 v[36:39], v[152:155], v[214:217], v[36:39]
	v_mfma_f32_16x16x32_bf16 v[32:35], v[166:169], v[214:217], v[32:35]
	v_mfma_f32_16x16x32_bf16 v[60:63], v[156:159], v[194:197], v[60:63]
	v_mfma_f32_16x16x32_bf16 v[56:59], v[170:173], v[194:197], v[56:59]
	v_mfma_f32_16x16x32_bf16 v[52:55], v[156:159], v[202:205], v[52:55]
	v_mfma_f32_16x16x32_bf16 v[48:51], v[170:173], v[202:205], v[48:51]
	v_mfma_f32_16x16x32_bf16 v[44:47], v[156:159], v[210:213], v[44:47]
	v_mfma_f32_16x16x32_bf16 v[40:43], v[170:173], v[210:213], v[40:43]
	v_mfma_f32_16x16x32_bf16 v[36:39], v[156:159], v[218:221], v[36:39]
	v_mfma_f32_16x16x32_bf16 v[32:35], v[170:173], v[218:221], v[32:35]
	s_setprio 0
	s_setprio 1
	v_mfma_f32_16x16x32_bf16 v[124:127], v[174:177], v[190:193], v[124:127]
	v_mfma_f32_16x16x32_bf16 v[120:123], v[182:185], v[190:193], v[120:123]
	v_mfma_f32_16x16x32_bf16 v[116:119], v[174:177], v[198:201], v[116:119]
	v_mfma_f32_16x16x32_bf16 v[112:115], v[182:185], v[198:201], v[112:115]
	v_mfma_f32_16x16x32_bf16 v[108:111], v[174:177], v[206:209], v[108:111]
	v_mfma_f32_16x16x32_bf16 v[104:107], v[182:185], v[206:209], v[104:107]
	v_mfma_f32_16x16x32_bf16 v[100:103], v[174:177], v[214:217], v[100:103]
	v_mfma_f32_16x16x32_bf16 v[96:99], v[182:185], v[214:217], v[96:99]
	v_mfma_f32_16x16x32_bf16 v[124:127], v[178:181], v[194:197], v[124:127]
	v_mfma_f32_16x16x32_bf16 v[120:123], v[186:189], v[194:197], v[120:123]
	v_mfma_f32_16x16x32_bf16 v[116:119], v[178:181], v[202:205], v[116:119]
	v_mfma_f32_16x16x32_bf16 v[112:115], v[186:189], v[202:205], v[112:115]
	v_mfma_f32_16x16x32_bf16 v[108:111], v[178:181], v[210:213], v[108:111]
	v_mfma_f32_16x16x32_bf16 v[104:107], v[186:189], v[210:213], v[104:107]
	v_mfma_f32_16x16x32_bf16 v[100:103], v[178:181], v[218:221], v[100:103]
	v_mfma_f32_16x16x32_bf16 v[96:99], v[186:189], v[218:221], v[96:99]
	s_setprio 0
	s_barrier
	s_add_i32 s14, s34, s24
	s_mov_b32 m0, s14
	ds_read_b128 v[190:193], v165 offset:49152
	ds_read_b128 v[194:197], v165 offset:50176
	ds_read_b128 v[198:201], v165 offset:51200
	ds_read_b128 v[202:205], v165 offset:52224
	ds_read_b128 v[206:209], v165 offset:53248
	ds_read_b128 v[210:213], v165 offset:54272
	ds_read_b128 v[214:217], v165 offset:55296
	ds_read_b128 v[218:221], v165 offset:56320
	s_add_u32 s98, s76, s10
	s_addc_u32 s99, s77, s11
	global_load_lds_dwordx4 v130, s[98:99]
	s_add_i32 m0, s14, 0x2000
	s_add_u32 s14, s76, 0x80080
	s_addc_u32 s15, s77, 0
	s_add_i32 s34, s35, s24
	global_load_lds_dwordx4 v134, s[98:99]
	s_mov_b32 m0, s34
	s_nop 0
	global_load_lds_dwordx4 v130, s[14:15]
	s_add_i32 m0, s34, 0x2000
	s_nop 0
	global_load_lds_dwordx4 v134, s[14:15]
	s_mov_b32 m0, s61
	s_nop 0
	s_add_u32 s100, s78, s10
	s_addc_u32 s101, s79, s11
	global_load_lds_dwordx4 v128, s[100:101]
	s_mov_b32 m0, s73
	s_nop 0
	global_load_lds_dwordx4 v132, s[100:101]
	s_waitcnt vmcnt(8)
	s_waitcnt lgkmcnt(0)
	s_barrier
	s_setprio 1
	s_waitcnt lgkmcnt(0)
	v_mfma_f32_16x16x32_bf16 v[28:31], v[152:155], v[190:193], v[28:31]
	v_mfma_f32_16x16x32_bf16 v[24:27], v[166:169], v[190:193], v[24:27]
	v_mfma_f32_16x16x32_bf16 v[20:23], v[152:155], v[198:201], v[20:23]
	v_mfma_f32_16x16x32_bf16 v[16:19], v[166:169], v[198:201], v[16:19]
	v_mfma_f32_16x16x32_bf16 v[12:15], v[152:155], v[206:209], v[12:15]
	v_mfma_f32_16x16x32_bf16 v[8:11], v[166:169], v[206:209], v[8:11]
	v_mfma_f32_16x16x32_bf16 v[4:7], v[152:155], v[214:217], v[4:7]
	v_mfma_f32_16x16x32_bf16 v[0:3], v[166:169], v[214:217], v[0:3]
	v_mfma_f32_16x16x32_bf16 v[28:31], v[156:159], v[194:197], v[28:31]
	v_mfma_f32_16x16x32_bf16 v[24:27], v[170:173], v[194:197], v[24:27]
	v_mfma_f32_16x16x32_bf16 v[20:23], v[156:159], v[202:205], v[20:23]
	v_mfma_f32_16x16x32_bf16 v[16:19], v[170:173], v[202:205], v[16:19]
	v_mfma_f32_16x16x32_bf16 v[12:15], v[156:159], v[210:213], v[12:15]
	v_mfma_f32_16x16x32_bf16 v[8:11], v[170:173], v[210:213], v[8:11]
	v_mfma_f32_16x16x32_bf16 v[4:7], v[156:159], v[218:221], v[4:7]
	v_mfma_f32_16x16x32_bf16 v[0:3], v[170:173], v[218:221], v[0:3]
	s_setprio 0
	s_setprio 1
	v_mfma_f32_16x16x32_bf16 v[92:95], v[174:177], v[190:193], v[92:95]
	v_mfma_f32_16x16x32_bf16 v[88:91], v[182:185], v[190:193], v[88:91]
	v_mfma_f32_16x16x32_bf16 v[84:87], v[174:177], v[198:201], v[84:87]
	v_mfma_f32_16x16x32_bf16 v[80:83], v[182:185], v[198:201], v[80:83]
	v_mfma_f32_16x16x32_bf16 v[76:79], v[174:177], v[206:209], v[76:79]
	v_mfma_f32_16x16x32_bf16 v[72:75], v[182:185], v[206:209], v[72:75]
	v_mfma_f32_16x16x32_bf16 v[68:71], v[174:177], v[214:217], v[68:71]
	v_mfma_f32_16x16x32_bf16 v[64:67], v[182:185], v[214:217], v[64:67]
	v_mfma_f32_16x16x32_bf16 v[92:95], v[178:181], v[194:197], v[92:95]
	v_mfma_f32_16x16x32_bf16 v[88:91], v[186:189], v[194:197], v[88:91]
	v_mfma_f32_16x16x32_bf16 v[84:87], v[178:181], v[202:205], v[84:87]
	v_mfma_f32_16x16x32_bf16 v[80:83], v[186:189], v[202:205], v[80:83]
	v_mfma_f32_16x16x32_bf16 v[76:79], v[178:181], v[210:213], v[76:79]
	v_mfma_f32_16x16x32_bf16 v[72:75], v[186:189], v[210:213], v[72:75]
	v_mfma_f32_16x16x32_bf16 v[68:71], v[178:181], v[218:221], v[68:71]
	v_mfma_f32_16x16x32_bf16 v[64:67], v[186:189], v[218:221], v[64:67]
	s_setprio 0
	s_barrier
	s_add_i32 s89, s89, 2
	s_add_u32 s74, s74, 0x100
	s_addc_u32 s75, s75, 0
	s_add_u32 s84, s84, 0x100
	s_addc_u32 s88, s88, 0
	s_cmp_gt_u32 s89, 29
	s_cbranch_scc0 .LBB0_273
	s_and_b64 vcc, exec, s[28:29]
	s_cbranch_vccz .LBB0_276
	s_barrier

; #define PG8_STAGE(bufoff, gbase, voff) do { _Pragma("unroll") for (int _i = 0; _i < 2; ++_i) \
;         __builtin_amdgcn_global_load_lds((const unsigned*)((const char*)(gbase) + (voff)[_i]), (LAS unsigned*)(lds + (bufoff) + ldsw + _i * 8192), 16, 0, 0); } while (0)
; #define PG8_LDA(dst, b, h) do { _Pragma("unroll") for (int m = 0; m < 4; ++m) _Pragma("unroll") for (int k = 0; k < 2; ++k) dst[m][k] = *(const LAS bf16x8*)(lds + PG8_SA(b, h) + aoff + m * 2048 + k * 1024); } while (0)
; #define PG8_LDB(dst, b, h) do { _Pragma("unroll") for (int n = 0; n < 2; ++n) _Pragma("unroll") for (int k = 0; k < 2; ++k) dst[n][k] = *(const LAS bf16x8*)(lds + PG8_SB(b, h) + boff + n * 2048 + k * 1024); } while (0)
; #define PG8_WAIT_V(n) asm volatile("s_waitcnt vmcnt(" #n ")" ::: "memory")
; template <int K, int LDA, int LDB, class Epi, class Sched>
; __device__ __forceinline__ void gemm_phase(LAS unsigned char* lds, const Gemm g, const Sched& S, const Epi& E, int wv) {
;     ...
;         for (int t = 0; t < nt; t += 2) {
;             const bool last = (t == nt - 2);
;             const char* a1 = cA + (size_t)(t + 1) * kstep;
;             const char* a2 = last ? nA : cA + (size_t)(t + 2) * kstep; const char* b2 = last ? nB : cB + (size_t)(t + 2) * kstep;
;             const char* a3 = a2 + kstep; const char* b3 = b2 + kstep;
;             PG8_LDB(B0, 0, 0); PG8_LDB(B1, 0, 1); PG8_SCHED; PG8_LDA(At, 0, 0); PG8_STAGE(PG8_SA(1, 1), a1 + hstepA, voffA);
;             PG8_WAIT_V(8); PG8_WAIT_L(0); PG8_BAR; PG8_MMA(0, 0, At, B0); PG8_MMA(0, 1, At, B1); PG8_BAR; PG8_SCHED;
;             PG8_LDA(At, 0, 1); PG8_STAGE(PG8_SB(0, 0), b2, voffB); PG8_STAGE(PG8_SB(0, 1), b2 + hstepB, voffB); PG8_STAGE(PG8_SA(0, 0), a2, voffA);
;             PG8_WAIT_V(8); PG8_WAIT_L(0); PG8_BAR; PG8_MMA(1, 0, At, B0); PG8_MMA(1, 1, At, B1); PG8_BAR; PG8_SCHED;
;             PG8_LDB(B0, 1, 0); PG8_LDB(B1, 1, 1); PG8_SCHED; PG8_LDA(At, 1, 0); PG8_STAGE(PG8_SA(0, 1), a2 + hstepA, voffA);
;             PG8_WAIT_V(8); PG8_WAIT_L(0); PG8_BAR; PG8_MMA(0, 0, At, B0); PG8_MMA(0, 1, At, B1); PG8_BAR; PG8_SCHED;
;             PG8_LDA(At, 1, 1); PG8_STAGE(PG8_SB(1, 0), b3, voffB); PG8_STAGE(PG8_SB(1, 1), b3 + hstepB, voffB); PG8_STAGE(PG8_SA(1, 0), a3, voffA);
;             PG8_WAIT_V(8); PG8_WAIT_L(0); PG8_BAR; PG8_MMA(1, 0, At, B0); PG8_MMA(1, 1, At, B1); PG8_BAR; PG8_SCHED;
.LBB0_465:
	ds_read_b128 v[128:131], v201
	ds_read_b128 v[132:135], v201 offset:1024
	ds_read_b128 v[136:139], v201 offset:2048
	ds_read_b128 v[140:143], v201 offset:3072
	ds_read_b128 v[144:147], v205
	ds_read_b128 v[148:151], v205 offset:1024
	ds_read_b128 v[152:155], v205 offset:2048
	ds_read_b128 v[156:159], v205 offset:3072
	s_add_u32 s12, s66, 0x100
	s_addc_u32 s13, s67, 0
	s_cmp_eq_u32 s8, 4
	s_cselect_b32 s71, s61, s13
	s_cselect_b32 s70, s60, s12
	s_cselect_b32 s69, s59, s89
	s_cselect_b32 s68, s65, s84
	s_add_i32 m0, s72, 0xc000
	ds_read_b128 v[186:189], v209
	ds_read_b128 v[194:197], v209 offset:1024
	ds_read_b128 v[214:217], v209 offset:2048
	ds_read_b128 v[218:221], v209 offset:3072
	ds_read_b128 v[224:227], v209 offset:4096
	ds_read_b128 v[228:231], v209 offset:5120
	ds_read_b128 v[232:235], v209 offset:6144
	ds_read_b128 v[236:239], v209 offset:7168
	global_load_lds_dwordx4 v170, s[66:67]
	s_add_i32 m0, s72, 0xe000
	s_nop 0
	global_load_lds_dwordx4 v172, s[66:67]
	s_waitcnt vmcnt(8)
	s_waitcnt lgkmcnt(0)
	s_barrier
	s_setprio 1
	s_waitcnt lgkmcnt(0)
	v_mfma_f32_16x16x32_bf16 v[124:127], v[128:131], v[186:189], v[124:127]
	v_mfma_f32_16x16x32_bf16 v[120:123], v[136:139], v[186:189], v[120:123]
	v_mfma_f32_16x16x32_bf16 v[108:111], v[128:131], v[214:217], v[108:111]
	v_mfma_f32_16x16x32_bf16 v[104:107], v[136:139], v[214:217], v[104:107]
	v_mfma_f32_16x16x32_bf16 v[92:95], v[128:131], v[224:227], v[92:95]
	v_mfma_f32_16x16x32_bf16 v[88:91], v[136:139], v[224:227], v[88:91]
	v_mfma_f32_16x16x32_bf16 v[76:79], v[128:131], v[232:235], v[76:79]
	v_mfma_f32_16x16x32_bf16 v[72:75], v[136:139], v[232:235], v[72:75]
	v_mfma_f32_16x16x32_bf16 v[124:127], v[132:135], v[194:197], v[124:127]
	v_mfma_f32_16x16x32_bf16 v[120:123], v[140:143], v[194:197], v[120:123]
	v_mfma_f32_16x16x32_bf16 v[108:111], v[132:135], v[218:221], v[108:111]
	v_mfma_f32_16x16x32_bf16 v[104:107], v[140:143], v[218:221], v[104:107]
	v_mfma_f32_16x16x32_bf16 v[92:95], v[132:135], v[228:231], v[92:95]
	v_mfma_f32_16x16x32_bf16 v[88:91], v[140:143], v[228:231], v[88:91]
	v_mfma_f32_16x16x32_bf16 v[76:79], v[132:135], v[236:239], v[76:79]
	v_mfma_f32_16x16x32_bf16 v[72:75], v[140:143], v[236:239], v[72:75]
	s_setprio 0
	s_setprio 1
	v_mfma_f32_16x16x32_bf16 v[116:119], v[144:147], v[186:189], v[116:119]
	v_mfma_f32_16x16x32_bf16 v[112:115], v[152:155], v[186:189], v[112:115]
	v_mfma_f32_16x16x32_bf16 v[100:103], v[144:147], v[214:217], v[100:103]
	v_mfma_f32_16x16x32_bf16 v[96:99], v[152:155], v[214:217], v[96:99]
	v_mfma_f32_16x16x32_bf16 v[84:87], v[144:147], v[224:227], v[84:87]
	v_mfma_f32_16x16x32_bf16 v[80:83], v[152:155], v[224:227], v[80:83]
	v_mfma_f32_16x16x32_bf16 v[68:71], v[144:147], v[232:235], v[68:71]
	v_mfma_f32_16x16x32_bf16 v[64:67], v[152:155], v[232:235], v[64:67]
	v_mfma_f32_16x16x32_bf16 v[116:119], v[148:151], v[194:197], v[116:119]
	v_mfma_f32_16x16x32_bf16 v[112:115], v[156:159], v[194:197], v[112:115]
	v_mfma_f32_16x16x32_bf16 v[100:103], v[148:151], v[218:221], v[100:103]
	v_mfma_f32_16x16x32_bf16 v[96:99], v[156:159], v[218:221], v[96:99]
	v_mfma_f32_16x16x32_bf16 v[84:87], v[148:151], v[228:231], v[84:87]
	v_mfma_f32_16x16x32_bf16 v[80:83], v[156:159], v[228:231], v[80:83]
	v_mfma_f32_16x16x32_bf16 v[68:71], v[148:151], v[236:239], v[68:71]
	v_mfma_f32_16x16x32_bf16 v[64:67], v[156:159], v[236:239], v[64:67]
	s_setprio 0
	s_barrier
	s_add_i32 s9, s81, s24
	s_mov_b32 m0, s9
	ds_read_b128 v[186:189], v209 offset:16384
	ds_read_b128 v[194:197], v209 offset:17408
	ds_read_b128 v[214:217], v209 offset:18432
	ds_read_b128 v[218:221], v209 offset:19456
	ds_read_b128 v[224:227], v209 offset:20480
	ds_read_b128 v[228:231], v209 offset:21504
	ds_read_b128 v[232:235], v209 offset:22528
	ds_read_b128 v[236:239], v209 offset:23552
	global_load_lds_dwordx4 v162, s[68:69]
	s_add_i32 m0, s9, 0x2000
	s_add_u32 s14, s68, 0x20000
	s_addc_u32 s15, s69, 0
	s_add_i32 s9, s82, s24
	global_load_lds_dwordx4 v166, s[68:69]
	s_mov_b32 m0, s9
	s_nop 0
	global_load_lds_dwordx4 v162, s[14:15]
	s_add_i32 m0, s9, 0x2000
	s_nop 0
	global_load_lds_dwordx4 v166, s[14:15]
	s_mov_b32 m0, s72
	s_nop 0
	global_load_lds_dwordx4 v160, s[70:71]
	s_mov_b32 m0, s73
	s_nop 0
	global_load_lds_dwordx4 v164, s[70:71]
	s_waitcnt vmcnt(8)
	s_waitcnt lgkmcnt(0)
	s_barrier
	s_setprio 1
	s_waitcnt lgkmcnt(0)
	v_mfma_f32_16x16x32_bf16 v[60:63], v[128:131], v[186:189], v[60:63]
	v_mfma_f32_16x16x32_bf16 v[56:59], v[136:139], v[186:189], v[56:59]
	v_mfma_f32_16x16x32_bf16 v[44:47], v[128:131], v[214:217], v[44:47]
	v_mfma_f32_16x16x32_bf16 v[40:43], v[136:139], v[214:217], v[40:43]
	v_mfma_f32_16x16x32_bf16 v[28:31], v[128:131], v[224:227], v[28:31]
	v_mfma_f32_16x16x32_bf16 v[24:27], v[136:139], v[224:227], v[24:27]
	v_mfma_f32_16x16x32_bf16 v[12:15], v[128:131], v[232:235], v[12:15]
	v_mfma_f32_16x16x32_bf16 v[8:11], v[136:139], v[232:235], v[8:11]
	v_mfma_f32_16x16x32_bf16 v[60:63], v[132:135], v[194:197], v[60:63]
	v_mfma_f32_16x16x32_bf16 v[56:59], v[140:143], v[194:197], v[56:59]
	v_mfma_f32_16x16x32_bf16 v[44:47], v[132:135], v[218:221], v[44:47]
	v_mfma_f32_16x16x32_bf16 v[40:43], v[140:143], v[218:221], v[40:43]
	v_mfma_f32_16x16x32_bf16 v[28:31], v[132:135], v[228:231], v[28:31]
	v_mfma_f32_16x16x32_bf16 v[24:27], v[140:143], v[228:231], v[24:27]
	v_mfma_f32_16x16x32_bf16 v[12:15], v[132:135], v[236:239], v[12:15]
	v_mfma_f32_16x16x32_bf16 v[8:11], v[140:143], v[236:239], v[8:11]
	s_setprio 0
	s_setprio 1
	v_mfma_f32_16x16x32_bf16 v[52:55], v[144:147], v[186:189], v[52:55]
	v_mfma_f32_16x16x32_bf16 v[48:51], v[152:155], v[186:189], v[48:51]
	v_mfma_f32_16x16x32_bf16 v[36:39], v[144:147], v[214:217], v[36:39]
	v_mfma_f32_16x16x32_bf16 v[32:35], v[152:155], v[214:217], v[32:35]
	v_mfma_f32_16x16x32_bf16 v[20:23], v[144:147], v[224:227], v[20:23]
	v_mfma_f32_16x16x32_bf16 v[16:19], v[152:155], v[224:227], v[16:19]
	v_mfma_f32_16x16x32_bf16 v[4:7], v[144:147], v[232:235], v[4:7]
	v_mfma_f32_16x16x32_bf16 v[0:3], v[152:155], v[232:235], v[0:3]
	v_mfma_f32_16x16x32_bf16 v[52:55], v[148:151], v[194:197], v[52:55]
	v_mfma_f32_16x16x32_bf16 v[48:51], v[156:159], v[194:197], v[48:51]
	v_mfma_f32_16x16x32_bf16 v[36:39], v[148:151], v[218:221], v[36:39]
	v_mfma_f32_16x16x32_bf16 v[32:35], v[156:159], v[218:221], v[32:35]
	v_mfma_f32_16x16x32_bf16 v[20:23], v[148:151], v[228:231], v[20:23]
	v_mfma_f32_16x16x32_bf16 v[16:19], v[156:159], v[228:231], v[16:19]
	v_mfma_f32_16x16x32_bf16 v[4:7], v[148:151], v[236:239], v[4:7]
	v_mfma_f32_16x16x32_bf16 v[0:3], v[156:159], v[236:239], v[0:3]
	s_setprio 0
	s_barrier
; #define PG8_STAGE(bufoff, gbase, voff) do { _Pragma("unroll") for (int _i = 0; _i < 2; ++_i) \
;         __builtin_amdgcn_global_load_lds((const unsigned*)((const char*)(gbase) + (voff)[_i]), (LAS unsigned*)(lds + (bufoff) + ldsw + _i * 8192), 16, 0, 0); } while (0)
; #define PG8_LDA(dst, b, h) do { _Pragma("unroll") for (int m = 0; m < 4; ++m) _Pragma("unroll") for (int k = 0; k < 2; ++k) dst[m][k] = *(const LAS bf16x8*)(lds + PG8_SA(b, h) + aoff + m * 2048 + k * 1024); } while (0)
; #define PG8_LDB(dst, b, h) do { _Pragma("unroll") for (int n = 0; n < 2; ++n) _Pragma("unroll") for (int k = 0; k < 2; ++k) dst[n][k] = *(const LAS bf16x8*)(lds + PG8_SB(b, h) + boff + n * 2048 + k * 1024); } while (0)
; #define PG8_WAIT_V(n) asm volatile("s_waitcnt vmcnt(" #n ")" ::: "memory")
; template <int K, int LDA, int LDB, class Epi, class Sched>
; __device__ __forceinline__ void gemm_phase(LAS unsigned char* lds, const Gemm g, const Sched& S, const Epi& E, int wv) {
;     ...
;         for (int t = 0; t < nt; t += 2) {
;             const bool last = (t == nt - 2);
;             const char* a1 = cA + (size_t)(t + 1) * kstep;
;             const char* a2 = last ? nA : cA + (size_t)(t + 2) * kstep; const char* b2 = last ? nB : cB + (size_t)(t + 2) * kstep;
;             const char* a3 = a2 + kstep; const char* b3 = b2 + kstep;
;             PG8_LDB(B0, 0, 0); PG8_LDB(B1, 0, 1); PG8_SCHED; PG8_LDA(At, 0, 0); PG8_STAGE(PG8_SA(1, 1), a1 + hstepA, voffA);
;             PG8_WAIT_V(8); PG8_WAIT_L(0); PG8_BAR; PG8_MMA(0, 0, At, B0); PG8_MMA(0, 1, At, B1); PG8_BAR; PG8_SCHED;
;             PG8_LDA(At, 0, 1); PG8_STAGE(PG8_SB(0, 0), b2, voffB); PG8_STAGE(PG8_SB(0, 1), b2 + hstepB, voffB); PG8_STAGE(PG8_SA(0, 0), a2, voffA);
;             PG8_WAIT_V(8); PG8_WAIT_L(0); PG8_BAR; PG8_MMA(1, 0, At, B0); PG8_MMA(1, 1, At, B1); PG8_BAR; PG8_SCHED;
;             PG8_LDB(B0, 1, 0); PG8_LDB(B1, 1, 1); PG8_SCHED; PG8_LDA(At, 1, 0); PG8_STAGE(PG8_SA(0, 1), a2 + hstepA, voffA);
;             PG8_WAIT_V(8); PG8_WAIT_L(0); PG8_BAR; PG8_MMA(0, 0, At, B0); PG8_MMA(0, 1, At, B1); PG8_BAR; PG8_SCHED;
;             PG8_LDA(At, 1, 1); PG8_STAGE(PG8_SB(1, 0), b3, voffB); PG8_STAGE(PG8_SB(1, 1), b3 + hstepB, voffB); PG8_STAGE(PG8_SA(1, 0), a3, voffA);
;             PG8_WAIT_V(8); PG8_WAIT_L(0); PG8_BAR; PG8_MMA(1, 0, At, B0); PG8_MMA(1, 1, At, B1); PG8_BAR; PG8_SCHED;
	s_add_i32 s9, 0, 0x18000
	s_add_i32 s34, 0, 0x1c000
	v_add_u32_e32 v140, s9, v185
	v_add_u32_e32 v156, s34, v185
	ds_read_b128 v[128:131], v140
	ds_read_b128 v[132:135], v140 offset:1024
	ds_read_b128 v[136:139], v140 offset:2048
	ds_read_b128 v[140:143], v140 offset:3072
	ds_read_b128 v[144:147], v156
	ds_read_b128 v[148:151], v156 offset:1024
	ds_read_b128 v[152:155], v156 offset:2048
	ds_read_b128 v[156:159], v156 offset:3072
	s_add_u32 s14, s70, 0x120000
	s_addc_u32 s15, s71, 0
	s_mov_b32 m0, s74
	ds_read_b128 v[186:189], v209 offset:32768
	ds_read_b128 v[194:197], v209 offset:33792
	ds_read_b128 v[214:217], v209 offset:34816
	ds_read_b128 v[218:221], v209 offset:35840
	ds_read_b128 v[224:227], v209 offset:36864
	ds_read_b128 v[228:231], v209 offset:37888
	ds_read_b128 v[232:235], v209 offset:38912
	ds_read_b128 v[236:239], v209 offset:39936
	global_load_lds_dwordx4 v160, s[14:15]
	s_mov_b32 m0, s75
	s_nop 0
	global_load_lds_dwordx4 v164, s[14:15]
	s_waitcnt vmcnt(8)
	s_waitcnt lgkmcnt(0)
	s_barrier
	s_setprio 1
	s_waitcnt lgkmcnt(0)
	v_mfma_f32_16x16x32_bf16 v[124:127], v[128:131], v[186:189], v[124:127]
	v_mfma_f32_16x16x32_bf16 v[120:123], v[136:139], v[186:189], v[120:123]
	v_mfma_f32_16x16x32_bf16 v[108:111], v[128:131], v[214:217], v[108:111]
	v_mfma_f32_16x16x32_bf16 v[104:107], v[136:139], v[214:217], v[104:107]
	v_mfma_f32_16x16x32_bf16 v[92:95], v[128:131], v[224:227], v[92:95]
	v_mfma_f32_16x16x32_bf16 v[88:91], v[136:139], v[224:227], v[88:91]
	v_mfma_f32_16x16x32_bf16 v[76:79], v[128:131], v[232:235], v[76:79]
	v_mfma_f32_16x16x32_bf16 v[72:75], v[136:139], v[232:235], v[72:75]
	v_mfma_f32_16x16x32_bf16 v[124:127], v[132:135], v[194:197], v[124:127]
	v_mfma_f32_16x16x32_bf16 v[120:123], v[140:143], v[194:197], v[120:123]
	v_mfma_f32_16x16x32_bf16 v[108:111], v[132:135], v[218:221], v[108:111]
	v_mfma_f32_16x16x32_bf16 v[104:107], v[140:143], v[218:221], v[104:107]
	v_mfma_f32_16x16x32_bf16 v[92:95], v[132:135], v[228:231], v[92:95]
	v_mfma_f32_16x16x32_bf16 v[88:91], v[140:143], v[228:231], v[88:91]
	v_mfma_f32_16x16x32_bf16 v[76:79], v[132:135], v[236:239], v[76:79]
	v_mfma_f32_16x16x32_bf16 v[72:75], v[140:143], v[236:239], v[72:75]
	s_setprio 0
	s_setprio 1
	v_mfma_f32_16x16x32_bf16 v[116:119], v[144:147], v[186:189], v[116:119]
	v_mfma_f32_16x16x32_bf16 v[112:115], v[152:155], v[186:189], v[112:115]
	v_mfma_f32_16x16x32_bf16 v[100:103], v[144:147], v[214:217], v[100:103]
	v_mfma_f32_16x16x32_bf16 v[96:99], v[152:155], v[214:217], v[96:99]
	v_mfma_f32_16x16x32_bf16 v[84:87], v[144:147], v[224:227], v[84:87]
	v_mfma_f32_16x16x32_bf16 v[80:83], v[152:155], v[224:227], v[80:83]
	v_mfma_f32_16x16x32_bf16 v[68:71], v[144:147], v[232:235], v[68:71]
	v_mfma_f32_16x16x32_bf16 v[64:67], v[152:155], v[232:235], v[64:67]
	v_mfma_f32_16x16x32_bf16 v[116:119], v[148:151], v[194:197], v[116:119]
	v_mfma_f32_16x16x32_bf16 v[112:115], v[156:159], v[194:197], v[112:115]
	v_mfma_f32_16x16x32_bf16 v[100:103], v[148:151], v[218:221], v[100:103]
	v_mfma_f32_16x16x32_bf16 v[96:99], v[156:159], v[218:221], v[96:99]
	v_mfma_f32_16x16x32_bf16 v[84:87], v[148:151], v[228:231], v[84:87]
	v_mfma_f32_16x16x32_bf16 v[80:83], v[156:159], v[228:231], v[80:83]
	v_mfma_f32_16x16x32_bf16 v[68:71], v[148:151], v[236:239], v[68:71]
	v_mfma_f32_16x16x32_bf16 v[64:67], v[156:159], v[236:239], v[64:67]
	s_setprio 0
	s_barrier
	s_add_i32 s9, s9, s24
	s_mov_b32 m0, s9
	ds_read_b128 v[186:189], v209 offset:49152
	ds_read_b128 v[194:197], v209 offset:50176
	ds_read_b128 v[214:217], v209 offset:51200
	ds_read_b128 v[218:221], v209 offset:52224
	ds_read_b128 v[224:227], v209 offset:53248
	ds_read_b128 v[228:231], v209 offset:54272
	ds_read_b128 v[232:235], v209 offset:55296
	ds_read_b128 v[236:239], v209 offset:56320
	s_add_u32 s98, s68, s56
	s_addc_u32 s99, s69, s57
	global_load_lds_dwordx4 v162, s[98:99]
	s_add_i32 m0, s9, 0x2000
	s_add_u32 s14, s68, 0x20080
	s_addc_u32 s15, s69, 0
	s_add_i32 s9, s34, s24
	global_load_lds_dwordx4 v166, s[98:99]
	s_mov_b32 m0, s9
	s_nop 0
	global_load_lds_dwordx4 v162, s[14:15]
	s_add_i32 m0, s9, 0x2000
	s_nop 0
	global_load_lds_dwordx4 v166, s[14:15]
	s_mov_b32 m0, s78
	s_nop 0
	s_add_u32 s100, s70, s56
	s_addc_u32 s101, s71, s57
	global_load_lds_dwordx4 v160, s[100:101]
	s_mov_b32 m0, s79
	s_nop 0
	global_load_lds_dwordx4 v164, s[100:101]
	s_waitcnt vmcnt(8)
	s_waitcnt lgkmcnt(0)
	s_barrier
	s_setprio 1
	s_waitcnt lgkmcnt(0)
	v_mfma_f32_16x16x32_bf16 v[60:63], v[128:131], v[186:189], v[60:63]
	v_mfma_f32_16x16x32_bf16 v[56:59], v[136:139], v[186:189], v[56:59]
	v_mfma_f32_16x16x32_bf16 v[44:47], v[128:131], v[214:217], v[44:47]
	v_mfma_f32_16x16x32_bf16 v[40:43], v[136:139], v[214:217], v[40:43]
	v_mfma_f32_16x16x32_bf16 v[28:31], v[128:131], v[224:227], v[28:31]
	v_mfma_f32_16x16x32_bf16 v[24:27], v[136:139], v[224:227], v[24:27]
	v_mfma_f32_16x16x32_bf16 v[12:15], v[128:131], v[232:235], v[12:15]
	v_mfma_f32_16x16x32_bf16 v[8:11], v[136:139], v[232:235], v[8:11]
	v_mfma_f32_16x16x32_bf16 v[60:63], v[132:135], v[194:197], v[60:63]
	v_mfma_f32_16x16x32_bf16 v[56:59], v[140:143], v[194:197], v[56:59]
	v_mfma_f32_16x16x32_bf16 v[44:47], v[132:135], v[218:221], v[44:47]
	v_mfma_f32_16x16x32_bf16 v[40:43], v[140:143], v[218:221], v[40:43]
	v_mfma_f32_16x16x32_bf16 v[28:31], v[132:135], v[228:231], v[28:31]
	v_mfma_f32_16x16x32_bf16 v[24:27], v[140:143], v[228:231], v[24:27]
	v_mfma_f32_16x16x32_bf16 v[12:15], v[132:135], v[236:239], v[12:15]
	v_mfma_f32_16x16x32_bf16 v[8:11], v[140:143], v[236:239], v[8:11]
	s_setprio 0
	s_setprio 1
	v_mfma_f32_16x16x32_bf16 v[52:55], v[144:147], v[186:189], v[52:55]
	v_mfma_f32_16x16x32_bf16 v[48:51], v[152:155], v[186:189], v[48:51]
	v_mfma_f32_16x16x32_bf16 v[36:39], v[144:147], v[214:217], v[36:39]
	v_mfma_f32_16x16x32_bf16 v[32:35], v[152:155], v[214:217], v[32:35]
	v_mfma_f32_16x16x32_bf16 v[20:23], v[144:147], v[224:227], v[20:23]
	v_mfma_f32_16x16x32_bf16 v[16:19], v[152:155], v[224:227], v[16:19]
	v_mfma_f32_16x16x32_bf16 v[4:7], v[144:147], v[232:235], v[4:7]
	v_mfma_f32_16x16x32_bf16 v[0:3], v[152:155], v[232:235], v[0:3]
	v_mfma_f32_16x16x32_bf16 v[52:55], v[148:151], v[194:197], v[52:55]
	v_mfma_f32_16x16x32_bf16 v[48:51], v[156:159], v[194:197], v[48:51]
	v_mfma_f32_16x16x32_bf16 v[36:39], v[148:151], v[218:221], v[36:39]
	v_mfma_f32_16x16x32_bf16 v[32:35], v[156:159], v[218:221], v[32:35]
	v_mfma_f32_16x16x32_bf16 v[20:23], v[148:151], v[228:231], v[20:23]
	v_mfma_f32_16x16x32_bf16 v[16:19], v[156:159], v[228:231], v[16:19]
	v_mfma_f32_16x16x32_bf16 v[4:7], v[148:151], v[236:239], v[4:7]
	v_mfma_f32_16x16x32_bf16 v[0:3], v[156:159], v[236:239], v[0:3]
	s_setprio 0
	s_barrier
	s_add_i32 s8, s8, 2
	s_add_u32 s84, s84, 0x100
	s_addc_u32 s89, s89, 0
	s_cmp_gt_u32 s8, 5
	s_mov_b64 s[66:67], s[12:13]
	s_cbranch_scc0 .LBB0_465
	s_and_b64 vcc, exec, s[28:29]
	s_cbranch_vccz .LBB0_468
	s_barrier

; #define PG8_STAGE(bufoff, gbase, voff) do { _Pragma("unroll") for (int _i = 0; _i < 2; ++_i) \
;         __builtin_amdgcn_global_load_lds((const unsigned*)((const char*)(gbase) + (voff)[_i]), (LAS unsigned*)(lds + (bufoff) + ldsw + _i * 8192), 16, 0, 0); } while (0)
; #define PG8_LDA(dst, b, h) do { _Pragma("unroll") for (int m = 0; m < 4; ++m) _Pragma("unroll") for (int k = 0; k < 2; ++k) dst[m][k] = *(const LAS bf16x8*)(lds + PG8_SA(b, h) + aoff + m * 2048 + k * 1024); } while (0)
; #define PG8_LDB(dst, b, h) do { _Pragma("unroll") for (int n = 0; n < 2; ++n) _Pragma("unroll") for (int k = 0; k < 2; ++k) dst[n][k] = *(const LAS bf16x8*)(lds + PG8_SB(b, h) + boff + n * 2048 + k * 1024); } while (0)
; #define PG8_WAIT_V(n) asm volatile("s_waitcnt vmcnt(" #n ")" ::: "memory")
; template <int K, int LDA, int LDB, class Epi, class Sched>
; __device__ __forceinline__ void gemm_phase(LAS unsigned char* lds, const Gemm g, const Sched& S, const Epi& E, int wv) {
;     ...
;         for (int t = 0; t < nt; t += 2) {
;             const bool last = (t == nt - 2);
;             const char* a1 = cA + (size_t)(t + 1) * kstep;
;             const char* a2 = last ? nA : cA + (size_t)(t + 2) * kstep; const char* b2 = last ? nB : cB + (size_t)(t + 2) * kstep;
;             const char* a3 = a2 + kstep; const char* b3 = b2 + kstep;
;             PG8_LDB(B0, 0, 0); PG8_LDB(B1, 0, 1); PG8_SCHED; PG8_LDA(At, 0, 0); PG8_STAGE(PG8_SA(1, 1), a1 + hstepA, voffA);
;             PG8_WAIT_V(8); PG8_WAIT_L(0); PG8_BAR; PG8_MMA(0, 0, At, B0); PG8_MMA(0, 1, At, B1); PG8_BAR; PG8_SCHED;
;             PG8_LDA(At, 0, 1); PG8_STAGE(PG8_SB(0, 0), b2, voffB); PG8_STAGE(PG8_SB(0, 1), b2 + hstepB, voffB); PG8_STAGE(PG8_SA(0, 0), a2, voffA);
;             PG8_WAIT_V(8); PG8_WAIT_L(0); PG8_BAR; PG8_MMA(1, 0, At, B0); PG8_MMA(1, 1, At, B1); PG8_BAR; PG8_SCHED;
;             PG8_LDB(B0, 1, 0); PG8_LDB(B1, 1, 1); PG8_SCHED; PG8_LDA(At, 1, 0); PG8_STAGE(PG8_SA(0, 1), a2 + hstepA, voffA);
;             PG8_WAIT_V(8); PG8_WAIT_L(0); PG8_BAR; PG8_MMA(0, 0, At, B0); PG8_MMA(0, 1, At, B1); PG8_BAR; PG8_SCHED;
;             PG8_LDA(At, 1, 1); PG8_STAGE(PG8_SB(1, 0), b3, voffB); PG8_STAGE(PG8_SB(1, 1), b3 + hstepB, voffB); PG8_STAGE(PG8_SA(1, 0), a3, voffA);
;             PG8_WAIT_V(8); PG8_WAIT_L(0); PG8_BAR; PG8_MMA(1, 0, At, B0); PG8_MMA(1, 1, At, B1); PG8_BAR; PG8_SCHED;
.LBB0_519:
	s_add_u32 s14, s68, s72
	s_addc_u32 s15, s69, s73
	s_add_u32 s34, s14, 0x100
	s_addc_u32 s35, s15, 0
	s_and_b64 s[8:9], s[70:71], exec
	s_cselect_b32 s75, s63, s35
	s_cselect_b32 s74, s62, s34
	s_add_u32 s8, s66, s72
	s_addc_u32 s9, s67, s73
	s_add_u32 s34, s8, 0x100
	s_addc_u32 s35, s9, 0
	s_and_b64 s[8:9], s[70:71], exec
	s_cselect_b32 s77, s61, s35
	s_cselect_b32 s76, s84, s34
	s_add_u32 s80, s14, 0x120080
	ds_read_b128 v[144:147], v157
	ds_read_b128 v[164:167], v157 offset:1024
	ds_read_b128 v[168:171], v157 offset:2048
	ds_read_b128 v[172:175], v157 offset:3072
	ds_read_b128 v[176:179], v160
	ds_read_b128 v[180:183], v160 offset:1024
	ds_read_b128 v[184:187], v160 offset:2048
	ds_read_b128 v[188:191], v160 offset:3072
	s_addc_u32 s81, s15, 0
	s_add_i32 s15, s93, s24
	s_add_i32 m0, s86, 0xc000
	s_add_i32 s35, s86, 0xe000
	s_add_i32 s34, s15, 0x2000
	s_add_u32 s78, s76, 0x10000
	s_addc_u32 s79, s77, 0
	s_add_i32 s51, s94, s24
	s_add_i32 s50, s51, 0x2000
	s_add_i32 vcc_hi, 0, 0x18000
	s_add_i32 vcc_lo, 0, 0x1c000
	s_add_u32 s72, s74, 0x120000
	s_addc_u32 s73, s75, 0
	s_add_i32 s9, vcc_hi, s24
	s_add_i32 s14, s9, 0x2000
	s_add_u32 s70, s76, 0x10080
	s_addc_u32 s71, s77, 0
	s_add_i32 s8, vcc_lo, s24
	s_add_i32 s85, s8, 0x2000
	ds_read_b128 v[192:195], v161
	ds_read_b128 v[196:199], v161 offset:1024
	ds_read_b128 v[200:203], v161 offset:2048
	ds_read_b128 v[204:207], v161 offset:3072
	ds_read_b128 v[208:211], v161 offset:4096
	ds_read_b128 v[212:215], v161 offset:5120
	ds_read_b128 v[216:219], v161 offset:6144
	ds_read_b128 v[224:227], v161 offset:7168
	global_load_lds_dwordx4 v134, s[80:81]
	s_mov_b32 m0, s35
	s_nop 0
	global_load_lds_dwordx4 v130, s[80:81]
	s_waitcnt vmcnt(8)
	s_waitcnt lgkmcnt(0)
	s_barrier
	s_setprio 1
	s_waitcnt lgkmcnt(0)
	v_mfma_f32_16x16x32_bf16 v[124:127], v[144:147], v[192:195], v[124:127]
	v_mfma_f32_16x16x32_bf16 v[120:123], v[168:171], v[192:195], v[120:123]
	v_mfma_f32_16x16x32_bf16 v[112:115], v[144:147], v[200:203], v[112:115]
	v_mfma_f32_16x16x32_bf16 v[104:107], v[168:171], v[200:203], v[104:107]
	v_mfma_f32_16x16x32_bf16 v[96:99], v[144:147], v[208:211], v[96:99]
	v_mfma_f32_16x16x32_bf16 v[88:91], v[168:171], v[208:211], v[88:91]
	v_mfma_f32_16x16x32_bf16 v[80:83], v[144:147], v[216:219], v[80:83]
	v_mfma_f32_16x16x32_bf16 v[72:75], v[168:171], v[216:219], v[72:75]
	v_mfma_f32_16x16x32_bf16 v[124:127], v[164:167], v[196:199], v[124:127]
	v_mfma_f32_16x16x32_bf16 v[120:123], v[172:175], v[196:199], v[120:123]
	v_mfma_f32_16x16x32_bf16 v[112:115], v[164:167], v[204:207], v[112:115]
	v_mfma_f32_16x16x32_bf16 v[104:107], v[172:175], v[204:207], v[104:107]
	v_mfma_f32_16x16x32_bf16 v[96:99], v[164:167], v[212:215], v[96:99]
	v_mfma_f32_16x16x32_bf16 v[88:91], v[172:175], v[212:215], v[88:91]
	v_mfma_f32_16x16x32_bf16 v[80:83], v[164:167], v[224:227], v[80:83]
	v_mfma_f32_16x16x32_bf16 v[72:75], v[172:175], v[224:227], v[72:75]
	s_setprio 0
	s_setprio 1
	v_mfma_f32_16x16x32_bf16 v[116:119], v[176:179], v[192:195], v[116:119]
	v_mfma_f32_16x16x32_bf16 v[108:111], v[184:187], v[192:195], v[108:111]
	v_mfma_f32_16x16x32_bf16 v[100:103], v[176:179], v[200:203], v[100:103]
	v_mfma_f32_16x16x32_bf16 v[92:95], v[184:187], v[200:203], v[92:95]
	v_mfma_f32_16x16x32_bf16 v[84:87], v[176:179], v[208:211], v[84:87]
	v_mfma_f32_16x16x32_bf16 v[76:79], v[184:187], v[208:211], v[76:79]
	v_mfma_f32_16x16x32_bf16 v[68:71], v[176:179], v[216:219], v[68:71]
	v_mfma_f32_16x16x32_bf16 v[64:67], v[184:187], v[216:219], v[64:67]
	v_mfma_f32_16x16x32_bf16 v[116:119], v[180:183], v[196:199], v[116:119]
	v_mfma_f32_16x16x32_bf16 v[108:111], v[188:191], v[196:199], v[108:111]
	v_mfma_f32_16x16x32_bf16 v[100:103], v[180:183], v[204:207], v[100:103]
	v_mfma_f32_16x16x32_bf16 v[92:95], v[188:191], v[204:207], v[92:95]
	v_mfma_f32_16x16x32_bf16 v[84:87], v[180:183], v[212:215], v[84:87]
	v_mfma_f32_16x16x32_bf16 v[76:79], v[188:191], v[212:215], v[76:79]
	v_mfma_f32_16x16x32_bf16 v[68:71], v[180:183], v[224:227], v[68:71]
	v_mfma_f32_16x16x32_bf16 v[64:67], v[188:191], v[224:227], v[64:67]
	s_setprio 0
	s_barrier
	s_mov_b32 m0, s15
	ds_read_b128 v[192:195], v161 offset:16384
	ds_read_b128 v[196:199], v161 offset:17408
	ds_read_b128 v[200:203], v161 offset:18432
	ds_read_b128 v[204:207], v161 offset:19456
	ds_read_b128 v[208:211], v161 offset:20480
	ds_read_b128 v[212:215], v161 offset:21504
	ds_read_b128 v[216:219], v161 offset:22528
	ds_read_b128 v[224:227], v161 offset:23552
	global_load_lds_dwordx4 v132, s[76:77]
	s_mov_b32 m0, s34
	s_nop 0
	global_load_lds_dwordx4 v128, s[76:77]
	s_mov_b32 m0, s51
	s_nop 0
	global_load_lds_dwordx4 v132, s[78:79]
	s_mov_b32 m0, s50
	s_nop 0
	global_load_lds_dwordx4 v128, s[78:79]
	s_mov_b32 m0, s86
	s_nop 0
	global_load_lds_dwordx4 v134, s[74:75]
	s_mov_b32 m0, s87
	s_nop 0
	global_load_lds_dwordx4 v130, s[74:75]
	s_waitcnt vmcnt(8)
	s_waitcnt lgkmcnt(0)
	s_barrier
; #define PG8_STAGE(bufoff, gbase, voff) do { _Pragma("unroll") for (int _i = 0; _i < 2; ++_i) \
;         __builtin_amdgcn_global_load_lds((const unsigned*)((const char*)(gbase) + (voff)[_i]), (LAS unsigned*)(lds + (bufoff) + ldsw + _i * 8192), 16, 0, 0); } while (0)
; #define PG8_LDA(dst, b, h) do { _Pragma("unroll") for (int m = 0; m < 4; ++m) _Pragma("unroll") for (int k = 0; k < 2; ++k) dst[m][k] = *(const LAS bf16x8*)(lds + PG8_SA(b, h) + aoff + m * 2048 + k * 1024); } while (0)
; #define PG8_LDB(dst, b, h) do { _Pragma("unroll") for (int n = 0; n < 2; ++n) _Pragma("unroll") for (int k = 0; k < 2; ++k) dst[n][k] = *(const LAS bf16x8*)(lds + PG8_SB(b, h) + boff + n * 2048 + k * 1024); } while (0)
; #define PG8_WAIT_V(n) asm volatile("s_waitcnt vmcnt(" #n ")" ::: "memory")
; template <int K, int LDA, int LDB, class Epi, class Sched>
; __device__ __forceinline__ void gemm_phase(LAS unsigned char* lds, const Gemm g, const Sched& S, const Epi& E, int wv) {
;     ...
;         for (int t = 0; t < nt; t += 2) {
;             const bool last = (t == nt - 2);
;             const char* a1 = cA + (size_t)(t + 1) * kstep;
;             const char* a2 = last ? nA : cA + (size_t)(t + 2) * kstep; const char* b2 = last ? nB : cB + (size_t)(t + 2) * kstep;
;             const char* a3 = a2 + kstep; const char* b3 = b2 + kstep;
;             PG8_LDB(B0, 0, 0); PG8_LDB(B1, 0, 1); PG8_SCHED; PG8_LDA(At, 0, 0); PG8_STAGE(PG8_SA(1, 1), a1 + hstepA, voffA);
;             PG8_WAIT_V(8); PG8_WAIT_L(0); PG8_BAR; PG8_MMA(0, 0, At, B0); PG8_MMA(0, 1, At, B1); PG8_BAR; PG8_SCHED;
;             PG8_LDA(At, 0, 1); PG8_STAGE(PG8_SB(0, 0), b2, voffB); PG8_STAGE(PG8_SB(0, 1), b2 + hstepB, voffB); PG8_STAGE(PG8_SA(0, 0), a2, voffA);
;             PG8_WAIT_V(8); PG8_WAIT_L(0); PG8_BAR; PG8_MMA(1, 0, At, B0); PG8_MMA(1, 1, At, B1); PG8_BAR; PG8_SCHED;
;             PG8_LDB(B0, 1, 0); PG8_LDB(B1, 1, 1); PG8_SCHED; PG8_LDA(At, 1, 0); PG8_STAGE(PG8_SA(0, 1), a2 + hstepA, voffA);
;             PG8_WAIT_V(8); PG8_WAIT_L(0); PG8_BAR; PG8_MMA(0, 0, At, B0); PG8_MMA(0, 1, At, B1); PG8_BAR; PG8_SCHED;
;             PG8_LDA(At, 1, 1); PG8_STAGE(PG8_SB(1, 0), b3, voffB); PG8_STAGE(PG8_SB(1, 1), b3 + hstepB, voffB); PG8_STAGE(PG8_SA(1, 0), a3, voffA);
;             PG8_WAIT_V(8); PG8_WAIT_L(0); PG8_BAR; PG8_MMA(1, 0, At, B0); PG8_MMA(1, 1, At, B1); PG8_BAR; PG8_SCHED;
	s_setprio 1
	s_waitcnt lgkmcnt(0)
	v_mfma_f32_16x16x32_bf16 v[60:63], v[144:147], v[192:195], v[60:63]
	v_mfma_f32_16x16x32_bf16 v[56:59], v[168:171], v[192:195], v[56:59]
	v_mfma_f32_16x16x32_bf16 v[48:51], v[144:147], v[200:203], v[48:51]
	v_mfma_f32_16x16x32_bf16 v[40:43], v[168:171], v[200:203], v[40:43]
	v_mfma_f32_16x16x32_bf16 v[32:35], v[144:147], v[208:211], v[32:35]
	v_mfma_f32_16x16x32_bf16 v[24:27], v[168:171], v[208:211], v[24:27]
	v_mfma_f32_16x16x32_bf16 v[16:19], v[144:147], v[216:219], v[16:19]
	v_mfma_f32_16x16x32_bf16 v[8:11], v[168:171], v[216:219], v[8:11]
	v_mfma_f32_16x16x32_bf16 v[60:63], v[164:167], v[196:199], v[60:63]
	v_mfma_f32_16x16x32_bf16 v[56:59], v[172:175], v[196:199], v[56:59]
	v_mfma_f32_16x16x32_bf16 v[48:51], v[164:167], v[204:207], v[48:51]
	v_mfma_f32_16x16x32_bf16 v[40:43], v[172:175], v[204:207], v[40:43]
	v_mfma_f32_16x16x32_bf16 v[32:35], v[164:167], v[212:215], v[32:35]
	v_mfma_f32_16x16x32_bf16 v[24:27], v[172:175], v[212:215], v[24:27]
	v_mfma_f32_16x16x32_bf16 v[16:19], v[164:167], v[224:227], v[16:19]
	v_mfma_f32_16x16x32_bf16 v[8:11], v[172:175], v[224:227], v[8:11]
	s_setprio 0
	s_setprio 1
	v_mfma_f32_16x16x32_bf16 v[52:55], v[176:179], v[192:195], v[52:55]
	v_mfma_f32_16x16x32_bf16 v[44:47], v[184:187], v[192:195], v[44:47]
	v_mfma_f32_16x16x32_bf16 v[36:39], v[176:179], v[200:203], v[36:39]
	v_mfma_f32_16x16x32_bf16 v[28:31], v[184:187], v[200:203], v[28:31]
	v_mfma_f32_16x16x32_bf16 v[20:23], v[176:179], v[208:211], v[20:23]
	v_mfma_f32_16x16x32_bf16 v[12:15], v[184:187], v[208:211], v[12:15]
	v_mfma_f32_16x16x32_bf16 v[4:7], v[176:179], v[216:219], v[4:7]
	v_mfma_f32_16x16x32_bf16 v[0:3], v[184:187], v[216:219], v[0:3]
	v_mfma_f32_16x16x32_bf16 v[52:55], v[180:183], v[196:199], v[52:55]
	v_mfma_f32_16x16x32_bf16 v[44:47], v[188:191], v[196:199], v[44:47]
	v_mfma_f32_16x16x32_bf16 v[36:39], v[180:183], v[204:207], v[36:39]
	v_mfma_f32_16x16x32_bf16 v[28:31], v[188:191], v[204:207], v[28:31]
	v_mfma_f32_16x16x32_bf16 v[20:23], v[180:183], v[212:215], v[20:23]
	v_mfma_f32_16x16x32_bf16 v[12:15], v[188:191], v[212:215], v[12:15]
	v_mfma_f32_16x16x32_bf16 v[4:7], v[180:183], v[224:227], v[4:7]
	v_mfma_f32_16x16x32_bf16 v[0:3], v[188:191], v[224:227], v[0:3]
	s_setprio 0
	s_barrier
	v_add_u32_e32 v142, vcc_hi, v149
	ds_read_b128 v[144:147], v142
	ds_read_b128 v[164:167], v142 offset:1024
	ds_read_b128 v[168:171], v142 offset:2048
	ds_read_b128 v[172:175], v142 offset:3072
	v_add_u32_e32 v142, vcc_lo, v149
	ds_read_b128 v[176:179], v142
	ds_read_b128 v[180:183], v142 offset:1024
	ds_read_b128 v[184:187], v142 offset:2048
	ds_read_b128 v[188:191], v142 offset:3072
	s_mov_b32 m0, s88
	ds_read_b128 v[192:195], v161 offset:32768
	ds_read_b128 v[196:199], v161 offset:33792
	ds_read_b128 v[200:203], v161 offset:34816
	ds_read_b128 v[204:207], v161 offset:35840
	ds_read_b128 v[208:211], v161 offset:36864
	ds_read_b128 v[212:215], v161 offset:37888
	ds_read_b128 v[216:219], v161 offset:38912
	ds_read_b128 v[224:227], v161 offset:39936
	global_load_lds_dwordx4 v134, s[72:73]
	s_mov_b32 m0, s89
	s_nop 0
	global_load_lds_dwordx4 v130, s[72:73]
	s_waitcnt vmcnt(8)
	s_waitcnt lgkmcnt(0)
	s_barrier
	s_setprio 1
	s_waitcnt lgkmcnt(0)
	v_mfma_f32_16x16x32_bf16 v[124:127], v[144:147], v[192:195], v[124:127]
	v_mfma_f32_16x16x32_bf16 v[120:123], v[168:171], v[192:195], v[120:123]
	v_mfma_f32_16x16x32_bf16 v[112:115], v[144:147], v[200:203], v[112:115]
	v_mfma_f32_16x16x32_bf16 v[104:107], v[168:171], v[200:203], v[104:107]
	v_mfma_f32_16x16x32_bf16 v[96:99], v[144:147], v[208:211], v[96:99]
	v_mfma_f32_16x16x32_bf16 v[88:91], v[168:171], v[208:211], v[88:91]
	v_mfma_f32_16x16x32_bf16 v[80:83], v[144:147], v[216:219], v[80:83]
	v_mfma_f32_16x16x32_bf16 v[72:75], v[168:171], v[216:219], v[72:75]
	v_mfma_f32_16x16x32_bf16 v[124:127], v[164:167], v[196:199], v[124:127]
	v_mfma_f32_16x16x32_bf16 v[120:123], v[172:175], v[196:199], v[120:123]
	v_mfma_f32_16x16x32_bf16 v[112:115], v[164:167], v[204:207], v[112:115]
	v_mfma_f32_16x16x32_bf16 v[104:107], v[172:175], v[204:207], v[104:107]
	v_mfma_f32_16x16x32_bf16 v[96:99], v[164:167], v[212:215], v[96:99]
	v_mfma_f32_16x16x32_bf16 v[88:91], v[172:175], v[212:215], v[88:91]
	v_mfma_f32_16x16x32_bf16 v[80:83], v[164:167], v[224:227], v[80:83]
	v_mfma_f32_16x16x32_bf16 v[72:75], v[172:175], v[224:227], v[72:75]
	s_setprio 0
	s_setprio 1
	v_mfma_f32_16x16x32_bf16 v[116:119], v[176:179], v[192:195], v[116:119]
	v_mfma_f32_16x16x32_bf16 v[108:111], v[184:187], v[192:195], v[108:111]
	v_mfma_f32_16x16x32_bf16 v[100:103], v[176:179], v[200:203], v[100:103]
	v_mfma_f32_16x16x32_bf16 v[92:95], v[184:187], v[200:203], v[92:95]
	v_mfma_f32_16x16x32_bf16 v[84:87], v[176:179], v[208:211], v[84:87]
	v_mfma_f32_16x16x32_bf16 v[76:79], v[184:187], v[208:211], v[76:79]
	v_mfma_f32_16x16x32_bf16 v[68:71], v[176:179], v[216:219], v[68:71]
	v_mfma_f32_16x16x32_bf16 v[64:67], v[184:187], v[216:219], v[64:67]
	v_mfma_f32_16x16x32_bf16 v[116:119], v[180:183], v[196:199], v[116:119]
	v_mfma_f32_16x16x32_bf16 v[108:111], v[188:191], v[196:199], v[108:111]
	v_mfma_f32_16x16x32_bf16 v[100:103], v[180:183], v[204:207], v[100:103]
	v_mfma_f32_16x16x32_bf16 v[92:95], v[188:191], v[204:207], v[92:95]
	v_mfma_f32_16x16x32_bf16 v[84:87], v[180:183], v[212:215], v[84:87]
	v_mfma_f32_16x16x32_bf16 v[76:79], v[188:191], v[212:215], v[76:79]
	v_mfma_f32_16x16x32_bf16 v[68:71], v[180:183], v[224:227], v[68:71]
	v_mfma_f32_16x16x32_bf16 v[64:67], v[188:191], v[224:227], v[64:67]
	s_setprio 0
	s_barrier
; #define PG8_STAGE(bufoff, gbase, voff) do { _Pragma("unroll") for (int _i = 0; _i < 2; ++_i) \
;         __builtin_amdgcn_global_load_lds((const unsigned*)((const char*)(gbase) + (voff)[_i]), (LAS unsigned*)(lds + (bufoff) + ldsw + _i * 8192), 16, 0, 0); } while (0)
; #define PG8_LDA(dst, b, h) do { _Pragma("unroll") for (int m = 0; m < 4; ++m) _Pragma("unroll") for (int k = 0; k < 2; ++k) dst[m][k] = *(const LAS bf16x8*)(lds + PG8_SA(b, h) + aoff + m * 2048 + k * 1024); } while (0)
; #define PG8_LDB(dst, b, h) do { _Pragma("unroll") for (int n = 0; n < 2; ++n) _Pragma("unroll") for (int k = 0; k < 2; ++k) dst[n][k] = *(const LAS bf16x8*)(lds + PG8_SB(b, h) + boff + n * 2048 + k * 1024); } while (0)
; #define PG8_WAIT_V(n) asm volatile("s_waitcnt vmcnt(" #n ")" ::: "memory")
; template <int K, int LDA, int LDB, class Epi, class Sched>
; __device__ __forceinline__ void gemm_phase(LAS unsigned char* lds, const Gemm g, const Sched& S, const Epi& E, int wv) {
;     ...
;         for (int t = 0; t < nt; t += 2) {
;             const bool last = (t == nt - 2);
;             const char* a1 = cA + (size_t)(t + 1) * kstep;
;             const char* a2 = last ? nA : cA + (size_t)(t + 2) * kstep; const char* b2 = last ? nB : cB + (size_t)(t + 2) * kstep;
;             const char* a3 = a2 + kstep; const char* b3 = b2 + kstep;
;             PG8_LDB(B0, 0, 0); PG8_LDB(B1, 0, 1); PG8_SCHED; PG8_LDA(At, 0, 0); PG8_STAGE(PG8_SA(1, 1), a1 + hstepA, voffA);
;             PG8_WAIT_V(8); PG8_WAIT_L(0); PG8_BAR; PG8_MMA(0, 0, At, B0); PG8_MMA(0, 1, At, B1); PG8_BAR; PG8_SCHED;
;             PG8_LDA(At, 0, 1); PG8_STAGE(PG8_SB(0, 0), b2, voffB); PG8_STAGE(PG8_SB(0, 1), b2 + hstepB, voffB); PG8_STAGE(PG8_SA(0, 0), a2, voffA);
;             PG8_WAIT_V(8); PG8_WAIT_L(0); PG8_BAR; PG8_MMA(1, 0, At, B0); PG8_MMA(1, 1, At, B1); PG8_BAR; PG8_SCHED;
;             PG8_LDB(B0, 1, 0); PG8_LDB(B1, 1, 1); PG8_SCHED; PG8_LDA(At, 1, 0); PG8_STAGE(PG8_SA(0, 1), a2 + hstepA, voffA);
;             PG8_WAIT_V(8); PG8_WAIT_L(0); PG8_BAR; PG8_MMA(0, 0, At, B0); PG8_MMA(0, 1, At, B1); PG8_BAR; PG8_SCHED;
;             PG8_LDA(At, 1, 1); PG8_STAGE(PG8_SB(1, 0), b3, voffB); PG8_STAGE(PG8_SB(1, 1), b3 + hstepB, voffB); PG8_STAGE(PG8_SA(1, 0), a3, voffA);
;             PG8_WAIT_V(8); PG8_WAIT_L(0); PG8_BAR; PG8_MMA(1, 0, At, B0); PG8_MMA(1, 1, At, B1); PG8_BAR; PG8_SCHED;
	s_mov_b32 m0, s9
	ds_read_b128 v[192:195], v161 offset:49152
	ds_read_b128 v[196:199], v161 offset:50176
	ds_read_b128 v[200:203], v161 offset:51200
	ds_read_b128 v[204:207], v161 offset:52224
	ds_read_b128 v[208:211], v161 offset:53248
	ds_read_b128 v[212:215], v161 offset:54272
	ds_read_b128 v[216:219], v161 offset:55296
	ds_read_b128 v[224:227], v161 offset:56320
	s_add_u32 s98, s76, s56
	s_addc_u32 s99, s77, s57
	global_load_lds_dwordx4 v132, s[98:99]
	s_mov_b32 m0, s14
	s_nop 0
	global_load_lds_dwordx4 v128, s[98:99]
	s_mov_b32 m0, s8
	s_nop 0
	global_load_lds_dwordx4 v132, s[70:71]
	s_mov_b32 m0, s85
	s_nop 0
	global_load_lds_dwordx4 v128, s[70:71]
	s_mov_b32 m0, s91
	s_nop 0
	s_add_u32 s100, s74, s56
	s_addc_u32 s101, s75, s57
	global_load_lds_dwordx4 v134, s[100:101]
	s_mov_b32 m0, s92
	s_nop 0
	global_load_lds_dwordx4 v130, s[100:101]
	s_waitcnt vmcnt(8)
	s_waitcnt lgkmcnt(0)
	s_barrier
	s_setprio 1
	s_waitcnt lgkmcnt(0)
	v_mfma_f32_16x16x32_bf16 v[60:63], v[144:147], v[192:195], v[60:63]
	v_mfma_f32_16x16x32_bf16 v[56:59], v[168:171], v[192:195], v[56:59]
	v_mfma_f32_16x16x32_bf16 v[48:51], v[144:147], v[200:203], v[48:51]
	v_mfma_f32_16x16x32_bf16 v[40:43], v[168:171], v[200:203], v[40:43]
	v_mfma_f32_16x16x32_bf16 v[32:35], v[144:147], v[208:211], v[32:35]
	v_mfma_f32_16x16x32_bf16 v[24:27], v[168:171], v[208:211], v[24:27]
	v_mfma_f32_16x16x32_bf16 v[16:19], v[144:147], v[216:219], v[16:19]
	v_mfma_f32_16x16x32_bf16 v[8:11], v[168:171], v[216:219], v[8:11]
	v_mfma_f32_16x16x32_bf16 v[60:63], v[164:167], v[196:199], v[60:63]
	v_mfma_f32_16x16x32_bf16 v[56:59], v[172:175], v[196:199], v[56:59]
	v_mfma_f32_16x16x32_bf16 v[48:51], v[164:167], v[204:207], v[48:51]
	v_mfma_f32_16x16x32_bf16 v[40:43], v[172:175], v[204:207], v[40:43]
	v_mfma_f32_16x16x32_bf16 v[32:35], v[164:167], v[212:215], v[32:35]
	v_mfma_f32_16x16x32_bf16 v[24:27], v[172:175], v[212:215], v[24:27]
	v_mfma_f32_16x16x32_bf16 v[16:19], v[164:167], v[224:227], v[16:19]
	v_mfma_f32_16x16x32_bf16 v[8:11], v[172:175], v[224:227], v[8:11]
	s_setprio 0
	s_setprio 1
	v_mfma_f32_16x16x32_bf16 v[52:55], v[176:179], v[192:195], v[52:55]
	v_mfma_f32_16x16x32_bf16 v[44:47], v[184:187], v[192:195], v[44:47]
	v_mfma_f32_16x16x32_bf16 v[36:39], v[176:179], v[200:203], v[36:39]
	v_mfma_f32_16x16x32_bf16 v[28:31], v[184:187], v[200:203], v[28:31]
	v_mfma_f32_16x16x32_bf16 v[20:23], v[176:179], v[208:211], v[20:23]
	v_mfma_f32_16x16x32_bf16 v[12:15], v[184:187], v[208:211], v[12:15]
	v_mfma_f32_16x16x32_bf16 v[4:7], v[176:179], v[216:219], v[4:7]
	v_mfma_f32_16x16x32_bf16 v[0:3], v[184:187], v[216:219], v[0:3]
	v_mfma_f32_16x16x32_bf16 v[52:55], v[180:183], v[196:199], v[52:55]
	v_mfma_f32_16x16x32_bf16 v[44:47], v[188:191], v[196:199], v[44:47]
	v_mfma_f32_16x16x32_bf16 v[36:39], v[180:183], v[204:207], v[36:39]
	v_mfma_f32_16x16x32_bf16 v[28:31], v[188:191], v[204:207], v[28:31]
	v_mfma_f32_16x16x32_bf16 v[20:23], v[180:183], v[212:215], v[20:23]
	v_mfma_f32_16x16x32_bf16 v[12:15], v[188:191], v[212:215], v[12:15]
	v_mfma_f32_16x16x32_bf16 v[4:7], v[180:183], v[224:227], v[4:7]
	v_mfma_f32_16x16x32_bf16 v[0:3], v[188:191], v[224:227], v[0:3]
	s_setprio 0
	s_barrier
	s_andn2_b64 vcc, exec, s[12:13]
	s_mov_b64 s[70:71], -1
	s_mov_b64 s[12:13], 0
	s_mov_b64 s[72:73], 0x100
	s_cbranch_vccz .LBB0_519
	s_and_b64 vcc, exec, s[28:29]
	s_cbranch_vccz .LBB0_522
	s_barrier

; #define PG8_STAGE(bufoff, gbase, voff) do { _Pragma("unroll") for (int _i = 0; _i < 2; ++_i) \
;         __builtin_amdgcn_global_load_lds((const unsigned*)((const char*)(gbase) + (voff)[_i]), (LAS unsigned*)(lds + (bufoff) + ldsw + _i * 8192), 16, 0, 0); } while (0)
; #define PG8_LDA(dst, b, h) do { _Pragma("unroll") for (int m = 0; m < 4; ++m) _Pragma("unroll") for (int k = 0; k < 2; ++k) dst[m][k] = *(const LAS bf16x8*)(lds + PG8_SA(b, h) + aoff + m * 2048 + k * 1024); } while (0)
; #define PG8_LDB(dst, b, h) do { _Pragma("unroll") for (int n = 0; n < 2; ++n) _Pragma("unroll") for (int k = 0; k < 2; ++k) dst[n][k] = *(const LAS bf16x8*)(lds + PG8_SB(b, h) + boff + n * 2048 + k * 1024); } while (0)
; #define PG8_WAIT_V(n) asm volatile("s_waitcnt vmcnt(" #n ")" ::: "memory")
; template <int K, int LDA, int LDB, class Epi, class Sched>
; __device__ __forceinline__ void gemm_phase(LAS unsigned char* lds, const Gemm g, const Sched& S, const Epi& E, int wv) {
;     ...
;         for (int t = 0; t < nt; t += 2) {
;             const bool last = (t == nt - 2);
;             const char* a1 = cA + (size_t)(t + 1) * kstep;
;             const char* a2 = last ? nA : cA + (size_t)(t + 2) * kstep; const char* b2 = last ? nB : cB + (size_t)(t + 2) * kstep;
;             const char* a3 = a2 + kstep; const char* b3 = b2 + kstep;
;             PG8_LDB(B0, 0, 0); PG8_LDB(B1, 0, 1); PG8_SCHED; PG8_LDA(At, 0, 0); PG8_STAGE(PG8_SA(1, 1), a1 + hstepA, voffA);
;             PG8_WAIT_V(8); PG8_WAIT_L(0); PG8_BAR; PG8_MMA(0, 0, At, B0); PG8_MMA(0, 1, At, B1); PG8_BAR; PG8_SCHED;
;             PG8_LDA(At, 0, 1); PG8_STAGE(PG8_SB(0, 0), b2, voffB); PG8_STAGE(PG8_SB(0, 1), b2 + hstepB, voffB); PG8_STAGE(PG8_SA(0, 0), a2, voffA);
;             PG8_WAIT_V(8); PG8_WAIT_L(0); PG8_BAR; PG8_MMA(1, 0, At, B0); PG8_MMA(1, 1, At, B1); PG8_BAR; PG8_SCHED;
;             PG8_LDB(B0, 1, 0); PG8_LDB(B1, 1, 1); PG8_SCHED; PG8_LDA(At, 1, 0); PG8_STAGE(PG8_SA(0, 1), a2 + hstepA, voffA);
;             PG8_WAIT_V(8); PG8_WAIT_L(0); PG8_BAR; PG8_MMA(0, 0, At, B0); PG8_MMA(0, 1, At, B1); PG8_BAR; PG8_SCHED;
;             PG8_LDA(At, 1, 1); PG8_STAGE(PG8_SB(1, 0), b3, voffB); PG8_STAGE(PG8_SB(1, 1), b3 + hstepB, voffB); PG8_STAGE(PG8_SA(1, 0), a3, voffA);
;             PG8_WAIT_V(8); PG8_WAIT_L(0); PG8_BAR; PG8_MMA(1, 0, At, B0); PG8_MMA(1, 1, At, B1); PG8_BAR; PG8_SCHED;
.LBB0_541:
	s_add_u32 s14, s70, s74
	s_addc_u32 s15, s71, s75
	s_add_u32 s34, s14, 0x100
	s_addc_u32 s35, s15, 0
	s_and_b64 s[8:9], s[72:73], exec
	s_cselect_b32 s77, s61, s35
	s_cselect_b32 s76, s96, s34
	s_add_u32 s8, s68, s74
	s_addc_u32 s9, s69, s75
	s_add_u32 s34, s8, 0x100
	s_addc_u32 s35, s9, 0
	s_and_b64 s[8:9], s[72:73], exec
	s_cselect_b32 s79, s63, s35
	s_cselect_b32 s78, s62, s34
	s_add_u32 s82, s14, 0x10080
	ds_read_b128 v[128:131], v165
	ds_read_b128 v[144:147], v165 offset:1024
	ds_read_b128 v[148:151], v165 offset:2048
	ds_read_b128 v[152:155], v165 offset:3072
	ds_read_b128 v[156:159], v166
	ds_read_b128 v[170:173], v166 offset:1024
	ds_read_b128 v[174:177], v166 offset:2048
	ds_read_b128 v[178:181], v166 offset:3072
	s_addc_u32 s83, s15, 0
	s_add_i32 s50, s92, s24
	s_add_i32 m0, s67, 0xc000
	s_add_i32 s34, s67, 0xe000
	s_add_i32 s14, s50, 0x2000
	s_add_u32 s80, s78, 0x120000
	s_addc_u32 s81, s79, 0
	s_add_i32 s85, s93, s24
	s_add_i32 s15, s85, 0x2000
	s_add_i32 vcc_hi, 0, 0x18000
	s_add_i32 vcc_lo, 0, 0x1c000
	s_add_u32 s74, s76, 0x10000
	s_addc_u32 s75, s77, 0
	s_add_i32 s97, vcc_hi, s24
	s_add_i32 s9, s97, 0x2000
	s_add_u32 s72, s78, 0x120080
	s_addc_u32 s73, s79, 0
	s_add_i32 s84, vcc_lo, s24
	s_add_i32 s8, s84, 0x2000
	ds_read_b128 v[182:185], v167
	ds_read_b128 v[186:189], v167 offset:1024
	ds_read_b128 v[190:193], v167 offset:2048
	ds_read_b128 v[194:197], v167 offset:3072
	ds_read_b128 v[198:201], v167 offset:4096
	ds_read_b128 v[202:205], v167 offset:5120
	ds_read_b128 v[206:209], v167 offset:6144
	ds_read_b128 v[210:213], v167 offset:7168
	global_load_lds_dwordx4 v138, s[82:83]
	s_mov_b32 m0, s34
	s_nop 0
	global_load_lds_dwordx4 v134, s[82:83]
	s_waitcnt vmcnt(8)
	s_waitcnt lgkmcnt(0)
	s_barrier
	s_setprio 1
	s_waitcnt lgkmcnt(0)
	v_mfma_f32_16x16x32_bf16 v[124:127], v[128:131], v[182:185], v[124:127]
	v_mfma_f32_16x16x32_bf16 v[120:123], v[148:151], v[182:185], v[120:123]
	v_mfma_f32_16x16x32_bf16 v[112:115], v[128:131], v[190:193], v[112:115]
	v_mfma_f32_16x16x32_bf16 v[104:107], v[148:151], v[190:193], v[104:107]
	v_mfma_f32_16x16x32_bf16 v[96:99], v[128:131], v[198:201], v[96:99]
	v_mfma_f32_16x16x32_bf16 v[88:91], v[148:151], v[198:201], v[88:91]
	v_mfma_f32_16x16x32_bf16 v[80:83], v[128:131], v[206:209], v[80:83]
	v_mfma_f32_16x16x32_bf16 v[72:75], v[148:151], v[206:209], v[72:75]
	v_mfma_f32_16x16x32_bf16 v[124:127], v[144:147], v[186:189], v[124:127]
	v_mfma_f32_16x16x32_bf16 v[120:123], v[152:155], v[186:189], v[120:123]
	v_mfma_f32_16x16x32_bf16 v[112:115], v[144:147], v[194:197], v[112:115]
	v_mfma_f32_16x16x32_bf16 v[104:107], v[152:155], v[194:197], v[104:107]
	v_mfma_f32_16x16x32_bf16 v[96:99], v[144:147], v[202:205], v[96:99]
	v_mfma_f32_16x16x32_bf16 v[88:91], v[152:155], v[202:205], v[88:91]
	v_mfma_f32_16x16x32_bf16 v[80:83], v[144:147], v[210:213], v[80:83]
	v_mfma_f32_16x16x32_bf16 v[72:75], v[152:155], v[210:213], v[72:75]
	s_setprio 0
	s_setprio 1
	v_mfma_f32_16x16x32_bf16 v[116:119], v[156:159], v[182:185], v[116:119]
	v_mfma_f32_16x16x32_bf16 v[108:111], v[174:177], v[182:185], v[108:111]
	v_mfma_f32_16x16x32_bf16 v[100:103], v[156:159], v[190:193], v[100:103]
	v_mfma_f32_16x16x32_bf16 v[92:95], v[174:177], v[190:193], v[92:95]
	v_mfma_f32_16x16x32_bf16 v[84:87], v[156:159], v[198:201], v[84:87]
	v_mfma_f32_16x16x32_bf16 v[76:79], v[174:177], v[198:201], v[76:79]
	v_mfma_f32_16x16x32_bf16 v[68:71], v[156:159], v[206:209], v[68:71]
	v_mfma_f32_16x16x32_bf16 v[64:67], v[174:177], v[206:209], v[64:67]
	v_mfma_f32_16x16x32_bf16 v[116:119], v[170:173], v[186:189], v[116:119]
	v_mfma_f32_16x16x32_bf16 v[108:111], v[178:181], v[186:189], v[108:111]
	v_mfma_f32_16x16x32_bf16 v[100:103], v[170:173], v[194:197], v[100:103]
	v_mfma_f32_16x16x32_bf16 v[92:95], v[178:181], v[194:197], v[92:95]
	v_mfma_f32_16x16x32_bf16 v[84:87], v[170:173], v[202:205], v[84:87]
	v_mfma_f32_16x16x32_bf16 v[76:79], v[178:181], v[202:205], v[76:79]
	v_mfma_f32_16x16x32_bf16 v[68:71], v[170:173], v[210:213], v[68:71]
	v_mfma_f32_16x16x32_bf16 v[64:67], v[178:181], v[210:213], v[64:67]
	s_setprio 0
	s_barrier
	s_mov_b32 m0, s50
	ds_read_b128 v[182:185], v167 offset:16384
	ds_read_b128 v[186:189], v167 offset:17408
	ds_read_b128 v[190:193], v167 offset:18432
	ds_read_b128 v[194:197], v167 offset:19456
	ds_read_b128 v[198:201], v167 offset:20480
	ds_read_b128 v[202:205], v167 offset:21504
	ds_read_b128 v[206:209], v167 offset:22528
	ds_read_b128 v[210:213], v167 offset:23552
	global_load_lds_dwordx4 v136, s[78:79]
	s_mov_b32 m0, s14
	s_nop 0
	global_load_lds_dwordx4 v132, s[78:79]
	s_mov_b32 m0, s85
	s_nop 0
	global_load_lds_dwordx4 v136, s[80:81]
	s_mov_b32 m0, s15
	s_nop 0
	global_load_lds_dwordx4 v132, s[80:81]
	s_mov_b32 m0, s67
	s_nop 0
	global_load_lds_dwordx4 v138, s[76:77]
	s_mov_b32 m0, s86
	s_nop 0
	global_load_lds_dwordx4 v134, s[76:77]
	s_waitcnt vmcnt(8)
	s_waitcnt lgkmcnt(0)
	s_barrier
; #define PG8_STAGE(bufoff, gbase, voff) do { _Pragma("unroll") for (int _i = 0; _i < 2; ++_i) \
;         __builtin_amdgcn_global_load_lds((const unsigned*)((const char*)(gbase) + (voff)[_i]), (LAS unsigned*)(lds + (bufoff) + ldsw + _i * 8192), 16, 0, 0); } while (0)
; #define PG8_LDA(dst, b, h) do { _Pragma("unroll") for (int m = 0; m < 4; ++m) _Pragma("unroll") for (int k = 0; k < 2; ++k) dst[m][k] = *(const LAS bf16x8*)(lds + PG8_SA(b, h) + aoff + m * 2048 + k * 1024); } while (0)
; #define PG8_LDB(dst, b, h) do { _Pragma("unroll") for (int n = 0; n < 2; ++n) _Pragma("unroll") for (int k = 0; k < 2; ++k) dst[n][k] = *(const LAS bf16x8*)(lds + PG8_SB(b, h) + boff + n * 2048 + k * 1024); } while (0)
; #define PG8_WAIT_V(n) asm volatile("s_waitcnt vmcnt(" #n ")" ::: "memory")
; template <int K, int LDA, int LDB, class Epi, class Sched>
; __device__ __forceinline__ void gemm_phase(LAS unsigned char* lds, const Gemm g, const Sched& S, const Epi& E, int wv) {
;     ...
;         for (int t = 0; t < nt; t += 2) {
;             const bool last = (t == nt - 2);
;             const char* a1 = cA + (size_t)(t + 1) * kstep;
;             const char* a2 = last ? nA : cA + (size_t)(t + 2) * kstep; const char* b2 = last ? nB : cB + (size_t)(t + 2) * kstep;
;             const char* a3 = a2 + kstep; const char* b3 = b2 + kstep;
;             PG8_LDB(B0, 0, 0); PG8_LDB(B1, 0, 1); PG8_SCHED; PG8_LDA(At, 0, 0); PG8_STAGE(PG8_SA(1, 1), a1 + hstepA, voffA);
;             PG8_WAIT_V(8); PG8_WAIT_L(0); PG8_BAR; PG8_MMA(0, 0, At, B0); PG8_MMA(0, 1, At, B1); PG8_BAR; PG8_SCHED;
;             PG8_LDA(At, 0, 1); PG8_STAGE(PG8_SB(0, 0), b2, voffB); PG8_STAGE(PG8_SB(0, 1), b2 + hstepB, voffB); PG8_STAGE(PG8_SA(0, 0), a2, voffA);
;             PG8_WAIT_V(8); PG8_WAIT_L(0); PG8_BAR; PG8_MMA(1, 0, At, B0); PG8_MMA(1, 1, At, B1); PG8_BAR; PG8_SCHED;
;             PG8_LDB(B0, 1, 0); PG8_LDB(B1, 1, 1); PG8_SCHED; PG8_LDA(At, 1, 0); PG8_STAGE(PG8_SA(0, 1), a2 + hstepA, voffA);
;             PG8_WAIT_V(8); PG8_WAIT_L(0); PG8_BAR; PG8_MMA(0, 0, At, B0); PG8_MMA(0, 1, At, B1); PG8_BAR; PG8_SCHED;
;             PG8_LDA(At, 1, 1); PG8_STAGE(PG8_SB(1, 0), b3, voffB); PG8_STAGE(PG8_SB(1, 1), b3 + hstepB, voffB); PG8_STAGE(PG8_SA(1, 0), a3, voffA);
;             PG8_WAIT_V(8); PG8_WAIT_L(0); PG8_BAR; PG8_MMA(1, 0, At, B0); PG8_MMA(1, 1, At, B1); PG8_BAR; PG8_SCHED;
	s_setprio 1
	s_waitcnt lgkmcnt(0)
	v_mfma_f32_16x16x32_bf16 v[60:63], v[128:131], v[182:185], v[60:63]
	v_mfma_f32_16x16x32_bf16 v[56:59], v[148:151], v[182:185], v[56:59]
	v_mfma_f32_16x16x32_bf16 v[48:51], v[128:131], v[190:193], v[48:51]
	v_mfma_f32_16x16x32_bf16 v[40:43], v[148:151], v[190:193], v[40:43]
	v_mfma_f32_16x16x32_bf16 v[32:35], v[128:131], v[198:201], v[32:35]
	v_mfma_f32_16x16x32_bf16 v[24:27], v[148:151], v[198:201], v[24:27]
	v_mfma_f32_16x16x32_bf16 v[16:19], v[128:131], v[206:209], v[16:19]
	v_mfma_f32_16x16x32_bf16 v[8:11], v[148:151], v[206:209], v[8:11]
	v_mfma_f32_16x16x32_bf16 v[60:63], v[144:147], v[186:189], v[60:63]
	v_mfma_f32_16x16x32_bf16 v[56:59], v[152:155], v[186:189], v[56:59]
	v_mfma_f32_16x16x32_bf16 v[48:51], v[144:147], v[194:197], v[48:51]
	v_mfma_f32_16x16x32_bf16 v[40:43], v[152:155], v[194:197], v[40:43]
	v_mfma_f32_16x16x32_bf16 v[32:35], v[144:147], v[202:205], v[32:35]
	v_mfma_f32_16x16x32_bf16 v[24:27], v[152:155], v[202:205], v[24:27]
	v_mfma_f32_16x16x32_bf16 v[16:19], v[144:147], v[210:213], v[16:19]
	v_mfma_f32_16x16x32_bf16 v[8:11], v[152:155], v[210:213], v[8:11]
	s_setprio 0
	s_setprio 1
	v_mfma_f32_16x16x32_bf16 v[52:55], v[156:159], v[182:185], v[52:55]
	v_mfma_f32_16x16x32_bf16 v[44:47], v[174:177], v[182:185], v[44:47]
	v_mfma_f32_16x16x32_bf16 v[36:39], v[156:159], v[190:193], v[36:39]
	v_mfma_f32_16x16x32_bf16 v[28:31], v[174:177], v[190:193], v[28:31]
	v_mfma_f32_16x16x32_bf16 v[20:23], v[156:159], v[198:201], v[20:23]
	v_mfma_f32_16x16x32_bf16 v[12:15], v[174:177], v[198:201], v[12:15]
	v_mfma_f32_16x16x32_bf16 v[4:7], v[156:159], v[206:209], v[4:7]
	v_mfma_f32_16x16x32_bf16 v[0:3], v[174:177], v[206:209], v[0:3]
	v_mfma_f32_16x16x32_bf16 v[52:55], v[170:173], v[186:189], v[52:55]
	v_mfma_f32_16x16x32_bf16 v[44:47], v[178:181], v[186:189], v[44:47]
	v_mfma_f32_16x16x32_bf16 v[36:39], v[170:173], v[194:197], v[36:39]
	v_mfma_f32_16x16x32_bf16 v[28:31], v[178:181], v[194:197], v[28:31]
	v_mfma_f32_16x16x32_bf16 v[20:23], v[170:173], v[202:205], v[20:23]
	v_mfma_f32_16x16x32_bf16 v[12:15], v[178:181], v[202:205], v[12:15]
	v_mfma_f32_16x16x32_bf16 v[4:7], v[170:173], v[210:213], v[4:7]
	v_mfma_f32_16x16x32_bf16 v[0:3], v[178:181], v[210:213], v[0:3]
	s_setprio 0
	s_barrier
	v_add_u32_e32 v152, vcc_hi, v163
	v_add_u32_e32 v169, vcc_lo, v163
	ds_read_b128 v[128:131], v152
	ds_read_b128 v[144:147], v152 offset:1024
	ds_read_b128 v[148:151], v152 offset:2048
	ds_read_b128 v[152:155], v152 offset:3072
	ds_read_b128 v[156:159], v169
	ds_read_b128 v[170:173], v169 offset:1024
	ds_read_b128 v[174:177], v169 offset:2048
	ds_read_b128 v[178:181], v169 offset:3072
	s_mov_b32 m0, s87
	ds_read_b128 v[182:185], v167 offset:32768
	ds_read_b128 v[186:189], v167 offset:33792
	ds_read_b128 v[190:193], v167 offset:34816
	ds_read_b128 v[194:197], v167 offset:35840
	ds_read_b128 v[198:201], v167 offset:36864
	ds_read_b128 v[202:205], v167 offset:37888
	ds_read_b128 v[206:209], v167 offset:38912
	ds_read_b128 v[210:213], v167 offset:39936
	global_load_lds_dwordx4 v138, s[74:75]
	s_mov_b32 m0, s88
	s_nop 0
	global_load_lds_dwordx4 v134, s[74:75]
	s_waitcnt vmcnt(8)
	s_waitcnt lgkmcnt(0)
	s_barrier
	s_setprio 1
	s_waitcnt lgkmcnt(0)
	v_mfma_f32_16x16x32_bf16 v[124:127], v[128:131], v[182:185], v[124:127]
	v_mfma_f32_16x16x32_bf16 v[120:123], v[148:151], v[182:185], v[120:123]
	v_mfma_f32_16x16x32_bf16 v[112:115], v[128:131], v[190:193], v[112:115]
	v_mfma_f32_16x16x32_bf16 v[104:107], v[148:151], v[190:193], v[104:107]
	v_mfma_f32_16x16x32_bf16 v[96:99], v[128:131], v[198:201], v[96:99]
	v_mfma_f32_16x16x32_bf16 v[88:91], v[148:151], v[198:201], v[88:91]
	v_mfma_f32_16x16x32_bf16 v[80:83], v[128:131], v[206:209], v[80:83]
	v_mfma_f32_16x16x32_bf16 v[72:75], v[148:151], v[206:209], v[72:75]
	v_mfma_f32_16x16x32_bf16 v[124:127], v[144:147], v[186:189], v[124:127]
	v_mfma_f32_16x16x32_bf16 v[120:123], v[152:155], v[186:189], v[120:123]
	v_mfma_f32_16x16x32_bf16 v[112:115], v[144:147], v[194:197], v[112:115]
	v_mfma_f32_16x16x32_bf16 v[104:107], v[152:155], v[194:197], v[104:107]
	v_mfma_f32_16x16x32_bf16 v[96:99], v[144:147], v[202:205], v[96:99]
	v_mfma_f32_16x16x32_bf16 v[88:91], v[152:155], v[202:205], v[88:91]
	v_mfma_f32_16x16x32_bf16 v[80:83], v[144:147], v[210:213], v[80:83]
	v_mfma_f32_16x16x32_bf16 v[72:75], v[152:155], v[210:213], v[72:75]
	s_setprio 0
	s_setprio 1
	v_mfma_f32_16x16x32_bf16 v[116:119], v[156:159], v[182:185], v[116:119]
	v_mfma_f32_16x16x32_bf16 v[108:111], v[174:177], v[182:185], v[108:111]
	v_mfma_f32_16x16x32_bf16 v[100:103], v[156:159], v[190:193], v[100:103]
	v_mfma_f32_16x16x32_bf16 v[92:95], v[174:177], v[190:193], v[92:95]
	v_mfma_f32_16x16x32_bf16 v[84:87], v[156:159], v[198:201], v[84:87]
	v_mfma_f32_16x16x32_bf16 v[76:79], v[174:177], v[198:201], v[76:79]
	v_mfma_f32_16x16x32_bf16 v[68:71], v[156:159], v[206:209], v[68:71]
	v_mfma_f32_16x16x32_bf16 v[64:67], v[174:177], v[206:209], v[64:67]
	v_mfma_f32_16x16x32_bf16 v[116:119], v[170:173], v[186:189], v[116:119]
	v_mfma_f32_16x16x32_bf16 v[108:111], v[178:181], v[186:189], v[108:111]
	v_mfma_f32_16x16x32_bf16 v[100:103], v[170:173], v[194:197], v[100:103]
	v_mfma_f32_16x16x32_bf16 v[92:95], v[178:181], v[194:197], v[92:95]
	v_mfma_f32_16x16x32_bf16 v[84:87], v[170:173], v[202:205], v[84:87]
	v_mfma_f32_16x16x32_bf16 v[76:79], v[178:181], v[202:205], v[76:79]
	v_mfma_f32_16x16x32_bf16 v[68:71], v[170:173], v[210:213], v[68:71]
	v_mfma_f32_16x16x32_bf16 v[64:67], v[178:181], v[210:213], v[64:67]
	s_setprio 0
	s_barrier
; #define PG8_STAGE(bufoff, gbase, voff) do { _Pragma("unroll") for (int _i = 0; _i < 2; ++_i) \
;         __builtin_amdgcn_global_load_lds((const unsigned*)((const char*)(gbase) + (voff)[_i]), (LAS unsigned*)(lds + (bufoff) + ldsw + _i * 8192), 16, 0, 0); } while (0)
; #define PG8_LDA(dst, b, h) do { _Pragma("unroll") for (int m = 0; m < 4; ++m) _Pragma("unroll") for (int k = 0; k < 2; ++k) dst[m][k] = *(const LAS bf16x8*)(lds + PG8_SA(b, h) + aoff + m * 2048 + k * 1024); } while (0)
; #define PG8_LDB(dst, b, h) do { _Pragma("unroll") for (int n = 0; n < 2; ++n) _Pragma("unroll") for (int k = 0; k < 2; ++k) dst[n][k] = *(const LAS bf16x8*)(lds + PG8_SB(b, h) + boff + n * 2048 + k * 1024); } while (0)
; #define PG8_WAIT_V(n) asm volatile("s_waitcnt vmcnt(" #n ")" ::: "memory")
; template <int K, int LDA, int LDB, class Epi, class Sched>
; __device__ __forceinline__ void gemm_phase(LAS unsigned char* lds, const Gemm g, const Sched& S, const Epi& E, int wv) {
;     ...
;         for (int t = 0; t < nt; t += 2) {
;             const bool last = (t == nt - 2);
;             const char* a1 = cA + (size_t)(t + 1) * kstep;
;             const char* a2 = last ? nA : cA + (size_t)(t + 2) * kstep; const char* b2 = last ? nB : cB + (size_t)(t + 2) * kstep;
;             const char* a3 = a2 + kstep; const char* b3 = b2 + kstep;
;             PG8_LDB(B0, 0, 0); PG8_LDB(B1, 0, 1); PG8_SCHED; PG8_LDA(At, 0, 0); PG8_STAGE(PG8_SA(1, 1), a1 + hstepA, voffA);
;             PG8_WAIT_V(8); PG8_WAIT_L(0); PG8_BAR; PG8_MMA(0, 0, At, B0); PG8_MMA(0, 1, At, B1); PG8_BAR; PG8_SCHED;
;             PG8_LDA(At, 0, 1); PG8_STAGE(PG8_SB(0, 0), b2, voffB); PG8_STAGE(PG8_SB(0, 1), b2 + hstepB, voffB); PG8_STAGE(PG8_SA(0, 0), a2, voffA);
;             PG8_WAIT_V(8); PG8_WAIT_L(0); PG8_BAR; PG8_MMA(1, 0, At, B0); PG8_MMA(1, 1, At, B1); PG8_BAR; PG8_SCHED;
;             PG8_LDB(B0, 1, 0); PG8_LDB(B1, 1, 1); PG8_SCHED; PG8_LDA(At, 1, 0); PG8_STAGE(PG8_SA(0, 1), a2 + hstepA, voffA);
;             PG8_WAIT_V(8); PG8_WAIT_L(0); PG8_BAR; PG8_MMA(0, 0, At, B0); PG8_MMA(0, 1, At, B1); PG8_BAR; PG8_SCHED;
;             PG8_LDA(At, 1, 1); PG8_STAGE(PG8_SB(1, 0), b3, voffB); PG8_STAGE(PG8_SB(1, 1), b3 + hstepB, voffB); PG8_STAGE(PG8_SA(1, 0), a3, voffA);
;             PG8_WAIT_V(8); PG8_WAIT_L(0); PG8_BAR; PG8_MMA(1, 0, At, B0); PG8_MMA(1, 1, At, B1); PG8_BAR; PG8_SCHED;
	s_mov_b32 m0, s97
	ds_read_b128 v[182:185], v167 offset:49152
	ds_read_b128 v[186:189], v167 offset:50176
	ds_read_b128 v[190:193], v167 offset:51200
	ds_read_b128 v[194:197], v167 offset:52224
	ds_read_b128 v[198:201], v167 offset:53248
	ds_read_b128 v[202:205], v167 offset:54272
	ds_read_b128 v[206:209], v167 offset:55296
	ds_read_b128 v[210:213], v167 offset:56320
	s_add_u32 s98, s78, s58
	s_addc_u32 s99, s79, s59
	global_load_lds_dwordx4 v136, s[98:99]
	s_mov_b32 m0, s9
	s_nop 0
	global_load_lds_dwordx4 v132, s[98:99]
	s_mov_b32 m0, s84
	s_nop 0
	global_load_lds_dwordx4 v136, s[72:73]
	s_mov_b32 m0, s8
	s_nop 0
	global_load_lds_dwordx4 v132, s[72:73]
	s_mov_b32 m0, s90
	s_nop 0
	s_add_u32 s100, s76, s58
	s_addc_u32 s101, s77, s59
	global_load_lds_dwordx4 v138, s[100:101]
	s_mov_b32 m0, s91
	s_nop 0
	global_load_lds_dwordx4 v134, s[100:101]
	s_waitcnt vmcnt(8)
	s_waitcnt lgkmcnt(0)
	s_barrier
	s_setprio 1
	s_waitcnt lgkmcnt(0)
	v_mfma_f32_16x16x32_bf16 v[60:63], v[128:131], v[182:185], v[60:63]
	v_mfma_f32_16x16x32_bf16 v[56:59], v[148:151], v[182:185], v[56:59]
	v_mfma_f32_16x16x32_bf16 v[48:51], v[128:131], v[190:193], v[48:51]
	v_mfma_f32_16x16x32_bf16 v[40:43], v[148:151], v[190:193], v[40:43]
	v_mfma_f32_16x16x32_bf16 v[32:35], v[128:131], v[198:201], v[32:35]
	v_mfma_f32_16x16x32_bf16 v[24:27], v[148:151], v[198:201], v[24:27]
	v_mfma_f32_16x16x32_bf16 v[16:19], v[128:131], v[206:209], v[16:19]
	v_mfma_f32_16x16x32_bf16 v[8:11], v[148:151], v[206:209], v[8:11]
	v_mfma_f32_16x16x32_bf16 v[60:63], v[144:147], v[186:189], v[60:63]
	v_mfma_f32_16x16x32_bf16 v[56:59], v[152:155], v[186:189], v[56:59]
	v_mfma_f32_16x16x32_bf16 v[48:51], v[144:147], v[194:197], v[48:51]
	v_mfma_f32_16x16x32_bf16 v[40:43], v[152:155], v[194:197], v[40:43]
	v_mfma_f32_16x16x32_bf16 v[32:35], v[144:147], v[202:205], v[32:35]
	v_mfma_f32_16x16x32_bf16 v[24:27], v[152:155], v[202:205], v[24:27]
	v_mfma_f32_16x16x32_bf16 v[16:19], v[144:147], v[210:213], v[16:19]
	v_mfma_f32_16x16x32_bf16 v[8:11], v[152:155], v[210:213], v[8:11]
	s_setprio 0
	s_setprio 1
	v_mfma_f32_16x16x32_bf16 v[52:55], v[156:159], v[182:185], v[52:55]
	v_mfma_f32_16x16x32_bf16 v[44:47], v[174:177], v[182:185], v[44:47]
	v_mfma_f32_16x16x32_bf16 v[36:39], v[156:159], v[190:193], v[36:39]
	v_mfma_f32_16x16x32_bf16 v[28:31], v[174:177], v[190:193], v[28:31]
	v_mfma_f32_16x16x32_bf16 v[20:23], v[156:159], v[198:201], v[20:23]
	v_mfma_f32_16x16x32_bf16 v[12:15], v[174:177], v[198:201], v[12:15]
	v_mfma_f32_16x16x32_bf16 v[4:7], v[156:159], v[206:209], v[4:7]
	v_mfma_f32_16x16x32_bf16 v[0:3], v[174:177], v[206:209], v[0:3]
	v_mfma_f32_16x16x32_bf16 v[52:55], v[170:173], v[186:189], v[52:55]
	v_mfma_f32_16x16x32_bf16 v[44:47], v[178:181], v[186:189], v[44:47]
	v_mfma_f32_16x16x32_bf16 v[36:39], v[170:173], v[194:197], v[36:39]
	v_mfma_f32_16x16x32_bf16 v[28:31], v[178:181], v[194:197], v[28:31]
	v_mfma_f32_16x16x32_bf16 v[20:23], v[170:173], v[202:205], v[20:23]
	v_mfma_f32_16x16x32_bf16 v[12:15], v[178:181], v[202:205], v[12:15]
	v_mfma_f32_16x16x32_bf16 v[4:7], v[170:173], v[210:213], v[4:7]
	v_mfma_f32_16x16x32_bf16 v[0:3], v[178:181], v[210:213], v[0:3]
	s_setprio 0
	s_barrier
	s_andn2_b64 vcc, exec, s[16:17]
	s_mov_b64 s[72:73], -1
	s_mov_b64 s[16:17], 0
	s_mov_b64 s[74:75], 0x100
	s_cbranch_vccz .LBB0_541
	s_and_b64 vcc, exec, s[28:29]
	s_cbranch_vccz .LBB0_544
	s_barrier

; #define PG8_STAGE(bufoff, gbase, voff) do { _Pragma("unroll") for (int _i = 0; _i < 2; ++_i) \
;         __builtin_amdgcn_global_load_lds((const unsigned*)((const char*)(gbase) + (voff)[_i]), (LAS unsigned*)(lds + (bufoff) + ldsw + _i * 8192), 16, 0, 0); } while (0)
; #define PG8_LDA(dst, b, h) do { _Pragma("unroll") for (int m = 0; m < 4; ++m) _Pragma("unroll") for (int k = 0; k < 2; ++k) dst[m][k] = *(const LAS bf16x8*)(lds + PG8_SA(b, h) + aoff + m * 2048 + k * 1024); } while (0)
; #define PG8_LDB(dst, b, h) do { _Pragma("unroll") for (int n = 0; n < 2; ++n) _Pragma("unroll") for (int k = 0; k < 2; ++k) dst[n][k] = *(const LAS bf16x8*)(lds + PG8_SB(b, h) + boff + n * 2048 + k * 1024); } while (0)
; #define PG8_WAIT_V(n) asm volatile("s_waitcnt vmcnt(" #n ")" ::: "memory")
; template <int K, int LDA, int LDB, class Epi, class Sched>
; __device__ __forceinline__ void gemm_phase(LAS unsigned char* lds, const Gemm g, const Sched& S, const Epi& E, int wv) {
;     ...
;         for (int t = 0; t < nt; t += 2) {
;             const bool last = (t == nt - 2);
;             const char* a1 = cA + (size_t)(t + 1) * kstep;
;             const char* a2 = last ? nA : cA + (size_t)(t + 2) * kstep; const char* b2 = last ? nB : cB + (size_t)(t + 2) * kstep;
;             const char* a3 = a2 + kstep; const char* b3 = b2 + kstep;
;             PG8_LDB(B0, 0, 0); PG8_LDB(B1, 0, 1); PG8_SCHED; PG8_LDA(At, 0, 0); PG8_STAGE(PG8_SA(1, 1), a1 + hstepA, voffA);
;             PG8_WAIT_V(8); PG8_WAIT_L(0); PG8_BAR; PG8_MMA(0, 0, At, B0); PG8_MMA(0, 1, At, B1); PG8_BAR; PG8_SCHED;
;             PG8_LDA(At, 0, 1); PG8_STAGE(PG8_SB(0, 0), b2, voffB); PG8_STAGE(PG8_SB(0, 1), b2 + hstepB, voffB); PG8_STAGE(PG8_SA(0, 0), a2, voffA);
;             PG8_WAIT_V(8); PG8_WAIT_L(0); PG8_BAR; PG8_MMA(1, 0, At, B0); PG8_MMA(1, 1, At, B1); PG8_BAR; PG8_SCHED;
;             PG8_LDB(B0, 1, 0); PG8_LDB(B1, 1, 1); PG8_SCHED; PG8_LDA(At, 1, 0); PG8_STAGE(PG8_SA(0, 1), a2 + hstepA, voffA);
;             PG8_WAIT_V(8); PG8_WAIT_L(0); PG8_BAR; PG8_MMA(0, 0, At, B0); PG8_MMA(0, 1, At, B1); PG8_BAR; PG8_SCHED;
;             PG8_LDA(At, 1, 1); PG8_STAGE(PG8_SB(1, 0), b3, voffB); PG8_STAGE(PG8_SB(1, 1), b3 + hstepB, voffB); PG8_STAGE(PG8_SA(1, 0), a3, voffA);
;             PG8_WAIT_V(8); PG8_WAIT_L(0); PG8_BAR; PG8_MMA(1, 0, At, B0); PG8_MMA(1, 1, At, B1); PG8_BAR; PG8_SCHED;
.LBB0_700:
	ds_read_b128 v[144:147], v185
	ds_read_b128 v[148:151], v185 offset:1024
	ds_read_b128 v[152:155], v185 offset:2048
	ds_read_b128 v[156:159], v185 offset:3072
	ds_read_b128 v[160:163], v186
	ds_read_b128 v[164:167], v186 offset:1024
	ds_read_b128 v[168:171], v186 offset:2048
	ds_read_b128 v[172:175], v186 offset:3072
	s_add_u32 s8, s66, 0xfff80080
	s_addc_u32 s9, s67, -1
	s_cmp_eq_u32 s82, 28
	s_cselect_b32 s71, s59, s9
	s_cselect_b32 s70, s78, s8
	s_cselect_b32 s69, s57, s81
	s_cselect_b32 s68, s79, s80
	s_add_i32 m0, s44, 0xc000
	ds_read_b128 v[176:179], v187
	ds_read_b128 v[188:191], v187 offset:1024
	ds_read_b128 v[192:195], v187 offset:2048
	ds_read_b128 v[196:199], v187 offset:3072
	ds_read_b128 v[200:203], v187 offset:4096
	ds_read_b128 v[204:207], v187 offset:5120
	ds_read_b128 v[208:211], v187 offset:6144
	ds_read_b128 v[212:215], v187 offset:7168
	global_load_lds_dwordx4 v136, s[66:67]
	s_add_i32 m0, s44, 0xe000
	s_nop 0
	global_load_lds_dwordx4 v138, s[66:67]
	s_waitcnt vmcnt(8)
	s_waitcnt lgkmcnt(0)
	s_barrier
	s_setprio 1
	s_waitcnt lgkmcnt(0)
	v_mfma_f32_16x16x32_bf16 v[124:127], v[144:147], v[176:179], v[124:127]
	v_mfma_f32_16x16x32_bf16 v[120:123], v[152:155], v[176:179], v[120:123]
	v_mfma_f32_16x16x32_bf16 v[112:115], v[144:147], v[192:195], v[112:115]
	v_mfma_f32_16x16x32_bf16 v[104:107], v[152:155], v[192:195], v[104:107]
	v_mfma_f32_16x16x32_bf16 v[92:95], v[144:147], v[200:203], v[92:95]
	v_mfma_f32_16x16x32_bf16 v[88:91], v[152:155], v[200:203], v[88:91]
	v_mfma_f32_16x16x32_bf16 v[80:83], v[144:147], v[208:211], v[80:83]
	v_mfma_f32_16x16x32_bf16 v[72:75], v[152:155], v[208:211], v[72:75]
	v_mfma_f32_16x16x32_bf16 v[124:127], v[148:151], v[188:191], v[124:127]
	v_mfma_f32_16x16x32_bf16 v[120:123], v[156:159], v[188:191], v[120:123]
	v_mfma_f32_16x16x32_bf16 v[112:115], v[148:151], v[196:199], v[112:115]
	v_mfma_f32_16x16x32_bf16 v[104:107], v[156:159], v[196:199], v[104:107]
	v_mfma_f32_16x16x32_bf16 v[92:95], v[148:151], v[204:207], v[92:95]
	v_mfma_f32_16x16x32_bf16 v[88:91], v[156:159], v[204:207], v[88:91]
	v_mfma_f32_16x16x32_bf16 v[80:83], v[148:151], v[212:215], v[80:83]
	v_mfma_f32_16x16x32_bf16 v[72:75], v[156:159], v[212:215], v[72:75]
	s_setprio 0
	s_setprio 1
	v_mfma_f32_16x16x32_bf16 v[116:119], v[160:163], v[176:179], v[116:119]
	v_mfma_f32_16x16x32_bf16 v[108:111], v[168:171], v[176:179], v[108:111]
	v_mfma_f32_16x16x32_bf16 v[100:103], v[160:163], v[192:195], v[100:103]
	v_mfma_f32_16x16x32_bf16 v[96:99], v[168:171], v[192:195], v[96:99]
	v_mfma_f32_16x16x32_bf16 v[84:87], v[160:163], v[200:203], v[84:87]
	v_mfma_f32_16x16x32_bf16 v[76:79], v[168:171], v[200:203], v[76:79]
	v_mfma_f32_16x16x32_bf16 v[68:71], v[160:163], v[208:211], v[68:71]
	v_mfma_f32_16x16x32_bf16 v[64:67], v[168:171], v[208:211], v[64:67]
	v_mfma_f32_16x16x32_bf16 v[116:119], v[164:167], v[188:191], v[116:119]
	v_mfma_f32_16x16x32_bf16 v[108:111], v[172:175], v[188:191], v[108:111]
	v_mfma_f32_16x16x32_bf16 v[100:103], v[164:167], v[196:199], v[100:103]
	v_mfma_f32_16x16x32_bf16 v[96:99], v[172:175], v[196:199], v[96:99]
	v_mfma_f32_16x16x32_bf16 v[84:87], v[164:167], v[204:207], v[84:87]
	v_mfma_f32_16x16x32_bf16 v[76:79], v[172:175], v[204:207], v[76:79]
	v_mfma_f32_16x16x32_bf16 v[68:71], v[164:167], v[212:215], v[68:71]
	v_mfma_f32_16x16x32_bf16 v[64:67], v[172:175], v[212:215], v[64:67]
	s_setprio 0
	s_barrier
	s_add_i32 s8, s75, s24
	s_mov_b32 m0, s8
	ds_read_b128 v[176:179], v187 offset:16384
	ds_read_b128 v[188:191], v187 offset:17408
	ds_read_b128 v[192:195], v187 offset:18432
	ds_read_b128 v[196:199], v187 offset:19456
	ds_read_b128 v[200:203], v187 offset:20480
	ds_read_b128 v[204:207], v187 offset:21504
	ds_read_b128 v[208:211], v187 offset:22528
	ds_read_b128 v[212:215], v187 offset:23552
	global_load_lds_dwordx4 v132, s[68:69]
	s_add_i32 m0, s8, 0x2000
	s_add_u32 s8, s68, 0x80000
	s_addc_u32 s9, s69, 0
	s_add_i32 s14, s76, s24
	global_load_lds_dwordx4 v128, s[68:69]
	s_mov_b32 m0, s14
	s_nop 0
	global_load_lds_dwordx4 v132, s[8:9]
	s_add_i32 m0, s14, 0x2000
	s_nop 0
	global_load_lds_dwordx4 v128, s[8:9]
	s_mov_b32 m0, s44
	s_nop 0
	global_load_lds_dwordx4 v134, s[70:71]
	s_mov_b32 m0, s45
	s_nop 0
	global_load_lds_dwordx4 v130, s[70:71]
	s_waitcnt vmcnt(8)
	s_waitcnt lgkmcnt(0)
	s_barrier
	s_setprio 1
	s_waitcnt lgkmcnt(0)
	v_mfma_f32_16x16x32_bf16 v[60:63], v[144:147], v[176:179], v[60:63]
	v_mfma_f32_16x16x32_bf16 v[56:59], v[152:155], v[176:179], v[56:59]
	v_mfma_f32_16x16x32_bf16 v[48:51], v[144:147], v[192:195], v[48:51]
	v_mfma_f32_16x16x32_bf16 v[40:43], v[152:155], v[192:195], v[40:43]
	v_mfma_f32_16x16x32_bf16 v[28:31], v[144:147], v[200:203], v[28:31]
	v_mfma_f32_16x16x32_bf16 v[24:27], v[152:155], v[200:203], v[24:27]
	v_mfma_f32_16x16x32_bf16 v[16:19], v[144:147], v[208:211], v[16:19]
	v_mfma_f32_16x16x32_bf16 v[8:11], v[152:155], v[208:211], v[8:11]
	v_mfma_f32_16x16x32_bf16 v[60:63], v[148:151], v[188:191], v[60:63]
	v_mfma_f32_16x16x32_bf16 v[56:59], v[156:159], v[188:191], v[56:59]
	v_mfma_f32_16x16x32_bf16 v[48:51], v[148:151], v[196:199], v[48:51]
	v_mfma_f32_16x16x32_bf16 v[40:43], v[156:159], v[196:199], v[40:43]
	v_mfma_f32_16x16x32_bf16 v[28:31], v[148:151], v[204:207], v[28:31]
	v_mfma_f32_16x16x32_bf16 v[24:27], v[156:159], v[204:207], v[24:27]
	v_mfma_f32_16x16x32_bf16 v[16:19], v[148:151], v[212:215], v[16:19]
	v_mfma_f32_16x16x32_bf16 v[8:11], v[156:159], v[212:215], v[8:11]
	s_setprio 0
	s_setprio 1
	v_mfma_f32_16x16x32_bf16 v[52:55], v[160:163], v[176:179], v[52:55]
	v_mfma_f32_16x16x32_bf16 v[44:47], v[168:171], v[176:179], v[44:47]
	v_mfma_f32_16x16x32_bf16 v[36:39], v[160:163], v[192:195], v[36:39]
	v_mfma_f32_16x16x32_bf16 v[32:35], v[168:171], v[192:195], v[32:35]
	v_mfma_f32_16x16x32_bf16 v[20:23], v[160:163], v[200:203], v[20:23]
	v_mfma_f32_16x16x32_bf16 v[12:15], v[168:171], v[200:203], v[12:15]
	v_mfma_f32_16x16x32_bf16 v[4:7], v[160:163], v[208:211], v[4:7]
	v_mfma_f32_16x16x32_bf16 v[0:3], v[168:171], v[208:211], v[0:3]
	v_mfma_f32_16x16x32_bf16 v[52:55], v[164:167], v[188:191], v[52:55]
	v_mfma_f32_16x16x32_bf16 v[44:47], v[172:175], v[188:191], v[44:47]
	v_mfma_f32_16x16x32_bf16 v[36:39], v[164:167], v[196:199], v[36:39]
	v_mfma_f32_16x16x32_bf16 v[32:35], v[172:175], v[196:199], v[32:35]
	v_mfma_f32_16x16x32_bf16 v[20:23], v[164:167], v[204:207], v[20:23]
	v_mfma_f32_16x16x32_bf16 v[12:15], v[172:175], v[204:207], v[12:15]
	v_mfma_f32_16x16x32_bf16 v[4:7], v[164:167], v[212:215], v[4:7]
	v_mfma_f32_16x16x32_bf16 v[0:3], v[172:175], v[212:215], v[0:3]
	s_setprio 0
	s_barrier
; #define PG8_STAGE(bufoff, gbase, voff) do { _Pragma("unroll") for (int _i = 0; _i < 2; ++_i) \
;         __builtin_amdgcn_global_load_lds((const unsigned*)((const char*)(gbase) + (voff)[_i]), (LAS unsigned*)(lds + (bufoff) + ldsw + _i * 8192), 16, 0, 0); } while (0)
; #define PG8_LDA(dst, b, h) do { _Pragma("unroll") for (int m = 0; m < 4; ++m) _Pragma("unroll") for (int k = 0; k < 2; ++k) dst[m][k] = *(const LAS bf16x8*)(lds + PG8_SA(b, h) + aoff + m * 2048 + k * 1024); } while (0)
; #define PG8_LDB(dst, b, h) do { _Pragma("unroll") for (int n = 0; n < 2; ++n) _Pragma("unroll") for (int k = 0; k < 2; ++k) dst[n][k] = *(const LAS bf16x8*)(lds + PG8_SB(b, h) + boff + n * 2048 + k * 1024); } while (0)
; #define PG8_WAIT_V(n) asm volatile("s_waitcnt vmcnt(" #n ")" ::: "memory")
; template <int K, int LDA, int LDB, class Epi, class Sched>
; __device__ __forceinline__ void gemm_phase(LAS unsigned char* lds, const Gemm g, const Sched& S, const Epi& E, int wv) {
;     ...
;         for (int t = 0; t < nt; t += 2) {
;             const bool last = (t == nt - 2);
;             const char* a1 = cA + (size_t)(t + 1) * kstep;
;             const char* a2 = last ? nA : cA + (size_t)(t + 2) * kstep; const char* b2 = last ? nB : cB + (size_t)(t + 2) * kstep;
;             const char* a3 = a2 + kstep; const char* b3 = b2 + kstep;
;             PG8_LDB(B0, 0, 0); PG8_LDB(B1, 0, 1); PG8_SCHED; PG8_LDA(At, 0, 0); PG8_STAGE(PG8_SA(1, 1), a1 + hstepA, voffA);
;             PG8_WAIT_V(8); PG8_WAIT_L(0); PG8_BAR; PG8_MMA(0, 0, At, B0); PG8_MMA(0, 1, At, B1); PG8_BAR; PG8_SCHED;
;             PG8_LDA(At, 0, 1); PG8_STAGE(PG8_SB(0, 0), b2, voffB); PG8_STAGE(PG8_SB(0, 1), b2 + hstepB, voffB); PG8_STAGE(PG8_SA(0, 0), a2, voffA);
;             PG8_WAIT_V(8); PG8_WAIT_L(0); PG8_BAR; PG8_MMA(1, 0, At, B0); PG8_MMA(1, 1, At, B1); PG8_BAR; PG8_SCHED;
;             PG8_LDB(B0, 1, 0); PG8_LDB(B1, 1, 1); PG8_SCHED; PG8_LDA(At, 1, 0); PG8_STAGE(PG8_SA(0, 1), a2 + hstepA, voffA);
;             PG8_WAIT_V(8); PG8_WAIT_L(0); PG8_BAR; PG8_MMA(0, 0, At, B0); PG8_MMA(0, 1, At, B1); PG8_BAR; PG8_SCHED;
;             PG8_LDA(At, 1, 1); PG8_STAGE(PG8_SB(1, 0), b3, voffB); PG8_STAGE(PG8_SB(1, 1), b3 + hstepB, voffB); PG8_STAGE(PG8_SA(1, 0), a3, voffA);
;             PG8_WAIT_V(8); PG8_WAIT_L(0); PG8_BAR; PG8_MMA(1, 0, At, B0); PG8_MMA(1, 1, At, B1); PG8_BAR; PG8_SCHED;
	s_add_i32 s14, 0, 0x18000
	v_add_u32_e32 v140, s14, v183
	s_add_i32 s15, 0, 0x1c000
	ds_read_b128 v[144:147], v140
	ds_read_b128 v[148:151], v140 offset:1024
	ds_read_b128 v[152:155], v140 offset:2048
	ds_read_b128 v[156:159], v140 offset:3072
	v_add_u32_e32 v140, s15, v183
	ds_read_b128 v[160:163], v140
	ds_read_b128 v[164:167], v140 offset:1024
	ds_read_b128 v[168:171], v140 offset:2048
	ds_read_b128 v[172:175], v140 offset:3072
	s_add_u32 s8, s70, 0x80000
	s_addc_u32 s9, s71, 0
	s_mov_b32 m0, s55
	ds_read_b128 v[176:179], v187 offset:32768
	ds_read_b128 v[188:191], v187 offset:33792
	ds_read_b128 v[192:195], v187 offset:34816
	ds_read_b128 v[196:199], v187 offset:35840
	ds_read_b128 v[200:203], v187 offset:36864
	ds_read_b128 v[204:207], v187 offset:37888
	ds_read_b128 v[208:211], v187 offset:38912
	ds_read_b128 v[212:215], v187 offset:39936
	global_load_lds_dwordx4 v134, s[8:9]
	s_mov_b32 m0, s65
	s_nop 0
	global_load_lds_dwordx4 v130, s[8:9]
	s_waitcnt vmcnt(8)
	s_waitcnt lgkmcnt(0)
	s_barrier
	s_setprio 1
	s_waitcnt lgkmcnt(0)
	v_mfma_f32_16x16x32_bf16 v[124:127], v[144:147], v[176:179], v[124:127]
	v_mfma_f32_16x16x32_bf16 v[120:123], v[152:155], v[176:179], v[120:123]
	v_mfma_f32_16x16x32_bf16 v[112:115], v[144:147], v[192:195], v[112:115]
	v_mfma_f32_16x16x32_bf16 v[104:107], v[152:155], v[192:195], v[104:107]
	v_mfma_f32_16x16x32_bf16 v[92:95], v[144:147], v[200:203], v[92:95]
	v_mfma_f32_16x16x32_bf16 v[88:91], v[152:155], v[200:203], v[88:91]
	v_mfma_f32_16x16x32_bf16 v[80:83], v[144:147], v[208:211], v[80:83]
	v_mfma_f32_16x16x32_bf16 v[72:75], v[152:155], v[208:211], v[72:75]
	v_mfma_f32_16x16x32_bf16 v[124:127], v[148:151], v[188:191], v[124:127]
	v_mfma_f32_16x16x32_bf16 v[120:123], v[156:159], v[188:191], v[120:123]
	v_mfma_f32_16x16x32_bf16 v[112:115], v[148:151], v[196:199], v[112:115]
	v_mfma_f32_16x16x32_bf16 v[104:107], v[156:159], v[196:199], v[104:107]
	v_mfma_f32_16x16x32_bf16 v[92:95], v[148:151], v[204:207], v[92:95]
	v_mfma_f32_16x16x32_bf16 v[88:91], v[156:159], v[204:207], v[88:91]
	v_mfma_f32_16x16x32_bf16 v[80:83], v[148:151], v[212:215], v[80:83]
	v_mfma_f32_16x16x32_bf16 v[72:75], v[156:159], v[212:215], v[72:75]
	s_setprio 0
	s_setprio 1
	v_mfma_f32_16x16x32_bf16 v[116:119], v[160:163], v[176:179], v[116:119]
	v_mfma_f32_16x16x32_bf16 v[108:111], v[168:171], v[176:179], v[108:111]
	v_mfma_f32_16x16x32_bf16 v[100:103], v[160:163], v[192:195], v[100:103]
	v_mfma_f32_16x16x32_bf16 v[96:99], v[168:171], v[192:195], v[96:99]
	v_mfma_f32_16x16x32_bf16 v[84:87], v[160:163], v[200:203], v[84:87]
	v_mfma_f32_16x16x32_bf16 v[76:79], v[168:171], v[200:203], v[76:79]
	v_mfma_f32_16x16x32_bf16 v[68:71], v[160:163], v[208:211], v[68:71]
	v_mfma_f32_16x16x32_bf16 v[64:67], v[168:171], v[208:211], v[64:67]
	v_mfma_f32_16x16x32_bf16 v[116:119], v[164:167], v[188:191], v[116:119]
	v_mfma_f32_16x16x32_bf16 v[108:111], v[172:175], v[188:191], v[108:111]
	v_mfma_f32_16x16x32_bf16 v[100:103], v[164:167], v[196:199], v[100:103]
	v_mfma_f32_16x16x32_bf16 v[96:99], v[172:175], v[196:199], v[96:99]
	v_mfma_f32_16x16x32_bf16 v[84:87], v[164:167], v[204:207], v[84:87]
	v_mfma_f32_16x16x32_bf16 v[76:79], v[172:175], v[204:207], v[76:79]
	v_mfma_f32_16x16x32_bf16 v[68:71], v[164:167], v[212:215], v[68:71]
	v_mfma_f32_16x16x32_bf16 v[64:67], v[172:175], v[212:215], v[64:67]
	s_setprio 0
	s_barrier
	s_add_i32 s8, s14, s24
	s_mov_b32 m0, s8
	ds_read_b128 v[176:179], v187 offset:49152
	ds_read_b128 v[188:191], v187 offset:50176
	ds_read_b128 v[192:195], v187 offset:51200
	ds_read_b128 v[196:199], v187 offset:52224
	ds_read_b128 v[200:203], v187 offset:53248
	ds_read_b128 v[204:207], v187 offset:54272
	ds_read_b128 v[208:211], v187 offset:55296
	ds_read_b128 v[212:215], v187 offset:56320
	s_add_u32 s98, s68, s52
	s_addc_u32 s99, s69, s53
	global_load_lds_dwordx4 v132, s[98:99]
	s_add_i32 m0, s8, 0x2000
	s_add_u32 s8, s68, 0x80080
	s_addc_u32 s9, s69, 0
	s_add_i32 s14, s15, s24
	global_load_lds_dwordx4 v128, s[98:99]
	s_mov_b32 m0, s14
	s_nop 0
	global_load_lds_dwordx4 v132, s[8:9]
	s_add_i32 m0, s14, 0x2000
	s_nop 0
	global_load_lds_dwordx4 v128, s[8:9]
	s_mov_b32 m0, s73
	s_nop 0
	s_add_u32 s100, s70, s52
	s_addc_u32 s101, s71, s53
	global_load_lds_dwordx4 v134, s[100:101]
	s_mov_b32 m0, s74
	s_nop 0
	global_load_lds_dwordx4 v130, s[100:101]
	s_waitcnt vmcnt(8)
	s_waitcnt lgkmcnt(0)
	s_barrier
	s_setprio 1
	s_waitcnt lgkmcnt(0)
	v_mfma_f32_16x16x32_bf16 v[60:63], v[144:147], v[176:179], v[60:63]
	v_mfma_f32_16x16x32_bf16 v[56:59], v[152:155], v[176:179], v[56:59]
	v_mfma_f32_16x16x32_bf16 v[48:51], v[144:147], v[192:195], v[48:51]
	v_mfma_f32_16x16x32_bf16 v[40:43], v[152:155], v[192:195], v[40:43]
	v_mfma_f32_16x16x32_bf16 v[28:31], v[144:147], v[200:203], v[28:31]
	v_mfma_f32_16x16x32_bf16 v[24:27], v[152:155], v[200:203], v[24:27]
	v_mfma_f32_16x16x32_bf16 v[16:19], v[144:147], v[208:211], v[16:19]
	v_mfma_f32_16x16x32_bf16 v[8:11], v[152:155], v[208:211], v[8:11]
	v_mfma_f32_16x16x32_bf16 v[60:63], v[148:151], v[188:191], v[60:63]
	v_mfma_f32_16x16x32_bf16 v[56:59], v[156:159], v[188:191], v[56:59]
	v_mfma_f32_16x16x32_bf16 v[48:51], v[148:151], v[196:199], v[48:51]
	v_mfma_f32_16x16x32_bf16 v[40:43], v[156:159], v[196:199], v[40:43]
	v_mfma_f32_16x16x32_bf16 v[28:31], v[148:151], v[204:207], v[28:31]
	v_mfma_f32_16x16x32_bf16 v[24:27], v[156:159], v[204:207], v[24:27]
	v_mfma_f32_16x16x32_bf16 v[16:19], v[148:151], v[212:215], v[16:19]
	v_mfma_f32_16x16x32_bf16 v[8:11], v[156:159], v[212:215], v[8:11]
	s_setprio 0
	s_setprio 1
	v_mfma_f32_16x16x32_bf16 v[52:55], v[160:163], v[176:179], v[52:55]
	v_mfma_f32_16x16x32_bf16 v[44:47], v[168:171], v[176:179], v[44:47]
	v_mfma_f32_16x16x32_bf16 v[36:39], v[160:163], v[192:195], v[36:39]
	v_mfma_f32_16x16x32_bf16 v[32:35], v[168:171], v[192:195], v[32:35]
	v_mfma_f32_16x16x32_bf16 v[20:23], v[160:163], v[200:203], v[20:23]
	v_mfma_f32_16x16x32_bf16 v[12:15], v[168:171], v[200:203], v[12:15]
	v_mfma_f32_16x16x32_bf16 v[4:7], v[160:163], v[208:211], v[4:7]
	v_mfma_f32_16x16x32_bf16 v[0:3], v[168:171], v[208:211], v[0:3]
	v_mfma_f32_16x16x32_bf16 v[52:55], v[164:167], v[188:191], v[52:55]
	v_mfma_f32_16x16x32_bf16 v[44:47], v[172:175], v[188:191], v[44:47]
	v_mfma_f32_16x16x32_bf16 v[36:39], v[164:167], v[196:199], v[36:39]
	v_mfma_f32_16x16x32_bf16 v[32:35], v[172:175], v[196:199], v[32:35]
	v_mfma_f32_16x16x32_bf16 v[20:23], v[164:167], v[204:207], v[20:23]
	v_mfma_f32_16x16x32_bf16 v[12:15], v[172:175], v[204:207], v[12:15]
	v_mfma_f32_16x16x32_bf16 v[4:7], v[164:167], v[212:215], v[4:7]
	v_mfma_f32_16x16x32_bf16 v[0:3], v[172:175], v[212:215], v[0:3]
	s_setprio 0
	s_barrier
	s_add_i32 s82, s82, 2
	s_add_u32 s66, s66, 0x100
	s_addc_u32 s67, s67, 0
	s_add_u32 s80, s80, 0x100
	s_addc_u32 s81, s81, 0
	s_cmp_gt_u32 s82, 29
	s_cbranch_scc0 .LBB0_700
	s_and_b64 vcc, exec, s[28:29]
	s_cbranch_vccz .LBB0_703
	s_barrier

; #define PG8_STAGE(bufoff, gbase, voff) do { _Pragma("unroll") for (int _i = 0; _i < 2; ++_i) \
;         __builtin_amdgcn_global_load_lds((const unsigned*)((const char*)(gbase) + (voff)[_i]), (LAS unsigned*)(lds + (bufoff) + ldsw + _i * 8192), 16, 0, 0); } while (0)
; #define PG8_LDA(dst, b, h) do { _Pragma("unroll") for (int m = 0; m < 4; ++m) _Pragma("unroll") for (int k = 0; k < 2; ++k) dst[m][k] = *(const LAS bf16x8*)(lds + PG8_SA(b, h) + aoff + m * 2048 + k * 1024); } while (0)
; #define PG8_LDB(dst, b, h) do { _Pragma("unroll") for (int n = 0; n < 2; ++n) _Pragma("unroll") for (int k = 0; k < 2; ++k) dst[n][k] = *(const LAS bf16x8*)(lds + PG8_SB(b, h) + boff + n * 2048 + k * 1024); } while (0)
; #define PG8_WAIT_V(n) asm volatile("s_waitcnt vmcnt(" #n ")" ::: "memory")
; template <int K, int LDA, int LDB, class Epi, class Sched>
; __device__ __forceinline__ void gemm_phase(LAS unsigned char* lds, const Gemm g, const Sched& S, const Epi& E, int wv) {
;     ...
;         for (int t = 0; t < nt; t += 2) {
;             const bool last = (t == nt - 2);
;             const char* a1 = cA + (size_t)(t + 1) * kstep;
;             const char* a2 = last ? nA : cA + (size_t)(t + 2) * kstep; const char* b2 = last ? nB : cB + (size_t)(t + 2) * kstep;
;             const char* a3 = a2 + kstep; const char* b3 = b2 + kstep;
;             PG8_LDB(B0, 0, 0); PG8_LDB(B1, 0, 1); PG8_SCHED; PG8_LDA(At, 0, 0); PG8_STAGE(PG8_SA(1, 1), a1 + hstepA, voffA);
;             PG8_WAIT_V(8); PG8_WAIT_L(0); PG8_BAR; PG8_MMA(0, 0, At, B0); PG8_MMA(0, 1, At, B1); PG8_BAR; PG8_SCHED;
;             PG8_LDA(At, 0, 1); PG8_STAGE(PG8_SB(0, 0), b2, voffB); PG8_STAGE(PG8_SB(0, 1), b2 + hstepB, voffB); PG8_STAGE(PG8_SA(0, 0), a2, voffA);
;             PG8_WAIT_V(8); PG8_WAIT_L(0); PG8_BAR; PG8_MMA(1, 0, At, B0); PG8_MMA(1, 1, At, B1); PG8_BAR; PG8_SCHED;
;             PG8_LDB(B0, 1, 0); PG8_LDB(B1, 1, 1); PG8_SCHED; PG8_LDA(At, 1, 0); PG8_STAGE(PG8_SA(0, 1), a2 + hstepA, voffA);
;             PG8_WAIT_V(8); PG8_WAIT_L(0); PG8_BAR; PG8_MMA(0, 0, At, B0); PG8_MMA(0, 1, At, B1); PG8_BAR; PG8_SCHED;
;             PG8_LDA(At, 1, 1); PG8_STAGE(PG8_SB(1, 0), b3, voffB); PG8_STAGE(PG8_SB(1, 1), b3 + hstepB, voffB); PG8_STAGE(PG8_SA(1, 0), a3, voffA);
;             PG8_WAIT_V(8); PG8_WAIT_L(0); PG8_BAR; PG8_MMA(1, 0, At, B0); PG8_MMA(1, 1, At, B1); PG8_BAR; PG8_SCHED;
.LBB0_838:
	s_waitcnt lgkmcnt(0)
	ds_read_b128 v[152:155], v163
	ds_read_b128 v[156:159], v163 offset:1024
	ds_read_b128 v[166:169], v163 offset:2048
	ds_read_b128 v[170:173], v163 offset:3072
	ds_read_b128 v[174:177], v164
	ds_read_b128 v[178:181], v164 offset:1024
	ds_read_b128 v[182:185], v164 offset:2048
	ds_read_b128 v[186:189], v164 offset:3072
	s_add_u32 s9, s92, 0xfff80080
	s_addc_u32 s34, s93, -1
	s_cmp_eq_u32 s8, 28
	s_cselect_b32 s97, s45, s34
	s_cselect_b32 s96, s62, s9
	s_cselect_b32 s95, s81, vcc_hi
	s_cselect_b32 s94, s83, vcc_lo
	s_add_i32 m0, s71, 0xc000
	ds_read_b128 v[190:193], v165
	ds_read_b128 v[194:197], v165 offset:1024
	ds_read_b128 v[198:201], v165 offset:2048
	ds_read_b128 v[202:205], v165 offset:3072
	ds_read_b128 v[206:209], v165 offset:4096
	ds_read_b128 v[210:213], v165 offset:5120
	ds_read_b128 v[214:217], v165 offset:6144
	ds_read_b128 v[218:221], v165 offset:7168
	global_load_lds_dwordx4 v144, s[92:93]
	s_add_i32 m0, s71, 0xe000
	s_nop 0
	global_load_lds_dwordx4 v146, s[92:93]
	s_waitcnt vmcnt(8)
	s_waitcnt lgkmcnt(0)
	s_barrier
	s_setprio 1
	s_waitcnt lgkmcnt(0)
	v_mfma_f32_16x16x32_bf16 v[64:67], v[152:155], v[190:193], v[64:67]
	v_mfma_f32_16x16x32_bf16 v[60:63], v[166:169], v[190:193], v[60:63]
	v_mfma_f32_16x16x32_bf16 v[56:59], v[152:155], v[198:201], v[56:59]
	v_mfma_f32_16x16x32_bf16 v[48:51], v[166:169], v[198:201], v[48:51]
	v_mfma_f32_16x16x32_bf16 v[44:47], v[152:155], v[206:209], v[44:47]
	v_mfma_f32_16x16x32_bf16 v[40:43], v[166:169], v[206:209], v[40:43]
	v_mfma_f32_16x16x32_bf16 v[36:39], v[152:155], v[214:217], v[36:39]
	v_mfma_f32_16x16x32_bf16 v[32:35], v[166:169], v[214:217], v[32:35]
	v_mfma_f32_16x16x32_bf16 v[64:67], v[156:159], v[194:197], v[64:67]
	v_mfma_f32_16x16x32_bf16 v[60:63], v[170:173], v[194:197], v[60:63]
	v_mfma_f32_16x16x32_bf16 v[56:59], v[156:159], v[202:205], v[56:59]
	v_mfma_f32_16x16x32_bf16 v[48:51], v[170:173], v[202:205], v[48:51]
	v_mfma_f32_16x16x32_bf16 v[44:47], v[156:159], v[210:213], v[44:47]
	v_mfma_f32_16x16x32_bf16 v[40:43], v[170:173], v[210:213], v[40:43]
	v_mfma_f32_16x16x32_bf16 v[36:39], v[156:159], v[218:221], v[36:39]
	v_mfma_f32_16x16x32_bf16 v[32:35], v[170:173], v[218:221], v[32:35]
	s_setprio 0
	s_setprio 1
	v_mfma_f32_16x16x32_bf16 v[124:127], v[174:177], v[190:193], v[124:127]
	v_mfma_f32_16x16x32_bf16 v[120:123], v[182:185], v[190:193], v[120:123]
	v_mfma_f32_16x16x32_bf16 v[116:119], v[174:177], v[198:201], v[116:119]
	v_mfma_f32_16x16x32_bf16 v[112:115], v[182:185], v[198:201], v[112:115]
	v_mfma_f32_16x16x32_bf16 v[108:111], v[174:177], v[206:209], v[108:111]
	v_mfma_f32_16x16x32_bf16 v[104:107], v[182:185], v[206:209], v[104:107]
	v_mfma_f32_16x16x32_bf16 v[100:103], v[174:177], v[214:217], v[100:103]
	v_mfma_f32_16x16x32_bf16 v[96:99], v[182:185], v[214:217], v[96:99]
	v_mfma_f32_16x16x32_bf16 v[124:127], v[178:181], v[194:197], v[124:127]
	v_mfma_f32_16x16x32_bf16 v[120:123], v[186:189], v[194:197], v[120:123]
	v_mfma_f32_16x16x32_bf16 v[116:119], v[178:181], v[202:205], v[116:119]
	v_mfma_f32_16x16x32_bf16 v[112:115], v[186:189], v[202:205], v[112:115]
	v_mfma_f32_16x16x32_bf16 v[108:111], v[178:181], v[210:213], v[108:111]
	v_mfma_f32_16x16x32_bf16 v[104:107], v[186:189], v[210:213], v[104:107]
	v_mfma_f32_16x16x32_bf16 v[100:103], v[178:181], v[218:221], v[100:103]
	v_mfma_f32_16x16x32_bf16 v[96:99], v[186:189], v[218:221], v[96:99]
	s_setprio 0
	s_barrier
	s_add_i32 s9, s91, s24
	s_mov_b32 m0, s9
	ds_read_b128 v[190:193], v165 offset:16384
	ds_read_b128 v[194:197], v165 offset:17408
	ds_read_b128 v[198:201], v165 offset:18432
	ds_read_b128 v[202:205], v165 offset:19456
	ds_read_b128 v[206:209], v165 offset:20480
	ds_read_b128 v[210:213], v165 offset:21504
	ds_read_b128 v[214:217], v165 offset:22528
	ds_read_b128 v[218:221], v165 offset:23552
	global_load_lds_dwordx4 v130, s[94:95]
	s_add_i32 m0, s9, 0x2000
	s_add_u32 s34, s94, 0x80000
	s_addc_u32 s35, s95, 0
	s_add_i32 s9, s42, s24
	global_load_lds_dwordx4 v134, s[94:95]
	s_mov_b32 m0, s9
	s_nop 0
	global_load_lds_dwordx4 v130, s[34:35]
	s_add_i32 m0, s9, 0x2000
	s_nop 0
	global_load_lds_dwordx4 v134, s[34:35]
	s_mov_b32 m0, s71
	s_nop 0
	global_load_lds_dwordx4 v128, s[96:97]
	s_mov_b32 m0, s73
	s_nop 0
	global_load_lds_dwordx4 v132, s[96:97]
	s_waitcnt vmcnt(8)
	s_waitcnt lgkmcnt(0)
	s_barrier
	s_setprio 1
	s_waitcnt lgkmcnt(0)
	v_mfma_f32_16x16x32_bf16 v[28:31], v[152:155], v[190:193], v[28:31]
	v_mfma_f32_16x16x32_bf16 v[24:27], v[166:169], v[190:193], v[24:27]
	v_mfma_f32_16x16x32_bf16 v[20:23], v[152:155], v[198:201], v[20:23]
	v_mfma_f32_16x16x32_bf16 v[16:19], v[166:169], v[198:201], v[16:19]
	v_mfma_f32_16x16x32_bf16 v[12:15], v[152:155], v[206:209], v[12:15]
	v_mfma_f32_16x16x32_bf16 v[8:11], v[166:169], v[206:209], v[8:11]
	v_mfma_f32_16x16x32_bf16 v[4:7], v[152:155], v[214:217], v[4:7]
	v_mfma_f32_16x16x32_bf16 v[0:3], v[166:169], v[214:217], v[0:3]
	v_mfma_f32_16x16x32_bf16 v[28:31], v[156:159], v[194:197], v[28:31]
	v_mfma_f32_16x16x32_bf16 v[24:27], v[170:173], v[194:197], v[24:27]
	v_mfma_f32_16x16x32_bf16 v[20:23], v[156:159], v[202:205], v[20:23]
	v_mfma_f32_16x16x32_bf16 v[16:19], v[170:173], v[202:205], v[16:19]
	v_mfma_f32_16x16x32_bf16 v[12:15], v[156:159], v[210:213], v[12:15]
	v_mfma_f32_16x16x32_bf16 v[8:11], v[170:173], v[210:213], v[8:11]
	v_mfma_f32_16x16x32_bf16 v[4:7], v[156:159], v[218:221], v[4:7]
	v_mfma_f32_16x16x32_bf16 v[0:3], v[170:173], v[218:221], v[0:3]
	s_setprio 0
	s_setprio 1
	v_mfma_f32_16x16x32_bf16 v[92:95], v[174:177], v[190:193], v[92:95]
	v_mfma_f32_16x16x32_bf16 v[88:91], v[182:185], v[190:193], v[88:91]
	v_mfma_f32_16x16x32_bf16 v[84:87], v[174:177], v[198:201], v[84:87]
	v_mfma_f32_16x16x32_bf16 v[80:83], v[182:185], v[198:201], v[80:83]
	v_mfma_f32_16x16x32_bf16 v[76:79], v[174:177], v[206:209], v[76:79]
	v_mfma_f32_16x16x32_bf16 v[72:75], v[182:185], v[206:209], v[72:75]
	v_mfma_f32_16x16x32_bf16 v[68:71], v[174:177], v[214:217], v[68:71]
	v_mfma_f32_16x16x32_bf16 v[52:55], v[182:185], v[214:217], v[52:55]
	v_mfma_f32_16x16x32_bf16 v[92:95], v[178:181], v[194:197], v[92:95]
	v_mfma_f32_16x16x32_bf16 v[88:91], v[186:189], v[194:197], v[88:91]
	v_mfma_f32_16x16x32_bf16 v[84:87], v[178:181], v[202:205], v[84:87]
	v_mfma_f32_16x16x32_bf16 v[80:83], v[186:189], v[202:205], v[80:83]
	v_mfma_f32_16x16x32_bf16 v[76:79], v[178:181], v[210:213], v[76:79]
	v_mfma_f32_16x16x32_bf16 v[72:75], v[186:189], v[210:213], v[72:75]
	v_mfma_f32_16x16x32_bf16 v[68:71], v[178:181], v[218:221], v[68:71]
	v_mfma_f32_16x16x32_bf16 v[52:55], v[186:189], v[218:221], v[52:55]
	s_setprio 0
	s_barrier
; #define PG8_STAGE(bufoff, gbase, voff) do { _Pragma("unroll") for (int _i = 0; _i < 2; ++_i) \
;         __builtin_amdgcn_global_load_lds((const unsigned*)((const char*)(gbase) + (voff)[_i]), (LAS unsigned*)(lds + (bufoff) + ldsw + _i * 8192), 16, 0, 0); } while (0)
; #define PG8_LDA(dst, b, h) do { _Pragma("unroll") for (int m = 0; m < 4; ++m) _Pragma("unroll") for (int k = 0; k < 2; ++k) dst[m][k] = *(const LAS bf16x8*)(lds + PG8_SA(b, h) + aoff + m * 2048 + k * 1024); } while (0)
; #define PG8_LDB(dst, b, h) do { _Pragma("unroll") for (int n = 0; n < 2; ++n) _Pragma("unroll") for (int k = 0; k < 2; ++k) dst[n][k] = *(const LAS bf16x8*)(lds + PG8_SB(b, h) + boff + n * 2048 + k * 1024); } while (0)
; #define PG8_MMA(ai, bj, At, Bt) do { __builtin_amdgcn_s_setprio(1); _Pragma("unroll") for (int m = 0; m < 4; ++m) _Pragma("unroll") for (int n = 0; n < 2; ++n) _Pragma("unroll") for (int k = 0; k < 2; ++k) \
;         acc[ai][bj][m][n] = __builtin_amdgcn_mfma_f32_16x16x32_bf16(Bt[n][k], At[m][k], acc[ai][bj][m][n], 0, 0, 0); __builtin_amdgcn_s_setprio(0); } while (0)
; #define PG8_WAIT_V(n) asm volatile("s_waitcnt vmcnt(" #n ")" ::: "memory")
; #define PG8_WAIT_L(n) asm volatile("s_waitcnt lgkmcnt(" #n ")" ::: "memory")
; #define PG8_BAR __builtin_amdgcn_s_barrier()
; #define PG8_SCHED __builtin_amdgcn_sched_barrier(0)
; template <int K, int LDA, int LDB, class Epi, class Sched>
; __device__ __forceinline__ void gemm_phase(LAS unsigned char* lds, const Gemm g, const Sched& S, const Epi& E, int wv) {
;     ...
;             PG8_LDB(B0, 1, 0); PG8_LDB(B1, 1, 1); PG8_SCHED; PG8_LDA(At, 1, 0); PG8_STAGE(PG8_SA(0, 1), a2 + hstepA, voffA);
;             PG8_WAIT_V(8); PG8_WAIT_L(0); PG8_BAR; PG8_MMA(0, 0, At, B0); PG8_MMA(0, 1, At, B1); PG8_BAR; PG8_SCHED;
;             PG8_LDA(At, 1, 1); PG8_STAGE(PG8_SB(1, 0), b3, voffB); PG8_STAGE(PG8_SB(1, 1), b3 + hstepB, voffB); PG8_STAGE(PG8_SA(1, 0), a3, voffA);
;             PG8_WAIT_V(8); PG8_WAIT_L(0); PG8_BAR; PG8_MMA(1, 0, At, B0); PG8_MMA(1, 1, At, B1); PG8_BAR; PG8_SCHED;
;         }
;         if (wr == 0) PG8_BAR;
	s_add_i32 s9, 0, 0x18000
	v_add_u32_e32 v136, s9, v161
	s_add_i32 s10, 0, 0x1c000
	ds_read_b128 v[152:155], v136
	ds_read_b128 v[156:159], v136 offset:1024
	ds_read_b128 v[166:169], v136 offset:2048
	ds_read_b128 v[170:173], v136 offset:3072
	v_add_u32_e32 v136, s10, v161
	ds_read_b128 v[174:177], v136
	ds_read_b128 v[178:181], v136 offset:1024
	ds_read_b128 v[182:185], v136 offset:2048
	ds_read_b128 v[186:189], v136 offset:3072
	s_add_u32 s34, s96, 0x80000
	s_addc_u32 s35, s97, 0
	s_mov_b32 m0, s75
	ds_read_b128 v[190:193], v165 offset:32768
	ds_read_b128 v[194:197], v165 offset:33792
	ds_read_b128 v[198:201], v165 offset:34816
	ds_read_b128 v[202:205], v165 offset:35840
	ds_read_b128 v[206:209], v165 offset:36864
	ds_read_b128 v[210:213], v165 offset:37888
	ds_read_b128 v[214:217], v165 offset:38912
	ds_read_b128 v[218:221], v165 offset:39936
	global_load_lds_dwordx4 v128, s[34:35]
	s_mov_b32 m0, s77
	s_nop 0
	global_load_lds_dwordx4 v132, s[34:35]
	s_waitcnt vmcnt(8)
	s_waitcnt lgkmcnt(0)
	s_barrier
	s_setprio 1
	s_waitcnt lgkmcnt(0)
	v_mfma_f32_16x16x32_bf16 v[64:67], v[152:155], v[190:193], v[64:67]
	v_mfma_f32_16x16x32_bf16 v[60:63], v[166:169], v[190:193], v[60:63]
	v_mfma_f32_16x16x32_bf16 v[56:59], v[152:155], v[198:201], v[56:59]
	v_mfma_f32_16x16x32_bf16 v[48:51], v[166:169], v[198:201], v[48:51]
	v_mfma_f32_16x16x32_bf16 v[44:47], v[152:155], v[206:209], v[44:47]
	v_mfma_f32_16x16x32_bf16 v[40:43], v[166:169], v[206:209], v[40:43]
	v_mfma_f32_16x16x32_bf16 v[36:39], v[152:155], v[214:217], v[36:39]
	v_mfma_f32_16x16x32_bf16 v[32:35], v[166:169], v[214:217], v[32:35]
	v_mfma_f32_16x16x32_bf16 v[64:67], v[156:159], v[194:197], v[64:67]
	v_mfma_f32_16x16x32_bf16 v[60:63], v[170:173], v[194:197], v[60:63]
	v_mfma_f32_16x16x32_bf16 v[56:59], v[156:159], v[202:205], v[56:59]
	v_mfma_f32_16x16x32_bf16 v[48:51], v[170:173], v[202:205], v[48:51]
	v_mfma_f32_16x16x32_bf16 v[44:47], v[156:159], v[210:213], v[44:47]
	v_mfma_f32_16x16x32_bf16 v[40:43], v[170:173], v[210:213], v[40:43]
	v_mfma_f32_16x16x32_bf16 v[36:39], v[156:159], v[218:221], v[36:39]
	v_mfma_f32_16x16x32_bf16 v[32:35], v[170:173], v[218:221], v[32:35]
	s_setprio 0
	s_setprio 1
	v_mfma_f32_16x16x32_bf16 v[124:127], v[174:177], v[190:193], v[124:127]
	v_mfma_f32_16x16x32_bf16 v[120:123], v[182:185], v[190:193], v[120:123]
	v_mfma_f32_16x16x32_bf16 v[116:119], v[174:177], v[198:201], v[116:119]
	v_mfma_f32_16x16x32_bf16 v[112:115], v[182:185], v[198:201], v[112:115]
	v_mfma_f32_16x16x32_bf16 v[108:111], v[174:177], v[206:209], v[108:111]
	v_mfma_f32_16x16x32_bf16 v[104:107], v[182:185], v[206:209], v[104:107]
	v_mfma_f32_16x16x32_bf16 v[100:103], v[174:177], v[214:217], v[100:103]
	v_mfma_f32_16x16x32_bf16 v[96:99], v[182:185], v[214:217], v[96:99]
	v_mfma_f32_16x16x32_bf16 v[124:127], v[178:181], v[194:197], v[124:127]
	v_mfma_f32_16x16x32_bf16 v[120:123], v[186:189], v[194:197], v[120:123]
	v_mfma_f32_16x16x32_bf16 v[116:119], v[178:181], v[202:205], v[116:119]
	v_mfma_f32_16x16x32_bf16 v[112:115], v[186:189], v[202:205], v[112:115]
	v_mfma_f32_16x16x32_bf16 v[108:111], v[178:181], v[210:213], v[108:111]
	v_mfma_f32_16x16x32_bf16 v[104:107], v[186:189], v[210:213], v[104:107]
	v_mfma_f32_16x16x32_bf16 v[100:103], v[178:181], v[218:221], v[100:103]
	v_mfma_f32_16x16x32_bf16 v[96:99], v[186:189], v[218:221], v[96:99]
	s_setprio 0
	s_barrier
	s_add_i32 s9, s9, s24
	s_mov_b32 m0, s9
	ds_read_b128 v[190:193], v165 offset:49152
	ds_read_b128 v[194:197], v165 offset:50176
	ds_read_b128 v[198:201], v165 offset:51200
	ds_read_b128 v[202:205], v165 offset:52224
	ds_read_b128 v[206:209], v165 offset:53248
	ds_read_b128 v[210:213], v165 offset:54272
	ds_read_b128 v[214:217], v165 offset:55296
	ds_read_b128 v[218:221], v165 offset:56320
	s_add_u32 s98, s94, s64
	s_addc_u32 s99, s95, s65
	global_load_lds_dwordx4 v130, s[98:99]
	s_add_i32 m0, s9, 0x2000
	s_add_u32 s34, s94, 0x80080
	s_addc_u32 s35, s95, 0
	s_add_i32 s9, s10, s24
	global_load_lds_dwordx4 v134, s[98:99]
	s_mov_b32 m0, s9
	s_nop 0
	global_load_lds_dwordx4 v130, s[34:35]
	s_add_i32 m0, s9, 0x2000
	s_nop 0
	global_load_lds_dwordx4 v134, s[34:35]
	s_mov_b32 m0, s79
	s_nop 0
	s_add_u32 s100, s96, s64
	s_addc_u32 s101, s97, s65
	global_load_lds_dwordx4 v128, s[100:101]
	s_mov_b32 m0, s89
	s_nop 0
	global_load_lds_dwordx4 v132, s[100:101]
	s_waitcnt vmcnt(8)
	s_waitcnt lgkmcnt(0)
	s_barrier
	s_setprio 1
	s_waitcnt lgkmcnt(0)
	v_mfma_f32_16x16x32_bf16 v[28:31], v[152:155], v[190:193], v[28:31]
	v_mfma_f32_16x16x32_bf16 v[24:27], v[166:169], v[190:193], v[24:27]
	v_mfma_f32_16x16x32_bf16 v[20:23], v[152:155], v[198:201], v[20:23]
	v_mfma_f32_16x16x32_bf16 v[16:19], v[166:169], v[198:201], v[16:19]
	v_mfma_f32_16x16x32_bf16 v[12:15], v[152:155], v[206:209], v[12:15]
	v_mfma_f32_16x16x32_bf16 v[8:11], v[166:169], v[206:209], v[8:11]
	v_mfma_f32_16x16x32_bf16 v[4:7], v[152:155], v[214:217], v[4:7]
	v_mfma_f32_16x16x32_bf16 v[0:3], v[166:169], v[214:217], v[0:3]
	v_mfma_f32_16x16x32_bf16 v[28:31], v[156:159], v[194:197], v[28:31]
	v_mfma_f32_16x16x32_bf16 v[24:27], v[170:173], v[194:197], v[24:27]
	v_mfma_f32_16x16x32_bf16 v[20:23], v[156:159], v[202:205], v[20:23]
	v_mfma_f32_16x16x32_bf16 v[16:19], v[170:173], v[202:205], v[16:19]
	v_mfma_f32_16x16x32_bf16 v[12:15], v[156:159], v[210:213], v[12:15]
	v_mfma_f32_16x16x32_bf16 v[8:11], v[170:173], v[210:213], v[8:11]
	v_mfma_f32_16x16x32_bf16 v[4:7], v[156:159], v[218:221], v[4:7]
	v_mfma_f32_16x16x32_bf16 v[0:3], v[170:173], v[218:221], v[0:3]
	s_setprio 0
	s_setprio 1
	v_mfma_f32_16x16x32_bf16 v[92:95], v[174:177], v[190:193], v[92:95]
	v_mfma_f32_16x16x32_bf16 v[88:91], v[182:185], v[190:193], v[88:91]
	v_mfma_f32_16x16x32_bf16 v[84:87], v[174:177], v[198:201], v[84:87]
	v_mfma_f32_16x16x32_bf16 v[80:83], v[182:185], v[198:201], v[80:83]
	v_mfma_f32_16x16x32_bf16 v[76:79], v[174:177], v[206:209], v[76:79]
	v_mfma_f32_16x16x32_bf16 v[72:75], v[182:185], v[206:209], v[72:75]
	v_mfma_f32_16x16x32_bf16 v[68:71], v[174:177], v[214:217], v[68:71]
	v_mfma_f32_16x16x32_bf16 v[52:55], v[182:185], v[214:217], v[52:55]
	v_mfma_f32_16x16x32_bf16 v[92:95], v[178:181], v[194:197], v[92:95]
	v_mfma_f32_16x16x32_bf16 v[88:91], v[186:189], v[194:197], v[88:91]
	v_mfma_f32_16x16x32_bf16 v[84:87], v[178:181], v[202:205], v[84:87]
	v_mfma_f32_16x16x32_bf16 v[80:83], v[186:189], v[202:205], v[80:83]
	v_mfma_f32_16x16x32_bf16 v[76:79], v[178:181], v[210:213], v[76:79]
	v_mfma_f32_16x16x32_bf16 v[72:75], v[186:189], v[210:213], v[72:75]
	v_mfma_f32_16x16x32_bf16 v[68:71], v[178:181], v[218:221], v[68:71]
	v_mfma_f32_16x16x32_bf16 v[52:55], v[186:189], v[218:221], v[52:55]
	s_setprio 0
	s_barrier
	s_add_i32 s8, s8, 2
	s_add_u32 s92, s92, 0x100
	s_addc_u32 s93, s93, 0
	s_add_u32 vcc_lo, vcc_lo, 0x100
	s_addc_u32 vcc_hi, vcc_hi, 0
	s_cmp_gt_u32 s8, 29
	s_cbranch_scc0 .LBB0_838
	s_and_b64 vcc, exec, s[28:29]
	s_cbranch_vccz .LBB0_841
	s_barrier

; #define PG8_STAGE(bufoff, gbase, voff) do { _Pragma("unroll") for (int _i = 0; _i < 2; ++_i) \
;         __builtin_amdgcn_global_load_lds((const unsigned*)((const char*)(gbase) + (voff)[_i]), (LAS unsigned*)(lds + (bufoff) + ldsw + _i * 8192), 16, 0, 0); } while (0)
; #define PG8_LDA(dst, b, h) do { _Pragma("unroll") for (int m = 0; m < 4; ++m) _Pragma("unroll") for (int k = 0; k < 2; ++k) dst[m][k] = *(const LAS bf16x8*)(lds + PG8_SA(b, h) + aoff + m * 2048 + k * 1024); } while (0)
; #define PG8_LDB(dst, b, h) do { _Pragma("unroll") for (int n = 0; n < 2; ++n) _Pragma("unroll") for (int k = 0; k < 2; ++k) dst[n][k] = *(const LAS bf16x8*)(lds + PG8_SB(b, h) + boff + n * 2048 + k * 1024); } while (0)
; #define PG8_MMA(ai, bj, At, Bt) do { __builtin_amdgcn_s_setprio(1); _Pragma("unroll") for (int m = 0; m < 4; ++m) _Pragma("unroll") for (int n = 0; n < 2; ++n) _Pragma("unroll") for (int k = 0; k < 2; ++k) \
;         acc[ai][bj][m][n] = __builtin_amdgcn_mfma_f32_16x16x32_bf16(Bt[n][k], At[m][k], acc[ai][bj][m][n], 0, 0, 0); __builtin_amdgcn_s_setprio(0); } while (0)
; #define PG8_WAIT_V(n) asm volatile("s_waitcnt vmcnt(" #n ")" ::: "memory")
; #define PG8_WAIT_L(n) asm volatile("s_waitcnt lgkmcnt(" #n ")" ::: "memory")
; #define PG8_BAR __builtin_amdgcn_s_barrier()
; #define PG8_SCHED __builtin_amdgcn_sched_barrier(0)
; template <int K, int LDA, int LDB, class Epi, class Sched>
; __device__ __forceinline__ void gemm_phase(LAS unsigned char* lds, const Gemm g, const Sched& S, const Epi& E, int wv) {
;     ...
;         for (int t = 0; t < nt; t += 2) {
;             const bool last = (t == nt - 2);
;             const char* a1 = cA + (size_t)(t + 1) * kstep;
;             const char* a2 = last ? nA : cA + (size_t)(t + 2) * kstep; const char* b2 = last ? nB : cB + (size_t)(t + 2) * kstep;
;             const char* a3 = a2 + kstep; const char* b3 = b2 + kstep;
;             PG8_LDB(B0, 0, 0); PG8_LDB(B1, 0, 1); PG8_SCHED; PG8_LDA(At, 0, 0); PG8_STAGE(PG8_SA(1, 1), a1 + hstepA, voffA);
;             PG8_WAIT_V(8); PG8_WAIT_L(0); PG8_BAR; PG8_MMA(0, 0, At, B0); PG8_MMA(0, 1, At, B1); PG8_BAR; PG8_SCHED;
;             PG8_LDA(At, 0, 1); PG8_STAGE(PG8_SB(0, 0), b2, voffB); PG8_STAGE(PG8_SB(0, 1), b2 + hstepB, voffB); PG8_STAGE(PG8_SA(0, 0), a2, voffA);
;             PG8_WAIT_V(8); PG8_WAIT_L(0); PG8_BAR; PG8_MMA(1, 0, At, B0); PG8_MMA(1, 1, At, B1); PG8_BAR; PG8_SCHED;
.LBB0_1030:
	ds_read_b128 v[128:131], v201
	ds_read_b128 v[132:135], v201 offset:1024
	ds_read_b128 v[136:139], v201 offset:2048
	ds_read_b128 v[140:143], v201 offset:3072
	ds_read_b128 v[144:147], v205
	ds_read_b128 v[148:151], v205 offset:1024
	ds_read_b128 v[152:155], v205 offset:2048
	ds_read_b128 v[156:159], v205 offset:3072
	s_add_u32 s8, s42, 0x100
	s_addc_u32 s9, s43, 0
	s_cmp_eq_u32 s77, 4
	s_cselect_b32 s59, s37, s9
	s_cselect_b32 s58, s36, s8
	s_cselect_b32 s57, s35, s76
	s_cselect_b32 s56, s41, s75
	s_add_i32 m0, s45, 0xc000
	ds_read_b128 v[186:189], v209
	ds_read_b128 v[194:197], v209 offset:1024
	ds_read_b128 v[214:217], v209 offset:2048
	ds_read_b128 v[218:221], v209 offset:3072
	ds_read_b128 v[224:227], v209 offset:4096
	ds_read_b128 v[228:231], v209 offset:5120
	ds_read_b128 v[232:235], v209 offset:6144
	ds_read_b128 v[236:239], v209 offset:7168
	global_load_lds_dwordx4 v170, s[42:43]
	s_add_i32 m0, s45, 0xe000
	s_nop 0
	global_load_lds_dwordx4 v172, s[42:43]
	s_waitcnt vmcnt(8)
	s_waitcnt lgkmcnt(0)
	s_barrier
	s_setprio 1
	s_waitcnt lgkmcnt(0)
	v_mfma_f32_16x16x32_bf16 v[124:127], v[128:131], v[186:189], v[124:127]
	v_mfma_f32_16x16x32_bf16 v[120:123], v[136:139], v[186:189], v[120:123]
	v_mfma_f32_16x16x32_bf16 v[108:111], v[128:131], v[214:217], v[108:111]
	v_mfma_f32_16x16x32_bf16 v[104:107], v[136:139], v[214:217], v[104:107]
	v_mfma_f32_16x16x32_bf16 v[92:95], v[128:131], v[224:227], v[92:95]
	v_mfma_f32_16x16x32_bf16 v[88:91], v[136:139], v[224:227], v[88:91]
	v_mfma_f32_16x16x32_bf16 v[76:79], v[128:131], v[232:235], v[76:79]
	v_mfma_f32_16x16x32_bf16 v[72:75], v[136:139], v[232:235], v[72:75]
	v_mfma_f32_16x16x32_bf16 v[124:127], v[132:135], v[194:197], v[124:127]
	v_mfma_f32_16x16x32_bf16 v[120:123], v[140:143], v[194:197], v[120:123]
	v_mfma_f32_16x16x32_bf16 v[108:111], v[132:135], v[218:221], v[108:111]
	v_mfma_f32_16x16x32_bf16 v[104:107], v[140:143], v[218:221], v[104:107]
	v_mfma_f32_16x16x32_bf16 v[92:95], v[132:135], v[228:231], v[92:95]
	v_mfma_f32_16x16x32_bf16 v[88:91], v[140:143], v[228:231], v[88:91]
	v_mfma_f32_16x16x32_bf16 v[76:79], v[132:135], v[236:239], v[76:79]
	v_mfma_f32_16x16x32_bf16 v[72:75], v[140:143], v[236:239], v[72:75]
	s_setprio 0
	s_setprio 1
	v_mfma_f32_16x16x32_bf16 v[116:119], v[144:147], v[186:189], v[116:119]
	v_mfma_f32_16x16x32_bf16 v[112:115], v[152:155], v[186:189], v[112:115]
	v_mfma_f32_16x16x32_bf16 v[100:103], v[144:147], v[214:217], v[100:103]
	v_mfma_f32_16x16x32_bf16 v[96:99], v[152:155], v[214:217], v[96:99]
	v_mfma_f32_16x16x32_bf16 v[84:87], v[144:147], v[224:227], v[84:87]
	v_mfma_f32_16x16x32_bf16 v[80:83], v[152:155], v[224:227], v[80:83]
	v_mfma_f32_16x16x32_bf16 v[68:71], v[144:147], v[232:235], v[68:71]
	v_mfma_f32_16x16x32_bf16 v[64:67], v[152:155], v[232:235], v[64:67]
	v_mfma_f32_16x16x32_bf16 v[116:119], v[148:151], v[194:197], v[116:119]
	v_mfma_f32_16x16x32_bf16 v[112:115], v[156:159], v[194:197], v[112:115]
	v_mfma_f32_16x16x32_bf16 v[100:103], v[148:151], v[218:221], v[100:103]
	v_mfma_f32_16x16x32_bf16 v[96:99], v[156:159], v[218:221], v[96:99]
	v_mfma_f32_16x16x32_bf16 v[84:87], v[148:151], v[228:231], v[84:87]
	v_mfma_f32_16x16x32_bf16 v[80:83], v[156:159], v[228:231], v[80:83]
	v_mfma_f32_16x16x32_bf16 v[68:71], v[148:151], v[236:239], v[68:71]
	v_mfma_f32_16x16x32_bf16 v[64:67], v[156:159], v[236:239], v[64:67]
	s_setprio 0
	s_barrier
	s_add_i32 s10, s69, s24
	s_mov_b32 m0, s10
	ds_read_b128 v[186:189], v209 offset:16384
	ds_read_b128 v[194:197], v209 offset:17408
	ds_read_b128 v[214:217], v209 offset:18432
	ds_read_b128 v[218:221], v209 offset:19456
	ds_read_b128 v[224:227], v209 offset:20480
	ds_read_b128 v[228:231], v209 offset:21504
	ds_read_b128 v[232:235], v209 offset:22528
	ds_read_b128 v[236:239], v209 offset:23552
	global_load_lds_dwordx4 v162, s[56:57]
	s_add_i32 m0, s10, 0x2000
	s_add_u32 s42, s56, 0x20000
	s_addc_u32 s43, s57, 0
	s_add_i32 s10, s70, s24
	global_load_lds_dwordx4 v166, s[56:57]
	s_mov_b32 m0, s10
	s_nop 0
	global_load_lds_dwordx4 v162, s[42:43]
	s_add_i32 m0, s10, 0x2000
	s_nop 0
	global_load_lds_dwordx4 v166, s[42:43]
	s_mov_b32 m0, s45
	s_nop 0
	global_load_lds_dwordx4 v160, s[58:59]
	s_mov_b32 m0, s60
	s_nop 0
	global_load_lds_dwordx4 v164, s[58:59]
	s_waitcnt vmcnt(8)
	s_waitcnt lgkmcnt(0)
	s_barrier
	s_setprio 1
	s_waitcnt lgkmcnt(0)
	v_mfma_f32_16x16x32_bf16 v[60:63], v[128:131], v[186:189], v[60:63]
	v_mfma_f32_16x16x32_bf16 v[56:59], v[136:139], v[186:189], v[56:59]
	v_mfma_f32_16x16x32_bf16 v[44:47], v[128:131], v[214:217], v[44:47]
	v_mfma_f32_16x16x32_bf16 v[40:43], v[136:139], v[214:217], v[40:43]
	v_mfma_f32_16x16x32_bf16 v[28:31], v[128:131], v[224:227], v[28:31]
	v_mfma_f32_16x16x32_bf16 v[24:27], v[136:139], v[224:227], v[24:27]
	v_mfma_f32_16x16x32_bf16 v[12:15], v[128:131], v[232:235], v[12:15]
	v_mfma_f32_16x16x32_bf16 v[8:11], v[136:139], v[232:235], v[8:11]
	v_mfma_f32_16x16x32_bf16 v[60:63], v[132:135], v[194:197], v[60:63]
	v_mfma_f32_16x16x32_bf16 v[56:59], v[140:143], v[194:197], v[56:59]
	v_mfma_f32_16x16x32_bf16 v[44:47], v[132:135], v[218:221], v[44:47]
	v_mfma_f32_16x16x32_bf16 v[40:43], v[140:143], v[218:221], v[40:43]
	v_mfma_f32_16x16x32_bf16 v[28:31], v[132:135], v[228:231], v[28:31]
	v_mfma_f32_16x16x32_bf16 v[24:27], v[140:143], v[228:231], v[24:27]
	v_mfma_f32_16x16x32_bf16 v[12:15], v[132:135], v[236:239], v[12:15]
	v_mfma_f32_16x16x32_bf16 v[8:11], v[140:143], v[236:239], v[8:11]
	s_setprio 0
	s_setprio 1
	v_mfma_f32_16x16x32_bf16 v[52:55], v[144:147], v[186:189], v[52:55]
	v_mfma_f32_16x16x32_bf16 v[48:51], v[152:155], v[186:189], v[48:51]
	v_mfma_f32_16x16x32_bf16 v[36:39], v[144:147], v[214:217], v[36:39]
	v_mfma_f32_16x16x32_bf16 v[32:35], v[152:155], v[214:217], v[32:35]
	v_mfma_f32_16x16x32_bf16 v[20:23], v[144:147], v[224:227], v[20:23]
	v_mfma_f32_16x16x32_bf16 v[16:19], v[152:155], v[224:227], v[16:19]
	v_mfma_f32_16x16x32_bf16 v[4:7], v[144:147], v[232:235], v[4:7]
	v_mfma_f32_16x16x32_bf16 v[0:3], v[152:155], v[232:235], v[0:3]
	v_mfma_f32_16x16x32_bf16 v[52:55], v[148:151], v[194:197], v[52:55]
	v_mfma_f32_16x16x32_bf16 v[48:51], v[156:159], v[194:197], v[48:51]
	v_mfma_f32_16x16x32_bf16 v[36:39], v[148:151], v[218:221], v[36:39]
	v_mfma_f32_16x16x32_bf16 v[32:35], v[156:159], v[218:221], v[32:35]
	v_mfma_f32_16x16x32_bf16 v[20:23], v[148:151], v[228:231], v[20:23]
	v_mfma_f32_16x16x32_bf16 v[16:19], v[156:159], v[228:231], v[16:19]
	v_mfma_f32_16x16x32_bf16 v[4:7], v[148:151], v[236:239], v[4:7]
	v_mfma_f32_16x16x32_bf16 v[0:3], v[156:159], v[236:239], v[0:3]
	s_setprio 0
	s_barrier
; #define PG8_STAGE(bufoff, gbase, voff) do { _Pragma("unroll") for (int _i = 0; _i < 2; ++_i) \
;         __builtin_amdgcn_global_load_lds((const unsigned*)((const char*)(gbase) + (voff)[_i]), (LAS unsigned*)(lds + (bufoff) + ldsw + _i * 8192), 16, 0, 0); } while (0)
; #define PG8_LDA(dst, b, h) do { _Pragma("unroll") for (int m = 0; m < 4; ++m) _Pragma("unroll") for (int k = 0; k < 2; ++k) dst[m][k] = *(const LAS bf16x8*)(lds + PG8_SA(b, h) + aoff + m * 2048 + k * 1024); } while (0)
; #define PG8_LDB(dst, b, h) do { _Pragma("unroll") for (int n = 0; n < 2; ++n) _Pragma("unroll") for (int k = 0; k < 2; ++k) dst[n][k] = *(const LAS bf16x8*)(lds + PG8_SB(b, h) + boff + n * 2048 + k * 1024); } while (0)
; #define PG8_MMA(ai, bj, At, Bt) do { __builtin_amdgcn_s_setprio(1); _Pragma("unroll") for (int m = 0; m < 4; ++m) _Pragma("unroll") for (int n = 0; n < 2; ++n) _Pragma("unroll") for (int k = 0; k < 2; ++k) \
;         acc[ai][bj][m][n] = __builtin_amdgcn_mfma_f32_16x16x32_bf16(Bt[n][k], At[m][k], acc[ai][bj][m][n], 0, 0, 0); __builtin_amdgcn_s_setprio(0); } while (0)
; #define PG8_WAIT_V(n) asm volatile("s_waitcnt vmcnt(" #n ")" ::: "memory")
; #define PG8_WAIT_L(n) asm volatile("s_waitcnt lgkmcnt(" #n ")" ::: "memory")
; #define PG8_BAR __builtin_amdgcn_s_barrier()
; #define PG8_SCHED __builtin_amdgcn_sched_barrier(0)
; template <int K, int LDA, int LDB, class Epi, class Sched>
; __device__ __forceinline__ void gemm_phase(LAS unsigned char* lds, const Gemm g, const Sched& S, const Epi& E, int wv) {
;     ...
;             PG8_LDB(B0, 1, 0); PG8_LDB(B1, 1, 1); PG8_SCHED; PG8_LDA(At, 1, 0); PG8_STAGE(PG8_SA(0, 1), a2 + hstepA, voffA);
;             PG8_WAIT_V(8); PG8_WAIT_L(0); PG8_BAR; PG8_MMA(0, 0, At, B0); PG8_MMA(0, 1, At, B1); PG8_BAR; PG8_SCHED;
;             PG8_LDA(At, 1, 1); PG8_STAGE(PG8_SB(1, 0), b3, voffB); PG8_STAGE(PG8_SB(1, 1), b3 + hstepB, voffB); PG8_STAGE(PG8_SA(1, 0), a3, voffA);
;             PG8_WAIT_V(8); PG8_WAIT_L(0); PG8_BAR; PG8_MMA(1, 0, At, B0); PG8_MMA(1, 1, At, B1); PG8_BAR; PG8_SCHED;
;         }
;         if (wr == 0) PG8_BAR;
	s_add_i32 s10, 0, 0x18000
	s_add_i32 s11, 0, 0x1c000
	v_add_u32_e32 v140, s10, v185
	v_add_u32_e32 v156, s11, v185
	ds_read_b128 v[128:131], v140
	ds_read_b128 v[132:135], v140 offset:1024
	ds_read_b128 v[136:139], v140 offset:2048
	ds_read_b128 v[140:143], v140 offset:3072
	ds_read_b128 v[144:147], v156
	ds_read_b128 v[148:151], v156 offset:1024
	ds_read_b128 v[152:155], v156 offset:2048
	ds_read_b128 v[156:159], v156 offset:3072
	s_add_u32 s42, s58, 0x120000
	s_addc_u32 s43, s59, 0
	s_mov_b32 m0, s61
	ds_read_b128 v[186:189], v209 offset:32768
	ds_read_b128 v[194:197], v209 offset:33792
	ds_read_b128 v[214:217], v209 offset:34816
	ds_read_b128 v[218:221], v209 offset:35840
	ds_read_b128 v[224:227], v209 offset:36864
	ds_read_b128 v[228:231], v209 offset:37888
	ds_read_b128 v[232:235], v209 offset:38912
	ds_read_b128 v[236:239], v209 offset:39936
	global_load_lds_dwordx4 v160, s[42:43]
	s_mov_b32 m0, s62
	s_nop 0
	global_load_lds_dwordx4 v164, s[42:43]
	s_waitcnt vmcnt(8)
	s_waitcnt lgkmcnt(0)
	s_barrier
	s_setprio 1
	s_waitcnt lgkmcnt(0)
	v_mfma_f32_16x16x32_bf16 v[124:127], v[128:131], v[186:189], v[124:127]
	v_mfma_f32_16x16x32_bf16 v[120:123], v[136:139], v[186:189], v[120:123]
	v_mfma_f32_16x16x32_bf16 v[108:111], v[128:131], v[214:217], v[108:111]
	v_mfma_f32_16x16x32_bf16 v[104:107], v[136:139], v[214:217], v[104:107]
	v_mfma_f32_16x16x32_bf16 v[92:95], v[128:131], v[224:227], v[92:95]
	v_mfma_f32_16x16x32_bf16 v[88:91], v[136:139], v[224:227], v[88:91]
	v_mfma_f32_16x16x32_bf16 v[76:79], v[128:131], v[232:235], v[76:79]
	v_mfma_f32_16x16x32_bf16 v[72:75], v[136:139], v[232:235], v[72:75]
	v_mfma_f32_16x16x32_bf16 v[124:127], v[132:135], v[194:197], v[124:127]
	v_mfma_f32_16x16x32_bf16 v[120:123], v[140:143], v[194:197], v[120:123]
	v_mfma_f32_16x16x32_bf16 v[108:111], v[132:135], v[218:221], v[108:111]
	v_mfma_f32_16x16x32_bf16 v[104:107], v[140:143], v[218:221], v[104:107]
	v_mfma_f32_16x16x32_bf16 v[92:95], v[132:135], v[228:231], v[92:95]
	v_mfma_f32_16x16x32_bf16 v[88:91], v[140:143], v[228:231], v[88:91]
	v_mfma_f32_16x16x32_bf16 v[76:79], v[132:135], v[236:239], v[76:79]
	v_mfma_f32_16x16x32_bf16 v[72:75], v[140:143], v[236:239], v[72:75]
	s_setprio 0
	s_setprio 1
	v_mfma_f32_16x16x32_bf16 v[116:119], v[144:147], v[186:189], v[116:119]
	v_mfma_f32_16x16x32_bf16 v[112:115], v[152:155], v[186:189], v[112:115]
	v_mfma_f32_16x16x32_bf16 v[100:103], v[144:147], v[214:217], v[100:103]
	v_mfma_f32_16x16x32_bf16 v[96:99], v[152:155], v[214:217], v[96:99]
	v_mfma_f32_16x16x32_bf16 v[84:87], v[144:147], v[224:227], v[84:87]
	v_mfma_f32_16x16x32_bf16 v[80:83], v[152:155], v[224:227], v[80:83]
	v_mfma_f32_16x16x32_bf16 v[68:71], v[144:147], v[232:235], v[68:71]
	v_mfma_f32_16x16x32_bf16 v[64:67], v[152:155], v[232:235], v[64:67]
	v_mfma_f32_16x16x32_bf16 v[116:119], v[148:151], v[194:197], v[116:119]
	v_mfma_f32_16x16x32_bf16 v[112:115], v[156:159], v[194:197], v[112:115]
	v_mfma_f32_16x16x32_bf16 v[100:103], v[148:151], v[218:221], v[100:103]
	v_mfma_f32_16x16x32_bf16 v[96:99], v[156:159], v[218:221], v[96:99]
	v_mfma_f32_16x16x32_bf16 v[84:87], v[148:151], v[228:231], v[84:87]
	v_mfma_f32_16x16x32_bf16 v[80:83], v[156:159], v[228:231], v[80:83]
	v_mfma_f32_16x16x32_bf16 v[68:71], v[148:151], v[236:239], v[68:71]
	v_mfma_f32_16x16x32_bf16 v[64:67], v[156:159], v[236:239], v[64:67]
	s_setprio 0
	s_barrier
	s_add_i32 s10, s10, s24
	s_mov_b32 m0, s10
	ds_read_b128 v[186:189], v209 offset:49152
	ds_read_b128 v[194:197], v209 offset:50176
	ds_read_b128 v[214:217], v209 offset:51200
	ds_read_b128 v[218:221], v209 offset:52224
	ds_read_b128 v[224:227], v209 offset:53248
	ds_read_b128 v[228:231], v209 offset:54272
	ds_read_b128 v[232:235], v209 offset:55296
	ds_read_b128 v[236:239], v209 offset:56320
	s_add_u32 s98, s56, s14
	s_addc_u32 s99, s57, s15
	global_load_lds_dwordx4 v162, s[98:99]
	s_add_i32 m0, s10, 0x2000
	s_add_u32 s42, s56, 0x20080
	s_addc_u32 s43, s57, 0
	s_add_i32 s10, s11, s24
	global_load_lds_dwordx4 v166, s[98:99]
	s_mov_b32 m0, s10
	s_nop 0
	global_load_lds_dwordx4 v162, s[42:43]
	s_add_i32 m0, s10, 0x2000
	s_nop 0
	global_load_lds_dwordx4 v166, s[42:43]
	s_mov_b32 m0, s65
	s_nop 0
	s_add_u32 s100, s58, s14
	s_addc_u32 s101, s59, s15
	global_load_lds_dwordx4 v160, s[100:101]
	s_mov_b32 m0, s66
	s_nop 0
	global_load_lds_dwordx4 v164, s[100:101]
	s_waitcnt vmcnt(8)
	s_waitcnt lgkmcnt(0)
	s_barrier
	s_setprio 1
	s_waitcnt lgkmcnt(0)
	v_mfma_f32_16x16x32_bf16 v[60:63], v[128:131], v[186:189], v[60:63]
	v_mfma_f32_16x16x32_bf16 v[56:59], v[136:139], v[186:189], v[56:59]
	v_mfma_f32_16x16x32_bf16 v[44:47], v[128:131], v[214:217], v[44:47]
	v_mfma_f32_16x16x32_bf16 v[40:43], v[136:139], v[214:217], v[40:43]
	v_mfma_f32_16x16x32_bf16 v[28:31], v[128:131], v[224:227], v[28:31]
	v_mfma_f32_16x16x32_bf16 v[24:27], v[136:139], v[224:227], v[24:27]
	v_mfma_f32_16x16x32_bf16 v[12:15], v[128:131], v[232:235], v[12:15]
	v_mfma_f32_16x16x32_bf16 v[8:11], v[136:139], v[232:235], v[8:11]
	v_mfma_f32_16x16x32_bf16 v[60:63], v[132:135], v[194:197], v[60:63]
	v_mfma_f32_16x16x32_bf16 v[56:59], v[140:143], v[194:197], v[56:59]
	v_mfma_f32_16x16x32_bf16 v[44:47], v[132:135], v[218:221], v[44:47]
	v_mfma_f32_16x16x32_bf16 v[40:43], v[140:143], v[218:221], v[40:43]
	v_mfma_f32_16x16x32_bf16 v[28:31], v[132:135], v[228:231], v[28:31]
	v_mfma_f32_16x16x32_bf16 v[24:27], v[140:143], v[228:231], v[24:27]
	v_mfma_f32_16x16x32_bf16 v[12:15], v[132:135], v[236:239], v[12:15]
	v_mfma_f32_16x16x32_bf16 v[8:11], v[140:143], v[236:239], v[8:11]
	s_setprio 0
	s_setprio 1
	v_mfma_f32_16x16x32_bf16 v[52:55], v[144:147], v[186:189], v[52:55]
	v_mfma_f32_16x16x32_bf16 v[48:51], v[152:155], v[186:189], v[48:51]
	v_mfma_f32_16x16x32_bf16 v[36:39], v[144:147], v[214:217], v[36:39]
	v_mfma_f32_16x16x32_bf16 v[32:35], v[152:155], v[214:217], v[32:35]
	v_mfma_f32_16x16x32_bf16 v[20:23], v[144:147], v[224:227], v[20:23]
	v_mfma_f32_16x16x32_bf16 v[16:19], v[152:155], v[224:227], v[16:19]
	v_mfma_f32_16x16x32_bf16 v[4:7], v[144:147], v[232:235], v[4:7]
	v_mfma_f32_16x16x32_bf16 v[0:3], v[152:155], v[232:235], v[0:3]
	v_mfma_f32_16x16x32_bf16 v[52:55], v[148:151], v[194:197], v[52:55]
	v_mfma_f32_16x16x32_bf16 v[48:51], v[156:159], v[194:197], v[48:51]
	v_mfma_f32_16x16x32_bf16 v[36:39], v[148:151], v[218:221], v[36:39]
	v_mfma_f32_16x16x32_bf16 v[32:35], v[156:159], v[218:221], v[32:35]
	v_mfma_f32_16x16x32_bf16 v[20:23], v[148:151], v[228:231], v[20:23]
	v_mfma_f32_16x16x32_bf16 v[16:19], v[156:159], v[228:231], v[16:19]
	v_mfma_f32_16x16x32_bf16 v[4:7], v[148:151], v[236:239], v[4:7]
	v_mfma_f32_16x16x32_bf16 v[0:3], v[156:159], v[236:239], v[0:3]
	s_setprio 0
	s_barrier
	s_add_i32 s77, s77, 2
	s_add_u32 s75, s75, 0x100
	s_addc_u32 s76, s76, 0
	s_cmp_gt_u32 s77, 5
	s_mov_b64 s[42:43], s[8:9]
	s_cbranch_scc0 .LBB0_1030
	s_and_b64 vcc, exec, s[28:29]
	s_cbranch_vccz .LBB0_1033
	s_barrier

; #define PG8_STAGE(bufoff, gbase, voff) do { _Pragma("unroll") for (int _i = 0; _i < 2; ++_i) \
;         __builtin_amdgcn_global_load_lds((const unsigned*)((const char*)(gbase) + (voff)[_i]), (LAS unsigned*)(lds + (bufoff) + ldsw + _i * 8192), 16, 0, 0); } while (0)
; #define PG8_LDA(dst, b, h) do { _Pragma("unroll") for (int m = 0; m < 4; ++m) _Pragma("unroll") for (int k = 0; k < 2; ++k) dst[m][k] = *(const LAS bf16x8*)(lds + PG8_SA(b, h) + aoff + m * 2048 + k * 1024); } while (0)
; #define PG8_LDB(dst, b, h) do { _Pragma("unroll") for (int n = 0; n < 2; ++n) _Pragma("unroll") for (int k = 0; k < 2; ++k) dst[n][k] = *(const LAS bf16x8*)(lds + PG8_SB(b, h) + boff + n * 2048 + k * 1024); } while (0)
; #define PG8_MMA(ai, bj, At, Bt) do { __builtin_amdgcn_s_setprio(1); _Pragma("unroll") for (int m = 0; m < 4; ++m) _Pragma("unroll") for (int n = 0; n < 2; ++n) _Pragma("unroll") for (int k = 0; k < 2; ++k) \
;         acc[ai][bj][m][n] = __builtin_amdgcn_mfma_f32_16x16x32_bf16(Bt[n][k], At[m][k], acc[ai][bj][m][n], 0, 0, 0); __builtin_amdgcn_s_setprio(0); } while (0)
; #define PG8_WAIT_V(n) asm volatile("s_waitcnt vmcnt(" #n ")" ::: "memory")
; #define PG8_WAIT_L(n) asm volatile("s_waitcnt lgkmcnt(" #n ")" ::: "memory")
; #define PG8_BAR __builtin_amdgcn_s_barrier()
; #define PG8_SCHED __builtin_amdgcn_sched_barrier(0)
; template <int K, int LDA, int LDB, class Epi, class Sched>
; __device__ __forceinline__ void gemm_phase(LAS unsigned char* lds, const Gemm g, const Sched& S, const Epi& E, int wv) {
;     ...
;             const bool last = (t == nt - 2);
;             const char* a1 = cA + (size_t)(t + 1) * kstep;
;             const char* a2 = last ? nA : cA + (size_t)(t + 2) * kstep; const char* b2 = last ? nB : cB + (size_t)(t + 2) * kstep;
;             const char* a3 = a2 + kstep; const char* b3 = b2 + kstep;
;             PG8_LDB(B0, 0, 0); PG8_LDB(B1, 0, 1); PG8_SCHED; PG8_LDA(At, 0, 0); PG8_STAGE(PG8_SA(1, 1), a1 + hstepA, voffA);
;             PG8_WAIT_V(8); PG8_WAIT_L(0); PG8_BAR; PG8_MMA(0, 0, At, B0); PG8_MMA(0, 1, At, B1); PG8_BAR; PG8_SCHED;
;             PG8_LDA(At, 0, 1); PG8_STAGE(PG8_SB(0, 0), b2, voffB); PG8_STAGE(PG8_SB(0, 1), b2 + hstepB, voffB); PG8_STAGE(PG8_SA(0, 0), a2, voffA);
;             PG8_WAIT_V(8); PG8_WAIT_L(0); PG8_BAR; PG8_MMA(1, 0, At, B0); PG8_MMA(1, 1, At, B1); PG8_BAR; PG8_SCHED;
.LBB0_1084:
	s_add_u32 s10, s54, s58
	s_addc_u32 s11, s55, s59
	s_add_u32 s62, s10, 0x100
	s_addc_u32 s63, s11, 0
	s_and_b64 s[60:61], s[56:57], exec
	s_cselect_b32 s61, s41, s63
	s_cselect_b32 s60, s40, s62
	s_add_u32 s58, s52, s58
	s_addc_u32 s59, s53, s59
	s_add_u32 s58, s58, 0x100
	s_addc_u32 s59, s59, 0
	s_and_b64 s[56:57], s[56:57], exec
	s_cselect_b32 s63, s39, s59
	s_cselect_b32 s62, s81, s58
	s_add_u32 s66, s10, 0x120080
	ds_read_b128 v[144:147], v157
	ds_read_b128 v[164:167], v157 offset:1024
	ds_read_b128 v[168:171], v157 offset:2048
	ds_read_b128 v[172:175], v157 offset:3072
	ds_read_b128 v[176:179], v160
	ds_read_b128 v[180:183], v160 offset:1024
	ds_read_b128 v[184:187], v160 offset:2048
	ds_read_b128 v[188:191], v160 offset:3072
	s_addc_u32 s67, s11, 0
	s_add_i32 s91, s76, s24
	s_add_i32 m0, s69, 0xc000
	s_add_i32 s10, s69, 0xe000
	s_add_i32 s88, s91, 0x2000
	s_add_u32 s64, s62, 0x10000
	s_addc_u32 s65, s63, 0
	s_add_i32 s90, s77, s24
	s_add_i32 s89, s90, 0x2000
	s_add_i32 s87, 0, 0x18000
	s_add_i32 s86, 0, 0x1c000
	s_add_u32 s58, s60, 0x120000
	s_addc_u32 s59, s61, 0
	s_add_i32 s85, s87, s24
	s_add_i32 s83, s85, 0x2000
	s_add_u32 s56, s62, 0x10080
	s_addc_u32 s57, s63, 0
	s_add_i32 s84, s86, s24
	s_add_i32 s82, s84, 0x2000
	ds_read_b128 v[192:195], v161
	ds_read_b128 v[196:199], v161 offset:1024
	ds_read_b128 v[200:203], v161 offset:2048
	ds_read_b128 v[204:207], v161 offset:3072
	ds_read_b128 v[208:211], v161 offset:4096
	ds_read_b128 v[212:215], v161 offset:5120
	ds_read_b128 v[216:219], v161 offset:6144
	ds_read_b128 v[224:227], v161 offset:7168
	global_load_lds_dwordx4 v134, s[66:67]
	s_mov_b32 m0, s10
	s_nop 0
	global_load_lds_dwordx4 v130, s[66:67]
	s_waitcnt vmcnt(8)
	s_waitcnt lgkmcnt(0)
	s_barrier
	s_setprio 1
	s_waitcnt lgkmcnt(0)
	v_mfma_f32_16x16x32_bf16 v[124:127], v[144:147], v[192:195], v[124:127]
	v_mfma_f32_16x16x32_bf16 v[120:123], v[168:171], v[192:195], v[120:123]
	v_mfma_f32_16x16x32_bf16 v[112:115], v[144:147], v[200:203], v[112:115]
	v_mfma_f32_16x16x32_bf16 v[104:107], v[168:171], v[200:203], v[104:107]
	v_mfma_f32_16x16x32_bf16 v[96:99], v[144:147], v[208:211], v[96:99]
	v_mfma_f32_16x16x32_bf16 v[88:91], v[168:171], v[208:211], v[88:91]
	v_mfma_f32_16x16x32_bf16 v[80:83], v[144:147], v[216:219], v[80:83]
	v_mfma_f32_16x16x32_bf16 v[72:75], v[168:171], v[216:219], v[72:75]
	v_mfma_f32_16x16x32_bf16 v[124:127], v[164:167], v[196:199], v[124:127]
	v_mfma_f32_16x16x32_bf16 v[120:123], v[172:175], v[196:199], v[120:123]
	v_mfma_f32_16x16x32_bf16 v[112:115], v[164:167], v[204:207], v[112:115]
	v_mfma_f32_16x16x32_bf16 v[104:107], v[172:175], v[204:207], v[104:107]
	v_mfma_f32_16x16x32_bf16 v[96:99], v[164:167], v[212:215], v[96:99]
	v_mfma_f32_16x16x32_bf16 v[88:91], v[172:175], v[212:215], v[88:91]
	v_mfma_f32_16x16x32_bf16 v[80:83], v[164:167], v[224:227], v[80:83]
	v_mfma_f32_16x16x32_bf16 v[72:75], v[172:175], v[224:227], v[72:75]
	s_setprio 0
	s_setprio 1
	v_mfma_f32_16x16x32_bf16 v[116:119], v[176:179], v[192:195], v[116:119]
	v_mfma_f32_16x16x32_bf16 v[108:111], v[184:187], v[192:195], v[108:111]
	v_mfma_f32_16x16x32_bf16 v[100:103], v[176:179], v[200:203], v[100:103]
	v_mfma_f32_16x16x32_bf16 v[92:95], v[184:187], v[200:203], v[92:95]
	v_mfma_f32_16x16x32_bf16 v[84:87], v[176:179], v[208:211], v[84:87]
	v_mfma_f32_16x16x32_bf16 v[76:79], v[184:187], v[208:211], v[76:79]
	v_mfma_f32_16x16x32_bf16 v[68:71], v[176:179], v[216:219], v[68:71]
	v_mfma_f32_16x16x32_bf16 v[64:67], v[184:187], v[216:219], v[64:67]
	v_mfma_f32_16x16x32_bf16 v[116:119], v[180:183], v[196:199], v[116:119]
	v_mfma_f32_16x16x32_bf16 v[108:111], v[188:191], v[196:199], v[108:111]
	v_mfma_f32_16x16x32_bf16 v[100:103], v[180:183], v[204:207], v[100:103]
	v_mfma_f32_16x16x32_bf16 v[92:95], v[188:191], v[204:207], v[92:95]
	v_mfma_f32_16x16x32_bf16 v[84:87], v[180:183], v[212:215], v[84:87]
	v_mfma_f32_16x16x32_bf16 v[76:79], v[188:191], v[212:215], v[76:79]
	v_mfma_f32_16x16x32_bf16 v[68:71], v[180:183], v[224:227], v[68:71]
	v_mfma_f32_16x16x32_bf16 v[64:67], v[188:191], v[224:227], v[64:67]
	s_setprio 0
	s_barrier
	s_mov_b32 m0, s91
	ds_read_b128 v[192:195], v161 offset:16384
	ds_read_b128 v[196:199], v161 offset:17408
	ds_read_b128 v[200:203], v161 offset:18432
	ds_read_b128 v[204:207], v161 offset:19456
	ds_read_b128 v[208:211], v161 offset:20480
	ds_read_b128 v[212:215], v161 offset:21504
	ds_read_b128 v[216:219], v161 offset:22528
	ds_read_b128 v[224:227], v161 offset:23552
	global_load_lds_dwordx4 v132, s[62:63]
	s_mov_b32 m0, s88
	s_nop 0
	global_load_lds_dwordx4 v128, s[62:63]
	s_mov_b32 m0, s90
	s_nop 0
	global_load_lds_dwordx4 v132, s[64:65]
	s_mov_b32 m0, s89
	s_nop 0
	global_load_lds_dwordx4 v128, s[64:65]
	s_mov_b32 m0, s69
	s_nop 0
	global_load_lds_dwordx4 v134, s[60:61]
	s_mov_b32 m0, s70
	s_nop 0
	global_load_lds_dwordx4 v130, s[60:61]
	s_waitcnt vmcnt(8)
	s_waitcnt lgkmcnt(0)
	s_barrier
; #define PG8_STAGE(bufoff, gbase, voff) do { _Pragma("unroll") for (int _i = 0; _i < 2; ++_i) \
;         __builtin_amdgcn_global_load_lds((const unsigned*)((const char*)(gbase) + (voff)[_i]), (LAS unsigned*)(lds + (bufoff) + ldsw + _i * 8192), 16, 0, 0); } while (0)
; #define PG8_LDA(dst, b, h) do { _Pragma("unroll") for (int m = 0; m < 4; ++m) _Pragma("unroll") for (int k = 0; k < 2; ++k) dst[m][k] = *(const LAS bf16x8*)(lds + PG8_SA(b, h) + aoff + m * 2048 + k * 1024); } while (0)
; #define PG8_LDB(dst, b, h) do { _Pragma("unroll") for (int n = 0; n < 2; ++n) _Pragma("unroll") for (int k = 0; k < 2; ++k) dst[n][k] = *(const LAS bf16x8*)(lds + PG8_SB(b, h) + boff + n * 2048 + k * 1024); } while (0)
; #define PG8_MMA(ai, bj, At, Bt) do { __builtin_amdgcn_s_setprio(1); _Pragma("unroll") for (int m = 0; m < 4; ++m) _Pragma("unroll") for (int n = 0; n < 2; ++n) _Pragma("unroll") for (int k = 0; k < 2; ++k) \
;         acc[ai][bj][m][n] = __builtin_amdgcn_mfma_f32_16x16x32_bf16(Bt[n][k], At[m][k], acc[ai][bj][m][n], 0, 0, 0); __builtin_amdgcn_s_setprio(0); } while (0)
; #define PG8_WAIT_V(n) asm volatile("s_waitcnt vmcnt(" #n ")" ::: "memory")
; #define PG8_WAIT_L(n) asm volatile("s_waitcnt lgkmcnt(" #n ")" ::: "memory")
; #define PG8_BAR __builtin_amdgcn_s_barrier()
; #define PG8_SCHED __builtin_amdgcn_sched_barrier(0)
; template <int K, int LDA, int LDB, class Epi, class Sched>
; __device__ __forceinline__ void gemm_phase(LAS unsigned char* lds, const Gemm g, const Sched& S, const Epi& E, int wv) {
;     ...
;             PG8_WAIT_V(8); PG8_WAIT_L(0); PG8_BAR; PG8_MMA(1, 0, At, B0); PG8_MMA(1, 1, At, B1); PG8_BAR; PG8_SCHED;
;             PG8_LDB(B0, 1, 0); PG8_LDB(B1, 1, 1); PG8_SCHED; PG8_LDA(At, 1, 0); PG8_STAGE(PG8_SA(0, 1), a2 + hstepA, voffA);
;             PG8_WAIT_V(8); PG8_WAIT_L(0); PG8_BAR; PG8_MMA(0, 0, At, B0); PG8_MMA(0, 1, At, B1); PG8_BAR; PG8_SCHED;
	s_setprio 1
	s_waitcnt lgkmcnt(0)
	v_mfma_f32_16x16x32_bf16 v[60:63], v[144:147], v[192:195], v[60:63]
	v_mfma_f32_16x16x32_bf16 v[56:59], v[168:171], v[192:195], v[56:59]
	v_mfma_f32_16x16x32_bf16 v[48:51], v[144:147], v[200:203], v[48:51]
	v_mfma_f32_16x16x32_bf16 v[40:43], v[168:171], v[200:203], v[40:43]
	v_mfma_f32_16x16x32_bf16 v[32:35], v[144:147], v[208:211], v[32:35]
	v_mfma_f32_16x16x32_bf16 v[24:27], v[168:171], v[208:211], v[24:27]
	v_mfma_f32_16x16x32_bf16 v[16:19], v[144:147], v[216:219], v[16:19]
	v_mfma_f32_16x16x32_bf16 v[8:11], v[168:171], v[216:219], v[8:11]
	v_mfma_f32_16x16x32_bf16 v[60:63], v[164:167], v[196:199], v[60:63]
	v_mfma_f32_16x16x32_bf16 v[56:59], v[172:175], v[196:199], v[56:59]
	v_mfma_f32_16x16x32_bf16 v[48:51], v[164:167], v[204:207], v[48:51]
	v_mfma_f32_16x16x32_bf16 v[40:43], v[172:175], v[204:207], v[40:43]
	v_mfma_f32_16x16x32_bf16 v[32:35], v[164:167], v[212:215], v[32:35]
	v_mfma_f32_16x16x32_bf16 v[24:27], v[172:175], v[212:215], v[24:27]
	v_mfma_f32_16x16x32_bf16 v[16:19], v[164:167], v[224:227], v[16:19]
	v_mfma_f32_16x16x32_bf16 v[8:11], v[172:175], v[224:227], v[8:11]
	s_setprio 0
	s_setprio 1
	v_mfma_f32_16x16x32_bf16 v[52:55], v[176:179], v[192:195], v[52:55]
	v_mfma_f32_16x16x32_bf16 v[44:47], v[184:187], v[192:195], v[44:47]
	v_mfma_f32_16x16x32_bf16 v[36:39], v[176:179], v[200:203], v[36:39]
	v_mfma_f32_16x16x32_bf16 v[28:31], v[184:187], v[200:203], v[28:31]
	v_mfma_f32_16x16x32_bf16 v[20:23], v[176:179], v[208:211], v[20:23]
	v_mfma_f32_16x16x32_bf16 v[12:15], v[184:187], v[208:211], v[12:15]
	v_mfma_f32_16x16x32_bf16 v[4:7], v[176:179], v[216:219], v[4:7]
	v_mfma_f32_16x16x32_bf16 v[0:3], v[184:187], v[216:219], v[0:3]
	v_mfma_f32_16x16x32_bf16 v[52:55], v[180:183], v[196:199], v[52:55]
	v_mfma_f32_16x16x32_bf16 v[44:47], v[188:191], v[196:199], v[44:47]
	v_mfma_f32_16x16x32_bf16 v[36:39], v[180:183], v[204:207], v[36:39]
	v_mfma_f32_16x16x32_bf16 v[28:31], v[188:191], v[204:207], v[28:31]
	v_mfma_f32_16x16x32_bf16 v[20:23], v[180:183], v[212:215], v[20:23]
	v_mfma_f32_16x16x32_bf16 v[12:15], v[188:191], v[212:215], v[12:15]
	v_mfma_f32_16x16x32_bf16 v[4:7], v[180:183], v[224:227], v[4:7]
	v_mfma_f32_16x16x32_bf16 v[0:3], v[188:191], v[224:227], v[0:3]
	s_setprio 0
	s_barrier
	v_add_u32_e32 v142, s87, v149
	ds_read_b128 v[144:147], v142
	ds_read_b128 v[164:167], v142 offset:1024
	ds_read_b128 v[168:171], v142 offset:2048
	ds_read_b128 v[172:175], v142 offset:3072
	v_add_u32_e32 v142, s86, v149
	ds_read_b128 v[176:179], v142
	ds_read_b128 v[180:183], v142 offset:1024
	ds_read_b128 v[184:187], v142 offset:2048
	ds_read_b128 v[188:191], v142 offset:3072
	s_mov_b32 m0, s71
	ds_read_b128 v[192:195], v161 offset:32768
	ds_read_b128 v[196:199], v161 offset:33792
	ds_read_b128 v[200:203], v161 offset:34816
	ds_read_b128 v[204:207], v161 offset:35840
	ds_read_b128 v[208:211], v161 offset:36864
	ds_read_b128 v[212:215], v161 offset:37888
	ds_read_b128 v[216:219], v161 offset:38912
	ds_read_b128 v[224:227], v161 offset:39936
	global_load_lds_dwordx4 v134, s[58:59]
	s_mov_b32 m0, s72
	s_nop 0
	global_load_lds_dwordx4 v130, s[58:59]
	s_waitcnt vmcnt(8)
	s_waitcnt lgkmcnt(0)
	s_barrier
	s_setprio 1
	s_waitcnt lgkmcnt(0)
	v_mfma_f32_16x16x32_bf16 v[124:127], v[144:147], v[192:195], v[124:127]
	v_mfma_f32_16x16x32_bf16 v[120:123], v[168:171], v[192:195], v[120:123]
	v_mfma_f32_16x16x32_bf16 v[112:115], v[144:147], v[200:203], v[112:115]
	v_mfma_f32_16x16x32_bf16 v[104:107], v[168:171], v[200:203], v[104:107]
	v_mfma_f32_16x16x32_bf16 v[96:99], v[144:147], v[208:211], v[96:99]
	v_mfma_f32_16x16x32_bf16 v[88:91], v[168:171], v[208:211], v[88:91]
	v_mfma_f32_16x16x32_bf16 v[80:83], v[144:147], v[216:219], v[80:83]
	v_mfma_f32_16x16x32_bf16 v[72:75], v[168:171], v[216:219], v[72:75]
	v_mfma_f32_16x16x32_bf16 v[124:127], v[164:167], v[196:199], v[124:127]
	v_mfma_f32_16x16x32_bf16 v[120:123], v[172:175], v[196:199], v[120:123]
	v_mfma_f32_16x16x32_bf16 v[112:115], v[164:167], v[204:207], v[112:115]
	v_mfma_f32_16x16x32_bf16 v[104:107], v[172:175], v[204:207], v[104:107]
	v_mfma_f32_16x16x32_bf16 v[96:99], v[164:167], v[212:215], v[96:99]
	v_mfma_f32_16x16x32_bf16 v[88:91], v[172:175], v[212:215], v[88:91]
	v_mfma_f32_16x16x32_bf16 v[80:83], v[164:167], v[224:227], v[80:83]
	v_mfma_f32_16x16x32_bf16 v[72:75], v[172:175], v[224:227], v[72:75]
	s_setprio 0
	s_setprio 1
	v_mfma_f32_16x16x32_bf16 v[116:119], v[176:179], v[192:195], v[116:119]
	v_mfma_f32_16x16x32_bf16 v[108:111], v[184:187], v[192:195], v[108:111]
	v_mfma_f32_16x16x32_bf16 v[100:103], v[176:179], v[200:203], v[100:103]
	v_mfma_f32_16x16x32_bf16 v[92:95], v[184:187], v[200:203], v[92:95]
	v_mfma_f32_16x16x32_bf16 v[84:87], v[176:179], v[208:211], v[84:87]
	v_mfma_f32_16x16x32_bf16 v[76:79], v[184:187], v[208:211], v[76:79]
	v_mfma_f32_16x16x32_bf16 v[68:71], v[176:179], v[216:219], v[68:71]
	v_mfma_f32_16x16x32_bf16 v[64:67], v[184:187], v[216:219], v[64:67]
	v_mfma_f32_16x16x32_bf16 v[116:119], v[180:183], v[196:199], v[116:119]
	v_mfma_f32_16x16x32_bf16 v[108:111], v[188:191], v[196:199], v[108:111]
	v_mfma_f32_16x16x32_bf16 v[100:103], v[180:183], v[204:207], v[100:103]
	v_mfma_f32_16x16x32_bf16 v[92:95], v[188:191], v[204:207], v[92:95]
	v_mfma_f32_16x16x32_bf16 v[84:87], v[180:183], v[212:215], v[84:87]
	v_mfma_f32_16x16x32_bf16 v[76:79], v[188:191], v[212:215], v[76:79]
	v_mfma_f32_16x16x32_bf16 v[68:71], v[180:183], v[224:227], v[68:71]
	v_mfma_f32_16x16x32_bf16 v[64:67], v[188:191], v[224:227], v[64:67]
	s_setprio 0
	s_barrier
; #define PG8_STAGE(bufoff, gbase, voff) do { _Pragma("unroll") for (int _i = 0; _i < 2; ++_i) \
;         __builtin_amdgcn_global_load_lds((const unsigned*)((const char*)(gbase) + (voff)[_i]), (LAS unsigned*)(lds + (bufoff) + ldsw + _i * 8192), 16, 0, 0); } while (0)
; #define PG8_LDA(dst, b, h) do { _Pragma("unroll") for (int m = 0; m < 4; ++m) _Pragma("unroll") for (int k = 0; k < 2; ++k) dst[m][k] = *(const LAS bf16x8*)(lds + PG8_SA(b, h) + aoff + m * 2048 + k * 1024); } while (0)
; #define PG8_MMA(ai, bj, At, Bt) do { __builtin_amdgcn_s_setprio(1); _Pragma("unroll") for (int m = 0; m < 4; ++m) _Pragma("unroll") for (int n = 0; n < 2; ++n) _Pragma("unroll") for (int k = 0; k < 2; ++k) \
;         acc[ai][bj][m][n] = __builtin_amdgcn_mfma_f32_16x16x32_bf16(Bt[n][k], At[m][k], acc[ai][bj][m][n], 0, 0, 0); __builtin_amdgcn_s_setprio(0); } while (0)
; #define PG8_WAIT_V(n) asm volatile("s_waitcnt vmcnt(" #n ")" ::: "memory")
; #define PG8_WAIT_L(n) asm volatile("s_waitcnt lgkmcnt(" #n ")" ::: "memory")
; #define PG8_BAR __builtin_amdgcn_s_barrier()
; #define PG8_SCHED __builtin_amdgcn_sched_barrier(0)
; template <int K, int LDA, int LDB, class Epi, class Sched>
; __device__ __forceinline__ void gemm_phase(LAS unsigned char* lds, const Gemm g, const Sched& S, const Epi& E, int wv) {
;     ...
;             PG8_LDA(At, 1, 1); PG8_STAGE(PG8_SB(1, 0), b3, voffB); PG8_STAGE(PG8_SB(1, 1), b3 + hstepB, voffB); PG8_STAGE(PG8_SA(1, 0), a3, voffA);
;             PG8_WAIT_V(8); PG8_WAIT_L(0); PG8_BAR; PG8_MMA(1, 0, At, B0); PG8_MMA(1, 1, At, B1); PG8_BAR; PG8_SCHED;
;         }
;         if (wr == 0) PG8_BAR;
	s_mov_b32 m0, s85
	ds_read_b128 v[192:195], v161 offset:49152
	ds_read_b128 v[196:199], v161 offset:50176
	ds_read_b128 v[200:203], v161 offset:51200
	ds_read_b128 v[204:207], v161 offset:52224
	ds_read_b128 v[208:211], v161 offset:53248
	ds_read_b128 v[212:215], v161 offset:54272
	ds_read_b128 v[216:219], v161 offset:55296
	ds_read_b128 v[224:227], v161 offset:56320
	s_add_u32 s98, s62, s34
	s_addc_u32 s99, s63, s35
	global_load_lds_dwordx4 v132, s[98:99]
	s_mov_b32 m0, s83
	s_nop 0
	global_load_lds_dwordx4 v128, s[98:99]
	s_mov_b32 m0, s84
	s_nop 0
	global_load_lds_dwordx4 v132, s[56:57]
	s_mov_b32 m0, s82
	s_nop 0
	global_load_lds_dwordx4 v128, s[56:57]
	s_mov_b32 m0, s74
	s_nop 0
	s_add_u32 s100, s60, s34
	s_addc_u32 s101, s61, s35
	global_load_lds_dwordx4 v134, s[100:101]
	s_mov_b32 m0, s75
	s_nop 0
	global_load_lds_dwordx4 v130, s[100:101]
	s_waitcnt vmcnt(8)
	s_waitcnt lgkmcnt(0)
	s_barrier
	s_setprio 1
	s_waitcnt lgkmcnt(0)
	v_mfma_f32_16x16x32_bf16 v[60:63], v[144:147], v[192:195], v[60:63]
	v_mfma_f32_16x16x32_bf16 v[56:59], v[168:171], v[192:195], v[56:59]
	v_mfma_f32_16x16x32_bf16 v[48:51], v[144:147], v[200:203], v[48:51]
	v_mfma_f32_16x16x32_bf16 v[40:43], v[168:171], v[200:203], v[40:43]
	v_mfma_f32_16x16x32_bf16 v[32:35], v[144:147], v[208:211], v[32:35]
	v_mfma_f32_16x16x32_bf16 v[24:27], v[168:171], v[208:211], v[24:27]
	v_mfma_f32_16x16x32_bf16 v[16:19], v[144:147], v[216:219], v[16:19]
	v_mfma_f32_16x16x32_bf16 v[8:11], v[168:171], v[216:219], v[8:11]
	v_mfma_f32_16x16x32_bf16 v[60:63], v[164:167], v[196:199], v[60:63]
	v_mfma_f32_16x16x32_bf16 v[56:59], v[172:175], v[196:199], v[56:59]
	v_mfma_f32_16x16x32_bf16 v[48:51], v[164:167], v[204:207], v[48:51]
	v_mfma_f32_16x16x32_bf16 v[40:43], v[172:175], v[204:207], v[40:43]
	v_mfma_f32_16x16x32_bf16 v[32:35], v[164:167], v[212:215], v[32:35]
	v_mfma_f32_16x16x32_bf16 v[24:27], v[172:175], v[212:215], v[24:27]
	v_mfma_f32_16x16x32_bf16 v[16:19], v[164:167], v[224:227], v[16:19]
	v_mfma_f32_16x16x32_bf16 v[8:11], v[172:175], v[224:227], v[8:11]
	s_setprio 0
	s_setprio 1
	v_mfma_f32_16x16x32_bf16 v[52:55], v[176:179], v[192:195], v[52:55]
	v_mfma_f32_16x16x32_bf16 v[44:47], v[184:187], v[192:195], v[44:47]
	v_mfma_f32_16x16x32_bf16 v[36:39], v[176:179], v[200:203], v[36:39]
	v_mfma_f32_16x16x32_bf16 v[28:31], v[184:187], v[200:203], v[28:31]
	v_mfma_f32_16x16x32_bf16 v[20:23], v[176:179], v[208:211], v[20:23]
	v_mfma_f32_16x16x32_bf16 v[12:15], v[184:187], v[208:211], v[12:15]
	v_mfma_f32_16x16x32_bf16 v[4:7], v[176:179], v[216:219], v[4:7]
	v_mfma_f32_16x16x32_bf16 v[0:3], v[184:187], v[216:219], v[0:3]
	v_mfma_f32_16x16x32_bf16 v[52:55], v[180:183], v[196:199], v[52:55]
	v_mfma_f32_16x16x32_bf16 v[44:47], v[188:191], v[196:199], v[44:47]
	v_mfma_f32_16x16x32_bf16 v[36:39], v[180:183], v[204:207], v[36:39]
	v_mfma_f32_16x16x32_bf16 v[28:31], v[188:191], v[204:207], v[28:31]
	v_mfma_f32_16x16x32_bf16 v[20:23], v[180:183], v[212:215], v[20:23]
	v_mfma_f32_16x16x32_bf16 v[12:15], v[188:191], v[212:215], v[12:15]
	v_mfma_f32_16x16x32_bf16 v[4:7], v[180:183], v[224:227], v[4:7]
	v_mfma_f32_16x16x32_bf16 v[0:3], v[188:191], v[224:227], v[0:3]
	s_setprio 0
	s_barrier
	s_andn2_b64 vcc, exec, s[8:9]
	s_mov_b64 s[56:57], -1
	s_mov_b64 s[8:9], 0
	s_mov_b64 s[58:59], 0x100
	s_cbranch_vccz .LBB0_1084
	s_and_b64 vcc, exec, s[28:29]
	s_cbranch_vccz .LBB0_1087
	s_barrier

; #define PG8_STAGE(bufoff, gbase, voff) do { _Pragma("unroll") for (int _i = 0; _i < 2; ++_i) \
;         __builtin_amdgcn_global_load_lds((const unsigned*)((const char*)(gbase) + (voff)[_i]), (LAS unsigned*)(lds + (bufoff) + ldsw + _i * 8192), 16, 0, 0); } while (0)
; #define PG8_LDA(dst, b, h) do { _Pragma("unroll") for (int m = 0; m < 4; ++m) _Pragma("unroll") for (int k = 0; k < 2; ++k) dst[m][k] = *(const LAS bf16x8*)(lds + PG8_SA(b, h) + aoff + m * 2048 + k * 1024); } while (0)
; #define PG8_LDB(dst, b, h) do { _Pragma("unroll") for (int n = 0; n < 2; ++n) _Pragma("unroll") for (int k = 0; k < 2; ++k) dst[n][k] = *(const LAS bf16x8*)(lds + PG8_SB(b, h) + boff + n * 2048 + k * 1024); } while (0)
; #define PG8_MMA(ai, bj, At, Bt) do { __builtin_amdgcn_s_setprio(1); _Pragma("unroll") for (int m = 0; m < 4; ++m) _Pragma("unroll") for (int n = 0; n < 2; ++n) _Pragma("unroll") for (int k = 0; k < 2; ++k) \
;         acc[ai][bj][m][n] = __builtin_amdgcn_mfma_f32_16x16x32_bf16(Bt[n][k], At[m][k], acc[ai][bj][m][n], 0, 0, 0); __builtin_amdgcn_s_setprio(0); } while (0)
; #define PG8_WAIT_V(n) asm volatile("s_waitcnt vmcnt(" #n ")" ::: "memory")
; #define PG8_WAIT_L(n) asm volatile("s_waitcnt lgkmcnt(" #n ")" ::: "memory")
; #define PG8_BAR __builtin_amdgcn_s_barrier()
; #define PG8_SCHED __builtin_amdgcn_sched_barrier(0)
; template <int K, int LDA, int LDB, class Epi, class Sched>
; __device__ __forceinline__ void gemm_phase(LAS unsigned char* lds, const Gemm g, const Sched& S, const Epi& E, int wv) {
;     ...
;             const bool last = (t == nt - 2);
;             const char* a1 = cA + (size_t)(t + 1) * kstep;
;             const char* a2 = last ? nA : cA + (size_t)(t + 2) * kstep; const char* b2 = last ? nB : cB + (size_t)(t + 2) * kstep;
;             const char* a3 = a2 + kstep; const char* b3 = b2 + kstep;
;             PG8_LDB(B0, 0, 0); PG8_LDB(B1, 0, 1); PG8_SCHED; PG8_LDA(At, 0, 0); PG8_STAGE(PG8_SA(1, 1), a1 + hstepA, voffA);
;             PG8_WAIT_V(8); PG8_WAIT_L(0); PG8_BAR; PG8_MMA(0, 0, At, B0); PG8_MMA(0, 1, At, B1); PG8_BAR; PG8_SCHED;
;             PG8_LDA(At, 0, 1); PG8_STAGE(PG8_SB(0, 0), b2, voffB); PG8_STAGE(PG8_SB(0, 1), b2 + hstepB, voffB); PG8_STAGE(PG8_SA(0, 0), a2, voffA);
;             PG8_WAIT_V(8); PG8_WAIT_L(0); PG8_BAR; PG8_MMA(1, 0, At, B0); PG8_MMA(1, 1, At, B1); PG8_BAR; PG8_SCHED;
.LBB0_1106:
	s_add_u32 s64, s54, s58
	s_addc_u32 s65, s55, s59
	s_add_u32 s62, s64, 0x100
	s_addc_u32 s63, s65, 0
	s_and_b64 s[60:61], s[56:57], exec
	s_cselect_b32 s61, s37, s63
	s_cselect_b32 s60, s77, s62
	s_add_u32 s58, s52, s58
	s_addc_u32 s59, s53, s59
	s_add_u32 s58, s58, 0x100
	s_addc_u32 s59, s59, 0
	s_and_b64 s[56:57], s[56:57], exec
	s_cselect_b32 s63, s39, s59
	s_cselect_b32 s62, s38, s58
	s_add_u32 s66, s64, 0x10080
	ds_read_b128 v[140:143], v161
	ds_read_b128 v[144:147], v161 offset:1024
	ds_read_b128 v[148:151], v161 offset:2048
	ds_read_b128 v[152:155], v161 offset:3072
	ds_read_b128 v[166:169], v162
	ds_read_b128 v[170:173], v162 offset:1024
	ds_read_b128 v[174:177], v162 offset:2048
	ds_read_b128 v[178:181], v162 offset:3072
	s_addc_u32 s67, s65, 0
	s_add_i32 s87, s73, s24
	s_add_i32 m0, s43, 0xc000
	s_add_i32 s88, s43, 0xe000
	s_add_i32 s84, s87, 0x2000
	s_add_u32 s64, s62, 0x120000
	s_addc_u32 s65, s63, 0
	s_add_i32 s86, s74, s24
	s_add_i32 s85, s86, 0x2000
	s_add_i32 s83, 0, 0x18000
	s_add_i32 s82, 0, 0x1c000
	s_add_u32 s58, s60, 0x10000
	s_addc_u32 s59, s61, 0
	s_add_i32 s81, s83, s24
	s_add_i32 s79, s81, 0x2000
	s_add_u32 s56, s62, 0x120080
	s_addc_u32 s57, s63, 0
	s_add_i32 s80, s82, s24
	s_add_i32 s78, s80, 0x2000
	ds_read_b128 v[182:185], v163
	ds_read_b128 v[186:189], v163 offset:1024
	ds_read_b128 v[190:193], v163 offset:2048
	ds_read_b128 v[194:197], v163 offset:3072
	ds_read_b128 v[198:201], v163 offset:4096
	ds_read_b128 v[202:205], v163 offset:5120
	ds_read_b128 v[206:209], v163 offset:6144
	ds_read_b128 v[210:213], v163 offset:7168
	global_load_lds_dwordx4 v134, s[66:67]
	s_mov_b32 m0, s88
	s_nop 0
	global_load_lds_dwordx4 v130, s[66:67]
	s_waitcnt vmcnt(8)
	s_waitcnt lgkmcnt(0)
	s_barrier
	s_setprio 1
	s_waitcnt lgkmcnt(0)
	v_mfma_f32_16x16x32_bf16 v[124:127], v[140:143], v[182:185], v[124:127]
	v_mfma_f32_16x16x32_bf16 v[120:123], v[148:151], v[182:185], v[120:123]
	v_mfma_f32_16x16x32_bf16 v[112:115], v[140:143], v[190:193], v[112:115]
	v_mfma_f32_16x16x32_bf16 v[104:107], v[148:151], v[190:193], v[104:107]
	v_mfma_f32_16x16x32_bf16 v[96:99], v[140:143], v[198:201], v[96:99]
	v_mfma_f32_16x16x32_bf16 v[88:91], v[148:151], v[198:201], v[88:91]
	v_mfma_f32_16x16x32_bf16 v[80:83], v[140:143], v[206:209], v[80:83]
	v_mfma_f32_16x16x32_bf16 v[72:75], v[148:151], v[206:209], v[72:75]
	v_mfma_f32_16x16x32_bf16 v[124:127], v[144:147], v[186:189], v[124:127]
	v_mfma_f32_16x16x32_bf16 v[120:123], v[152:155], v[186:189], v[120:123]
	v_mfma_f32_16x16x32_bf16 v[112:115], v[144:147], v[194:197], v[112:115]
	v_mfma_f32_16x16x32_bf16 v[104:107], v[152:155], v[194:197], v[104:107]
	v_mfma_f32_16x16x32_bf16 v[96:99], v[144:147], v[202:205], v[96:99]
	v_mfma_f32_16x16x32_bf16 v[88:91], v[152:155], v[202:205], v[88:91]
	v_mfma_f32_16x16x32_bf16 v[80:83], v[144:147], v[210:213], v[80:83]
	v_mfma_f32_16x16x32_bf16 v[72:75], v[152:155], v[210:213], v[72:75]
	s_setprio 0
	s_setprio 1
	v_mfma_f32_16x16x32_bf16 v[116:119], v[166:169], v[182:185], v[116:119]
	v_mfma_f32_16x16x32_bf16 v[108:111], v[174:177], v[182:185], v[108:111]
	v_mfma_f32_16x16x32_bf16 v[100:103], v[166:169], v[190:193], v[100:103]
	v_mfma_f32_16x16x32_bf16 v[92:95], v[174:177], v[190:193], v[92:95]
	v_mfma_f32_16x16x32_bf16 v[84:87], v[166:169], v[198:201], v[84:87]
	v_mfma_f32_16x16x32_bf16 v[76:79], v[174:177], v[198:201], v[76:79]
	v_mfma_f32_16x16x32_bf16 v[68:71], v[166:169], v[206:209], v[68:71]
	v_mfma_f32_16x16x32_bf16 v[64:67], v[174:177], v[206:209], v[64:67]
	v_mfma_f32_16x16x32_bf16 v[116:119], v[170:173], v[186:189], v[116:119]
	v_mfma_f32_16x16x32_bf16 v[108:111], v[178:181], v[186:189], v[108:111]
	v_mfma_f32_16x16x32_bf16 v[100:103], v[170:173], v[194:197], v[100:103]
	v_mfma_f32_16x16x32_bf16 v[92:95], v[178:181], v[194:197], v[92:95]
	v_mfma_f32_16x16x32_bf16 v[84:87], v[170:173], v[202:205], v[84:87]
	v_mfma_f32_16x16x32_bf16 v[76:79], v[178:181], v[202:205], v[76:79]
	v_mfma_f32_16x16x32_bf16 v[68:71], v[170:173], v[210:213], v[68:71]
	v_mfma_f32_16x16x32_bf16 v[64:67], v[178:181], v[210:213], v[64:67]
	s_setprio 0
	s_barrier
	s_mov_b32 m0, s87
	ds_read_b128 v[182:185], v163 offset:16384
	ds_read_b128 v[186:189], v163 offset:17408
	ds_read_b128 v[190:193], v163 offset:18432
	ds_read_b128 v[194:197], v163 offset:19456
	ds_read_b128 v[198:201], v163 offset:20480
	ds_read_b128 v[202:205], v163 offset:21504
	ds_read_b128 v[206:209], v163 offset:22528
	ds_read_b128 v[210:213], v163 offset:23552
	global_load_lds_dwordx4 v132, s[62:63]
	s_mov_b32 m0, s84
	s_nop 0
	global_load_lds_dwordx4 v128, s[62:63]
	s_mov_b32 m0, s86
	s_nop 0
	global_load_lds_dwordx4 v132, s[64:65]
	s_mov_b32 m0, s85
	s_nop 0
	global_load_lds_dwordx4 v128, s[64:65]
	s_mov_b32 m0, s43
	s_nop 0
	global_load_lds_dwordx4 v134, s[60:61]
	s_mov_b32 m0, s45
	s_nop 0
	global_load_lds_dwordx4 v130, s[60:61]
	s_waitcnt vmcnt(8)
	s_waitcnt lgkmcnt(0)
	s_barrier
; #define PG8_STAGE(bufoff, gbase, voff) do { _Pragma("unroll") for (int _i = 0; _i < 2; ++_i) \
;         __builtin_amdgcn_global_load_lds((const unsigned*)((const char*)(gbase) + (voff)[_i]), (LAS unsigned*)(lds + (bufoff) + ldsw + _i * 8192), 16, 0, 0); } while (0)
; #define PG8_LDA(dst, b, h) do { _Pragma("unroll") for (int m = 0; m < 4; ++m) _Pragma("unroll") for (int k = 0; k < 2; ++k) dst[m][k] = *(const LAS bf16x8*)(lds + PG8_SA(b, h) + aoff + m * 2048 + k * 1024); } while (0)
; #define PG8_LDB(dst, b, h) do { _Pragma("unroll") for (int n = 0; n < 2; ++n) _Pragma("unroll") for (int k = 0; k < 2; ++k) dst[n][k] = *(const LAS bf16x8*)(lds + PG8_SB(b, h) + boff + n * 2048 + k * 1024); } while (0)
; #define PG8_MMA(ai, bj, At, Bt) do { __builtin_amdgcn_s_setprio(1); _Pragma("unroll") for (int m = 0; m < 4; ++m) _Pragma("unroll") for (int n = 0; n < 2; ++n) _Pragma("unroll") for (int k = 0; k < 2; ++k) \
;         acc[ai][bj][m][n] = __builtin_amdgcn_mfma_f32_16x16x32_bf16(Bt[n][k], At[m][k], acc[ai][bj][m][n], 0, 0, 0); __builtin_amdgcn_s_setprio(0); } while (0)
; #define PG8_WAIT_V(n) asm volatile("s_waitcnt vmcnt(" #n ")" ::: "memory")
; #define PG8_WAIT_L(n) asm volatile("s_waitcnt lgkmcnt(" #n ")" ::: "memory")
; #define PG8_BAR __builtin_amdgcn_s_barrier()
; #define PG8_SCHED __builtin_amdgcn_sched_barrier(0)
; template <int K, int LDA, int LDB, class Epi, class Sched>
; __device__ __forceinline__ void gemm_phase(LAS unsigned char* lds, const Gemm g, const Sched& S, const Epi& E, int wv) {
;     ...
;             PG8_WAIT_V(8); PG8_WAIT_L(0); PG8_BAR; PG8_MMA(1, 0, At, B0); PG8_MMA(1, 1, At, B1); PG8_BAR; PG8_SCHED;
;             PG8_LDB(B0, 1, 0); PG8_LDB(B1, 1, 1); PG8_SCHED; PG8_LDA(At, 1, 0); PG8_STAGE(PG8_SA(0, 1), a2 + hstepA, voffA);
;             PG8_WAIT_V(8); PG8_WAIT_L(0); PG8_BAR; PG8_MMA(0, 0, At, B0); PG8_MMA(0, 1, At, B1); PG8_BAR; PG8_SCHED;
	s_setprio 1
	s_waitcnt lgkmcnt(0)
	v_mfma_f32_16x16x32_bf16 v[60:63], v[140:143], v[182:185], v[60:63]
	v_mfma_f32_16x16x32_bf16 v[56:59], v[148:151], v[182:185], v[56:59]
	v_mfma_f32_16x16x32_bf16 v[48:51], v[140:143], v[190:193], v[48:51]
	v_mfma_f32_16x16x32_bf16 v[40:43], v[148:151], v[190:193], v[40:43]
	v_mfma_f32_16x16x32_bf16 v[32:35], v[140:143], v[198:201], v[32:35]
	v_mfma_f32_16x16x32_bf16 v[24:27], v[148:151], v[198:201], v[24:27]
	v_mfma_f32_16x16x32_bf16 v[16:19], v[140:143], v[206:209], v[16:19]
	v_mfma_f32_16x16x32_bf16 v[8:11], v[148:151], v[206:209], v[8:11]
	v_mfma_f32_16x16x32_bf16 v[60:63], v[144:147], v[186:189], v[60:63]
	v_mfma_f32_16x16x32_bf16 v[56:59], v[152:155], v[186:189], v[56:59]
	v_mfma_f32_16x16x32_bf16 v[48:51], v[144:147], v[194:197], v[48:51]
	v_mfma_f32_16x16x32_bf16 v[40:43], v[152:155], v[194:197], v[40:43]
	v_mfma_f32_16x16x32_bf16 v[32:35], v[144:147], v[202:205], v[32:35]
	v_mfma_f32_16x16x32_bf16 v[24:27], v[152:155], v[202:205], v[24:27]
	v_mfma_f32_16x16x32_bf16 v[16:19], v[144:147], v[210:213], v[16:19]
	v_mfma_f32_16x16x32_bf16 v[8:11], v[152:155], v[210:213], v[8:11]
	s_setprio 0
	s_setprio 1
	v_mfma_f32_16x16x32_bf16 v[52:55], v[166:169], v[182:185], v[52:55]
	v_mfma_f32_16x16x32_bf16 v[44:47], v[174:177], v[182:185], v[44:47]
	v_mfma_f32_16x16x32_bf16 v[36:39], v[166:169], v[190:193], v[36:39]
	v_mfma_f32_16x16x32_bf16 v[28:31], v[174:177], v[190:193], v[28:31]
	v_mfma_f32_16x16x32_bf16 v[20:23], v[166:169], v[198:201], v[20:23]
	v_mfma_f32_16x16x32_bf16 v[12:15], v[174:177], v[198:201], v[12:15]
	v_mfma_f32_16x16x32_bf16 v[4:7], v[166:169], v[206:209], v[4:7]
	v_mfma_f32_16x16x32_bf16 v[0:3], v[174:177], v[206:209], v[0:3]
	v_mfma_f32_16x16x32_bf16 v[52:55], v[170:173], v[186:189], v[52:55]
	v_mfma_f32_16x16x32_bf16 v[44:47], v[178:181], v[186:189], v[44:47]
	v_mfma_f32_16x16x32_bf16 v[36:39], v[170:173], v[194:197], v[36:39]
	v_mfma_f32_16x16x32_bf16 v[28:31], v[178:181], v[194:197], v[28:31]
	v_mfma_f32_16x16x32_bf16 v[20:23], v[170:173], v[202:205], v[20:23]
	v_mfma_f32_16x16x32_bf16 v[12:15], v[178:181], v[202:205], v[12:15]
	v_mfma_f32_16x16x32_bf16 v[4:7], v[170:173], v[210:213], v[4:7]
	v_mfma_f32_16x16x32_bf16 v[0:3], v[178:181], v[210:213], v[0:3]
	s_setprio 0
	s_barrier
	v_add_u32_e32 v152, s83, v159
	v_add_u32_e32 v165, s82, v159
	ds_read_b128 v[140:143], v152
	ds_read_b128 v[144:147], v152 offset:1024
	ds_read_b128 v[148:151], v152 offset:2048
	ds_read_b128 v[152:155], v152 offset:3072
	ds_read_b128 v[166:169], v165
	ds_read_b128 v[170:173], v165 offset:1024
	ds_read_b128 v[174:177], v165 offset:2048
	ds_read_b128 v[178:181], v165 offset:3072
	s_mov_b32 m0, s68
	ds_read_b128 v[182:185], v163 offset:32768
	ds_read_b128 v[186:189], v163 offset:33792
	ds_read_b128 v[190:193], v163 offset:34816
	ds_read_b128 v[194:197], v163 offset:35840
	ds_read_b128 v[198:201], v163 offset:36864
	ds_read_b128 v[202:205], v163 offset:37888
	ds_read_b128 v[206:209], v163 offset:38912
	ds_read_b128 v[210:213], v163 offset:39936
	global_load_lds_dwordx4 v134, s[58:59]
	s_mov_b32 m0, s69
	s_nop 0
	global_load_lds_dwordx4 v130, s[58:59]
	s_waitcnt vmcnt(8)
	s_waitcnt lgkmcnt(0)
	s_barrier
	s_setprio 1
	s_waitcnt lgkmcnt(0)
	v_mfma_f32_16x16x32_bf16 v[124:127], v[140:143], v[182:185], v[124:127]
	v_mfma_f32_16x16x32_bf16 v[120:123], v[148:151], v[182:185], v[120:123]
	v_mfma_f32_16x16x32_bf16 v[112:115], v[140:143], v[190:193], v[112:115]
	v_mfma_f32_16x16x32_bf16 v[104:107], v[148:151], v[190:193], v[104:107]
	v_mfma_f32_16x16x32_bf16 v[96:99], v[140:143], v[198:201], v[96:99]
	v_mfma_f32_16x16x32_bf16 v[88:91], v[148:151], v[198:201], v[88:91]
	v_mfma_f32_16x16x32_bf16 v[80:83], v[140:143], v[206:209], v[80:83]
	v_mfma_f32_16x16x32_bf16 v[72:75], v[148:151], v[206:209], v[72:75]
	v_mfma_f32_16x16x32_bf16 v[124:127], v[144:147], v[186:189], v[124:127]
	v_mfma_f32_16x16x32_bf16 v[120:123], v[152:155], v[186:189], v[120:123]
	v_mfma_f32_16x16x32_bf16 v[112:115], v[144:147], v[194:197], v[112:115]
	v_mfma_f32_16x16x32_bf16 v[104:107], v[152:155], v[194:197], v[104:107]
	v_mfma_f32_16x16x32_bf16 v[96:99], v[144:147], v[202:205], v[96:99]
	v_mfma_f32_16x16x32_bf16 v[88:91], v[152:155], v[202:205], v[88:91]
	v_mfma_f32_16x16x32_bf16 v[80:83], v[144:147], v[210:213], v[80:83]
	v_mfma_f32_16x16x32_bf16 v[72:75], v[152:155], v[210:213], v[72:75]
	s_setprio 0
	s_setprio 1
	v_mfma_f32_16x16x32_bf16 v[116:119], v[166:169], v[182:185], v[116:119]
	v_mfma_f32_16x16x32_bf16 v[108:111], v[174:177], v[182:185], v[108:111]
	v_mfma_f32_16x16x32_bf16 v[100:103], v[166:169], v[190:193], v[100:103]
	v_mfma_f32_16x16x32_bf16 v[92:95], v[174:177], v[190:193], v[92:95]
	v_mfma_f32_16x16x32_bf16 v[84:87], v[166:169], v[198:201], v[84:87]
	v_mfma_f32_16x16x32_bf16 v[76:79], v[174:177], v[198:201], v[76:79]
	v_mfma_f32_16x16x32_bf16 v[68:71], v[166:169], v[206:209], v[68:71]
	v_mfma_f32_16x16x32_bf16 v[64:67], v[174:177], v[206:209], v[64:67]
	v_mfma_f32_16x16x32_bf16 v[116:119], v[170:173], v[186:189], v[116:119]
	v_mfma_f32_16x16x32_bf16 v[108:111], v[178:181], v[186:189], v[108:111]
	v_mfma_f32_16x16x32_bf16 v[100:103], v[170:173], v[194:197], v[100:103]
	v_mfma_f32_16x16x32_bf16 v[92:95], v[178:181], v[194:197], v[92:95]
	v_mfma_f32_16x16x32_bf16 v[84:87], v[170:173], v[202:205], v[84:87]
	v_mfma_f32_16x16x32_bf16 v[76:79], v[178:181], v[202:205], v[76:79]
	v_mfma_f32_16x16x32_bf16 v[68:71], v[170:173], v[210:213], v[68:71]
	v_mfma_f32_16x16x32_bf16 v[64:67], v[178:181], v[210:213], v[64:67]
	s_setprio 0
	s_barrier
; #define PG8_STAGE(bufoff, gbase, voff) do { _Pragma("unroll") for (int _i = 0; _i < 2; ++_i) \
;         __builtin_amdgcn_global_load_lds((const unsigned*)((const char*)(gbase) + (voff)[_i]), (LAS unsigned*)(lds + (bufoff) + ldsw + _i * 8192), 16, 0, 0); } while (0)
; #define PG8_LDA(dst, b, h) do { _Pragma("unroll") for (int m = 0; m < 4; ++m) _Pragma("unroll") for (int k = 0; k < 2; ++k) dst[m][k] = *(const LAS bf16x8*)(lds + PG8_SA(b, h) + aoff + m * 2048 + k * 1024); } while (0)
; #define PG8_MMA(ai, bj, At, Bt) do { __builtin_amdgcn_s_setprio(1); _Pragma("unroll") for (int m = 0; m < 4; ++m) _Pragma("unroll") for (int n = 0; n < 2; ++n) _Pragma("unroll") for (int k = 0; k < 2; ++k) \
;         acc[ai][bj][m][n] = __builtin_amdgcn_mfma_f32_16x16x32_bf16(Bt[n][k], At[m][k], acc[ai][bj][m][n], 0, 0, 0); __builtin_amdgcn_s_setprio(0); } while (0)
; #define PG8_WAIT_V(n) asm volatile("s_waitcnt vmcnt(" #n ")" ::: "memory")
; #define PG8_WAIT_L(n) asm volatile("s_waitcnt lgkmcnt(" #n ")" ::: "memory")
; #define PG8_BAR __builtin_amdgcn_s_barrier()
; #define PG8_SCHED __builtin_amdgcn_sched_barrier(0)
; template <int K, int LDA, int LDB, class Epi, class Sched>
; __device__ __forceinline__ void gemm_phase(LAS unsigned char* lds, const Gemm g, const Sched& S, const Epi& E, int wv) {
;     ...
;             PG8_LDA(At, 1, 1); PG8_STAGE(PG8_SB(1, 0), b3, voffB); PG8_STAGE(PG8_SB(1, 1), b3 + hstepB, voffB); PG8_STAGE(PG8_SA(1, 0), a3, voffA);
;             PG8_WAIT_V(8); PG8_WAIT_L(0); PG8_BAR; PG8_MMA(1, 0, At, B0); PG8_MMA(1, 1, At, B1); PG8_BAR; PG8_SCHED;
;         }
;         if (wr == 0) PG8_BAR;
	s_mov_b32 m0, s81
	ds_read_b128 v[182:185], v163 offset:49152
	ds_read_b128 v[186:189], v163 offset:50176
	ds_read_b128 v[190:193], v163 offset:51200
	ds_read_b128 v[194:197], v163 offset:52224
	ds_read_b128 v[198:201], v163 offset:53248
	ds_read_b128 v[202:205], v163 offset:54272
	ds_read_b128 v[206:209], v163 offset:55296
	ds_read_b128 v[210:213], v163 offset:56320
	s_add_u32 s98, s62, s10
	s_addc_u32 s99, s63, s11
	global_load_lds_dwordx4 v132, s[98:99]
	s_mov_b32 m0, s79
	s_nop 0
	global_load_lds_dwordx4 v128, s[98:99]
	s_mov_b32 m0, s80
	s_nop 0
	global_load_lds_dwordx4 v132, s[56:57]
	s_mov_b32 m0, s78
	s_nop 0
	global_load_lds_dwordx4 v128, s[56:57]
	s_mov_b32 m0, s71
	s_nop 0
	s_add_u32 s100, s60, s10
	s_addc_u32 s101, s61, s11
	global_load_lds_dwordx4 v134, s[100:101]
	s_mov_b32 m0, s72
	s_nop 0
	global_load_lds_dwordx4 v130, s[100:101]
	s_waitcnt vmcnt(8)
	s_waitcnt lgkmcnt(0)
	s_barrier
	s_setprio 1
	s_waitcnt lgkmcnt(0)
	v_mfma_f32_16x16x32_bf16 v[60:63], v[140:143], v[182:185], v[60:63]
	v_mfma_f32_16x16x32_bf16 v[56:59], v[148:151], v[182:185], v[56:59]
	v_mfma_f32_16x16x32_bf16 v[48:51], v[140:143], v[190:193], v[48:51]
	v_mfma_f32_16x16x32_bf16 v[40:43], v[148:151], v[190:193], v[40:43]
	v_mfma_f32_16x16x32_bf16 v[32:35], v[140:143], v[198:201], v[32:35]
	v_mfma_f32_16x16x32_bf16 v[24:27], v[148:151], v[198:201], v[24:27]
	v_mfma_f32_16x16x32_bf16 v[16:19], v[140:143], v[206:209], v[16:19]
	v_mfma_f32_16x16x32_bf16 v[8:11], v[148:151], v[206:209], v[8:11]
	v_mfma_f32_16x16x32_bf16 v[60:63], v[144:147], v[186:189], v[60:63]
	v_mfma_f32_16x16x32_bf16 v[56:59], v[152:155], v[186:189], v[56:59]
	v_mfma_f32_16x16x32_bf16 v[48:51], v[144:147], v[194:197], v[48:51]
	v_mfma_f32_16x16x32_bf16 v[40:43], v[152:155], v[194:197], v[40:43]
	v_mfma_f32_16x16x32_bf16 v[32:35], v[144:147], v[202:205], v[32:35]
	v_mfma_f32_16x16x32_bf16 v[24:27], v[152:155], v[202:205], v[24:27]
	v_mfma_f32_16x16x32_bf16 v[16:19], v[144:147], v[210:213], v[16:19]
	v_mfma_f32_16x16x32_bf16 v[8:11], v[152:155], v[210:213], v[8:11]
	s_setprio 0
	s_setprio 1
	v_mfma_f32_16x16x32_bf16 v[52:55], v[166:169], v[182:185], v[52:55]
	v_mfma_f32_16x16x32_bf16 v[44:47], v[174:177], v[182:185], v[44:47]
	v_mfma_f32_16x16x32_bf16 v[36:39], v[166:169], v[190:193], v[36:39]
	v_mfma_f32_16x16x32_bf16 v[28:31], v[174:177], v[190:193], v[28:31]
	v_mfma_f32_16x16x32_bf16 v[20:23], v[166:169], v[198:201], v[20:23]
	v_mfma_f32_16x16x32_bf16 v[12:15], v[174:177], v[198:201], v[12:15]
	v_mfma_f32_16x16x32_bf16 v[4:7], v[166:169], v[206:209], v[4:7]
	v_mfma_f32_16x16x32_bf16 v[0:3], v[174:177], v[206:209], v[0:3]
	v_mfma_f32_16x16x32_bf16 v[52:55], v[170:173], v[186:189], v[52:55]
	v_mfma_f32_16x16x32_bf16 v[44:47], v[178:181], v[186:189], v[44:47]
	v_mfma_f32_16x16x32_bf16 v[36:39], v[170:173], v[194:197], v[36:39]
	v_mfma_f32_16x16x32_bf16 v[28:31], v[178:181], v[194:197], v[28:31]
	v_mfma_f32_16x16x32_bf16 v[20:23], v[170:173], v[202:205], v[20:23]
	v_mfma_f32_16x16x32_bf16 v[12:15], v[178:181], v[202:205], v[12:15]
	v_mfma_f32_16x16x32_bf16 v[4:7], v[170:173], v[210:213], v[4:7]
	v_mfma_f32_16x16x32_bf16 v[0:3], v[178:181], v[210:213], v[0:3]
	s_setprio 0
	s_barrier
	s_andn2_b64 vcc, exec, s[8:9]
	s_mov_b64 s[56:57], -1
	s_mov_b64 s[8:9], 0
	s_mov_b64 s[58:59], 0x100
	s_cbranch_vccz .LBB0_1106
	s_and_b64 vcc, exec, s[28:29]
	s_cbranch_vccz .LBB0_1109
	s_barrier

; #define PG8_STAGE(bufoff, gbase, voff) do { _Pragma("unroll") for (int _i = 0; _i < 2; ++_i) \
;         __builtin_amdgcn_global_load_lds((const unsigned*)((const char*)(gbase) + (voff)[_i]), (LAS unsigned*)(lds + (bufoff) + ldsw + _i * 8192), 16, 0, 0); } while (0)
; #define PG8_LDA(dst, b, h) do { _Pragma("unroll") for (int m = 0; m < 4; ++m) _Pragma("unroll") for (int k = 0; k < 2; ++k) dst[m][k] = *(const LAS bf16x8*)(lds + PG8_SA(b, h) + aoff + m * 2048 + k * 1024); } while (0)
; #define PG8_LDB(dst, b, h) do { _Pragma("unroll") for (int n = 0; n < 2; ++n) _Pragma("unroll") for (int k = 0; k < 2; ++k) dst[n][k] = *(const LAS bf16x8*)(lds + PG8_SB(b, h) + boff + n * 2048 + k * 1024); } while (0)
; #define PG8_MMA(ai, bj, At, Bt) do { __builtin_amdgcn_s_setprio(1); _Pragma("unroll") for (int m = 0; m < 4; ++m) _Pragma("unroll") for (int n = 0; n < 2; ++n) _Pragma("unroll") for (int k = 0; k < 2; ++k) \
;         acc[ai][bj][m][n] = __builtin_amdgcn_mfma_f32_16x16x32_bf16(Bt[n][k], At[m][k], acc[ai][bj][m][n], 0, 0, 0); __builtin_amdgcn_s_setprio(0); } while (0)
; #define PG8_WAIT_V(n) asm volatile("s_waitcnt vmcnt(" #n ")" ::: "memory")
; #define PG8_WAIT_L(n) asm volatile("s_waitcnt lgkmcnt(" #n ")" ::: "memory")
; #define PG8_BAR __builtin_amdgcn_s_barrier()
; #define PG8_SCHED __builtin_amdgcn_sched_barrier(0)
; template <int K, int LDA, int LDB, class Epi, class Sched>
; __device__ __forceinline__ void gemm_phase(LAS unsigned char* lds, const Gemm g, const Sched& S, const Epi& E, int wv) {
;     ...
;             const bool last = (t == nt - 2);
;             const char* a1 = cA + (size_t)(t + 1) * kstep;
;             const char* a2 = last ? nA : cA + (size_t)(t + 2) * kstep; const char* b2 = last ? nB : cB + (size_t)(t + 2) * kstep;
;             const char* a3 = a2 + kstep; const char* b3 = b2 + kstep;
;             PG8_LDB(B0, 0, 0); PG8_LDB(B1, 0, 1); PG8_SCHED; PG8_LDA(At, 0, 0); PG8_STAGE(PG8_SA(1, 1), a1 + hstepA, voffA);
;             PG8_WAIT_V(8); PG8_WAIT_L(0); PG8_BAR; PG8_MMA(0, 0, At, B0); PG8_MMA(0, 1, At, B1); PG8_BAR; PG8_SCHED;
;             PG8_LDA(At, 0, 1); PG8_STAGE(PG8_SB(0, 0), b2, voffB); PG8_STAGE(PG8_SB(0, 1), b2 + hstepB, voffB); PG8_STAGE(PG8_SA(0, 0), a2, voffA);
;             PG8_WAIT_V(8); PG8_WAIT_L(0); PG8_BAR; PG8_MMA(1, 0, At, B0); PG8_MMA(1, 1, At, B1); PG8_BAR; PG8_SCHED;
.LBB0_1265:
	ds_read_b128 v[144:147], v185
	ds_read_b128 v[148:151], v185 offset:1024
	ds_read_b128 v[152:155], v185 offset:2048
	ds_read_b128 v[156:159], v185 offset:3072
	ds_read_b128 v[160:163], v186
	ds_read_b128 v[164:167], v186 offset:1024
	ds_read_b128 v[168:171], v186 offset:2048
	ds_read_b128 v[172:175], v186 offset:3072
	s_add_u32 s46, s44, 0xfff80080
	s_addc_u32 s47, s45, -1
	s_cmp_eq_u32 s62, 28
	s_cselect_b32 s49, s37, s47
	s_cselect_b32 s48, s58, s46
	s_cselect_b32 s47, s35, s61
	s_cselect_b32 s46, s59, s60
	v_lshl_add_u64 v[180:181], s[44:45], 0, v[136:137]
	s_add_i32 m0, s27, 0xc000
	ds_read_b128 v[176:179], v187
	ds_read_b128 v[188:191], v187 offset:1024
	ds_read_b128 v[192:195], v187 offset:2048
	ds_read_b128 v[196:199], v187 offset:3072
	ds_read_b128 v[200:203], v187 offset:4096
	ds_read_b128 v[204:207], v187 offset:5120
	ds_read_b128 v[208:211], v187 offset:6144
	ds_read_b128 v[212:215], v187 offset:7168
	global_load_lds_dwordx4 v136, s[44:45]
	v_lshl_add_u64 v[180:181], s[44:45], 0, v[138:139]
	s_add_i32 m0, s27, 0xe000
	s_nop 0
	global_load_lds_dwordx4 v138, s[44:45]
	s_waitcnt vmcnt(8)
	s_waitcnt lgkmcnt(0)
	s_barrier
	s_setprio 1
	s_waitcnt lgkmcnt(0)
	v_mfma_f32_16x16x32_bf16 v[124:127], v[144:147], v[176:179], v[124:127]
	v_mfma_f32_16x16x32_bf16 v[120:123], v[152:155], v[176:179], v[120:123]
	v_mfma_f32_16x16x32_bf16 v[112:115], v[144:147], v[192:195], v[112:115]
	v_mfma_f32_16x16x32_bf16 v[104:107], v[152:155], v[192:195], v[104:107]
	v_mfma_f32_16x16x32_bf16 v[92:95], v[144:147], v[200:203], v[92:95]
	v_mfma_f32_16x16x32_bf16 v[88:91], v[152:155], v[200:203], v[88:91]
	v_mfma_f32_16x16x32_bf16 v[80:83], v[144:147], v[208:211], v[80:83]
	v_mfma_f32_16x16x32_bf16 v[72:75], v[152:155], v[208:211], v[72:75]
	v_mfma_f32_16x16x32_bf16 v[124:127], v[148:151], v[188:191], v[124:127]
	v_mfma_f32_16x16x32_bf16 v[120:123], v[156:159], v[188:191], v[120:123]
	v_mfma_f32_16x16x32_bf16 v[112:115], v[148:151], v[196:199], v[112:115]
	v_mfma_f32_16x16x32_bf16 v[104:107], v[156:159], v[196:199], v[104:107]
	v_mfma_f32_16x16x32_bf16 v[92:95], v[148:151], v[204:207], v[92:95]
	v_mfma_f32_16x16x32_bf16 v[88:91], v[156:159], v[204:207], v[88:91]
	v_mfma_f32_16x16x32_bf16 v[80:83], v[148:151], v[212:215], v[80:83]
	v_mfma_f32_16x16x32_bf16 v[72:75], v[156:159], v[212:215], v[72:75]
	s_setprio 0
	s_setprio 1
	v_mfma_f32_16x16x32_bf16 v[116:119], v[160:163], v[176:179], v[116:119]
	v_mfma_f32_16x16x32_bf16 v[108:111], v[168:171], v[176:179], v[108:111]
	v_mfma_f32_16x16x32_bf16 v[100:103], v[160:163], v[192:195], v[100:103]
	v_mfma_f32_16x16x32_bf16 v[96:99], v[168:171], v[192:195], v[96:99]
	v_mfma_f32_16x16x32_bf16 v[84:87], v[160:163], v[200:203], v[84:87]
	v_mfma_f32_16x16x32_bf16 v[76:79], v[168:171], v[200:203], v[76:79]
	v_mfma_f32_16x16x32_bf16 v[68:71], v[160:163], v[208:211], v[68:71]
	v_mfma_f32_16x16x32_bf16 v[64:67], v[168:171], v[208:211], v[64:67]
	v_mfma_f32_16x16x32_bf16 v[116:119], v[164:167], v[188:191], v[116:119]
	v_mfma_f32_16x16x32_bf16 v[108:111], v[172:175], v[188:191], v[108:111]
	v_mfma_f32_16x16x32_bf16 v[100:103], v[164:167], v[196:199], v[100:103]
	v_mfma_f32_16x16x32_bf16 v[96:99], v[172:175], v[196:199], v[96:99]
	v_mfma_f32_16x16x32_bf16 v[84:87], v[164:167], v[204:207], v[84:87]
	v_mfma_f32_16x16x32_bf16 v[76:79], v[172:175], v[204:207], v[76:79]
	v_mfma_f32_16x16x32_bf16 v[68:71], v[164:167], v[212:215], v[68:71]
	v_mfma_f32_16x16x32_bf16 v[64:67], v[172:175], v[212:215], v[64:67]
	s_setprio 0
	s_barrier
	s_add_i32 s63, s55, s24
	v_lshl_add_u64 v[180:181], s[46:47], 0, v[132:133]
	s_mov_b32 m0, s63
	ds_read_b128 v[176:179], v187 offset:16384
	ds_read_b128 v[188:191], v187 offset:17408
	ds_read_b128 v[192:195], v187 offset:18432
	ds_read_b128 v[196:199], v187 offset:19456
	ds_read_b128 v[200:203], v187 offset:20480
	ds_read_b128 v[204:207], v187 offset:21504
	ds_read_b128 v[208:211], v187 offset:22528
	ds_read_b128 v[212:215], v187 offset:23552
	global_load_lds_dwordx4 v132, s[46:47]
	s_add_i32 m0, s63, 0x2000
	s_add_u32 s64, s46, 0x80000
	v_lshl_add_u64 v[216:217], s[46:47], 0, v[128:129]
	s_addc_u32 s65, s47, 0
	s_add_i32 s63, s56, s24
	global_load_lds_dwordx4 v128, s[46:47]
	v_lshl_add_u64 v[218:219], s[64:65], 0, v[132:133]
	s_mov_b32 m0, s63
	v_lshl_add_u64 v[220:221], s[48:49], 0, v[130:131]
	global_load_lds_dwordx4 v132, s[64:65]
	v_lshl_add_u64 v[218:219], s[64:65], 0, v[128:129]
	s_add_i32 m0, s63, 0x2000
	s_nop 0
	global_load_lds_dwordx4 v128, s[64:65]
	v_lshl_add_u64 v[218:219], s[48:49], 0, v[134:135]
	s_mov_b32 m0, s27
	s_nop 0
	global_load_lds_dwordx4 v134, s[48:49]
	s_mov_b32 m0, s43
	s_nop 0
	global_load_lds_dwordx4 v130, s[48:49]
	s_waitcnt vmcnt(8)
	s_waitcnt lgkmcnt(0)
	s_barrier
; #define PG8_STAGE(bufoff, gbase, voff) do { _Pragma("unroll") for (int _i = 0; _i < 2; ++_i) \
;         __builtin_amdgcn_global_load_lds((const unsigned*)((const char*)(gbase) + (voff)[_i]), (LAS unsigned*)(lds + (bufoff) + ldsw + _i * 8192), 16, 0, 0); } while (0)
; #define PG8_LDA(dst, b, h) do { _Pragma("unroll") for (int m = 0; m < 4; ++m) _Pragma("unroll") for (int k = 0; k < 2; ++k) dst[m][k] = *(const LAS bf16x8*)(lds + PG8_SA(b, h) + aoff + m * 2048 + k * 1024); } while (0)
; #define PG8_LDB(dst, b, h) do { _Pragma("unroll") for (int n = 0; n < 2; ++n) _Pragma("unroll") for (int k = 0; k < 2; ++k) dst[n][k] = *(const LAS bf16x8*)(lds + PG8_SB(b, h) + boff + n * 2048 + k * 1024); } while (0)
; #define PG8_MMA(ai, bj, At, Bt) do { __builtin_amdgcn_s_setprio(1); _Pragma("unroll") for (int m = 0; m < 4; ++m) _Pragma("unroll") for (int n = 0; n < 2; ++n) _Pragma("unroll") for (int k = 0; k < 2; ++k) \
;         acc[ai][bj][m][n] = __builtin_amdgcn_mfma_f32_16x16x32_bf16(Bt[n][k], At[m][k], acc[ai][bj][m][n], 0, 0, 0); __builtin_amdgcn_s_setprio(0); } while (0)
; #define PG8_WAIT_V(n) asm volatile("s_waitcnt vmcnt(" #n ")" ::: "memory")
; #define PG8_WAIT_L(n) asm volatile("s_waitcnt lgkmcnt(" #n ")" ::: "memory")
; #define PG8_BAR __builtin_amdgcn_s_barrier()
; #define PG8_SCHED __builtin_amdgcn_sched_barrier(0)
; template <int K, int LDA, int LDB, class Epi, class Sched>
; __device__ __forceinline__ void gemm_phase(LAS unsigned char* lds, const Gemm g, const Sched& S, const Epi& E, int wv) {
;     ...
;             PG8_WAIT_V(8); PG8_WAIT_L(0); PG8_BAR; PG8_MMA(1, 0, At, B0); PG8_MMA(1, 1, At, B1); PG8_BAR; PG8_SCHED;
;             PG8_LDB(B0, 1, 0); PG8_LDB(B1, 1, 1); PG8_SCHED; PG8_LDA(At, 1, 0); PG8_STAGE(PG8_SA(0, 1), a2 + hstepA, voffA);
;             PG8_WAIT_V(8); PG8_WAIT_L(0); PG8_BAR; PG8_MMA(0, 0, At, B0); PG8_MMA(0, 1, At, B1); PG8_BAR; PG8_SCHED;
	s_setprio 1
	s_waitcnt lgkmcnt(0)
	v_mfma_f32_16x16x32_bf16 v[60:63], v[144:147], v[176:179], v[60:63]
	v_mfma_f32_16x16x32_bf16 v[56:59], v[152:155], v[176:179], v[56:59]
	v_mfma_f32_16x16x32_bf16 v[48:51], v[144:147], v[192:195], v[48:51]
	v_mfma_f32_16x16x32_bf16 v[40:43], v[152:155], v[192:195], v[40:43]
	v_mfma_f32_16x16x32_bf16 v[28:31], v[144:147], v[200:203], v[28:31]
	v_mfma_f32_16x16x32_bf16 v[24:27], v[152:155], v[200:203], v[24:27]
	v_mfma_f32_16x16x32_bf16 v[16:19], v[144:147], v[208:211], v[16:19]
	v_mfma_f32_16x16x32_bf16 v[8:11], v[152:155], v[208:211], v[8:11]
	v_mfma_f32_16x16x32_bf16 v[60:63], v[148:151], v[188:191], v[60:63]
	v_mfma_f32_16x16x32_bf16 v[56:59], v[156:159], v[188:191], v[56:59]
	v_mfma_f32_16x16x32_bf16 v[48:51], v[148:151], v[196:199], v[48:51]
	v_mfma_f32_16x16x32_bf16 v[40:43], v[156:159], v[196:199], v[40:43]
	v_mfma_f32_16x16x32_bf16 v[28:31], v[148:151], v[204:207], v[28:31]
	v_mfma_f32_16x16x32_bf16 v[24:27], v[156:159], v[204:207], v[24:27]
	v_mfma_f32_16x16x32_bf16 v[16:19], v[148:151], v[212:215], v[16:19]
	v_mfma_f32_16x16x32_bf16 v[8:11], v[156:159], v[212:215], v[8:11]
	s_setprio 0
	s_setprio 1
	v_mfma_f32_16x16x32_bf16 v[52:55], v[160:163], v[176:179], v[52:55]
	v_mfma_f32_16x16x32_bf16 v[44:47], v[168:171], v[176:179], v[44:47]
	v_mfma_f32_16x16x32_bf16 v[36:39], v[160:163], v[192:195], v[36:39]
	v_mfma_f32_16x16x32_bf16 v[32:35], v[168:171], v[192:195], v[32:35]
	v_mfma_f32_16x16x32_bf16 v[20:23], v[160:163], v[200:203], v[20:23]
	v_mfma_f32_16x16x32_bf16 v[12:15], v[168:171], v[200:203], v[12:15]
	v_mfma_f32_16x16x32_bf16 v[4:7], v[160:163], v[208:211], v[4:7]
	v_mfma_f32_16x16x32_bf16 v[0:3], v[168:171], v[208:211], v[0:3]
	v_mfma_f32_16x16x32_bf16 v[52:55], v[164:167], v[188:191], v[52:55]
	v_mfma_f32_16x16x32_bf16 v[44:47], v[172:175], v[188:191], v[44:47]
	v_mfma_f32_16x16x32_bf16 v[36:39], v[164:167], v[196:199], v[36:39]
	v_mfma_f32_16x16x32_bf16 v[32:35], v[172:175], v[196:199], v[32:35]
	v_mfma_f32_16x16x32_bf16 v[20:23], v[164:167], v[204:207], v[20:23]
	v_mfma_f32_16x16x32_bf16 v[12:15], v[172:175], v[204:207], v[12:15]
	v_mfma_f32_16x16x32_bf16 v[4:7], v[164:167], v[212:215], v[4:7]
	v_mfma_f32_16x16x32_bf16 v[0:3], v[172:175], v[212:215], v[0:3]
	s_setprio 0
	s_barrier
	s_add_i32 s63, 0, 0x18000
	v_add_u32_e32 v140, s63, v183
	s_add_i32 s64, 0, 0x1c000
	ds_read_b128 v[144:147], v140
	ds_read_b128 v[148:151], v140 offset:1024
	ds_read_b128 v[152:155], v140 offset:2048
	ds_read_b128 v[156:159], v140 offset:3072
	v_add_u32_e32 v140, s64, v183
	ds_read_b128 v[160:163], v140
	ds_read_b128 v[164:167], v140 offset:1024
	ds_read_b128 v[168:171], v140 offset:2048
	ds_read_b128 v[172:175], v140 offset:3072
	s_add_u32 s48, s48, 0x80000
	s_addc_u32 s49, s49, 0
	s_mov_b32 m0, s50
	v_lshl_add_u64 v[224:225], s[48:49], 0, v[134:135]
	ds_read_b128 v[176:179], v187 offset:32768
	ds_read_b128 v[188:191], v187 offset:33792
	ds_read_b128 v[192:195], v187 offset:34816
	ds_read_b128 v[196:199], v187 offset:35840
	ds_read_b128 v[200:203], v187 offset:36864
	ds_read_b128 v[204:207], v187 offset:37888
	ds_read_b128 v[208:211], v187 offset:38912
	ds_read_b128 v[212:215], v187 offset:39936
	global_load_lds_dwordx4 v134, s[48:49]
	v_lshl_add_u64 v[224:225], s[48:49], 0, v[130:131]
	s_mov_b32 m0, s51
	s_nop 0
	global_load_lds_dwordx4 v130, s[48:49]
	s_waitcnt vmcnt(8)
	s_waitcnt lgkmcnt(0)
	s_barrier
	s_setprio 1
	s_waitcnt lgkmcnt(0)
	v_mfma_f32_16x16x32_bf16 v[124:127], v[144:147], v[176:179], v[124:127]
	v_mfma_f32_16x16x32_bf16 v[120:123], v[152:155], v[176:179], v[120:123]
	v_mfma_f32_16x16x32_bf16 v[112:115], v[144:147], v[192:195], v[112:115]
	v_mfma_f32_16x16x32_bf16 v[104:107], v[152:155], v[192:195], v[104:107]
	v_mfma_f32_16x16x32_bf16 v[92:95], v[144:147], v[200:203], v[92:95]
	v_mfma_f32_16x16x32_bf16 v[88:91], v[152:155], v[200:203], v[88:91]
	v_mfma_f32_16x16x32_bf16 v[80:83], v[144:147], v[208:211], v[80:83]
	v_mfma_f32_16x16x32_bf16 v[72:75], v[152:155], v[208:211], v[72:75]
	v_mfma_f32_16x16x32_bf16 v[124:127], v[148:151], v[188:191], v[124:127]
	v_mfma_f32_16x16x32_bf16 v[120:123], v[156:159], v[188:191], v[120:123]
	v_mfma_f32_16x16x32_bf16 v[112:115], v[148:151], v[196:199], v[112:115]
	v_mfma_f32_16x16x32_bf16 v[104:107], v[156:159], v[196:199], v[104:107]
	v_mfma_f32_16x16x32_bf16 v[92:95], v[148:151], v[204:207], v[92:95]
	v_mfma_f32_16x16x32_bf16 v[88:91], v[156:159], v[204:207], v[88:91]
	v_mfma_f32_16x16x32_bf16 v[80:83], v[148:151], v[212:215], v[80:83]
	v_mfma_f32_16x16x32_bf16 v[72:75], v[156:159], v[212:215], v[72:75]
	s_setprio 0
	s_setprio 1
	v_mfma_f32_16x16x32_bf16 v[116:119], v[160:163], v[176:179], v[116:119]
	v_mfma_f32_16x16x32_bf16 v[108:111], v[168:171], v[176:179], v[108:111]
	v_mfma_f32_16x16x32_bf16 v[100:103], v[160:163], v[192:195], v[100:103]
	v_mfma_f32_16x16x32_bf16 v[96:99], v[168:171], v[192:195], v[96:99]
	v_mfma_f32_16x16x32_bf16 v[84:87], v[160:163], v[200:203], v[84:87]
	v_mfma_f32_16x16x32_bf16 v[76:79], v[168:171], v[200:203], v[76:79]
	v_mfma_f32_16x16x32_bf16 v[68:71], v[160:163], v[208:211], v[68:71]
	v_mfma_f32_16x16x32_bf16 v[64:67], v[168:171], v[208:211], v[64:67]
	v_mfma_f32_16x16x32_bf16 v[116:119], v[164:167], v[188:191], v[116:119]
	v_mfma_f32_16x16x32_bf16 v[108:111], v[172:175], v[188:191], v[108:111]
	v_mfma_f32_16x16x32_bf16 v[100:103], v[164:167], v[196:199], v[100:103]
	v_mfma_f32_16x16x32_bf16 v[96:99], v[172:175], v[196:199], v[96:99]
	v_mfma_f32_16x16x32_bf16 v[84:87], v[164:167], v[204:207], v[84:87]
	v_mfma_f32_16x16x32_bf16 v[76:79], v[172:175], v[204:207], v[76:79]
	v_mfma_f32_16x16x32_bf16 v[68:71], v[164:167], v[212:215], v[68:71]
	v_mfma_f32_16x16x32_bf16 v[64:67], v[172:175], v[212:215], v[64:67]
	s_setprio 0
	s_barrier
; #define PG8_STAGE(bufoff, gbase, voff) do { _Pragma("unroll") for (int _i = 0; _i < 2; ++_i) \
;         __builtin_amdgcn_global_load_lds((const unsigned*)((const char*)(gbase) + (voff)[_i]), (LAS unsigned*)(lds + (bufoff) + ldsw + _i * 8192), 16, 0, 0); } while (0)
; #define PG8_LDA(dst, b, h) do { _Pragma("unroll") for (int m = 0; m < 4; ++m) _Pragma("unroll") for (int k = 0; k < 2; ++k) dst[m][k] = *(const LAS bf16x8*)(lds + PG8_SA(b, h) + aoff + m * 2048 + k * 1024); } while (0)
; #define PG8_MMA(ai, bj, At, Bt) do { __builtin_amdgcn_s_setprio(1); _Pragma("unroll") for (int m = 0; m < 4; ++m) _Pragma("unroll") for (int n = 0; n < 2; ++n) _Pragma("unroll") for (int k = 0; k < 2; ++k) \
;         acc[ai][bj][m][n] = __builtin_amdgcn_mfma_f32_16x16x32_bf16(Bt[n][k], At[m][k], acc[ai][bj][m][n], 0, 0, 0); __builtin_amdgcn_s_setprio(0); } while (0)
; #define PG8_WAIT_V(n) asm volatile("s_waitcnt vmcnt(" #n ")" ::: "memory")
; #define PG8_WAIT_L(n) asm volatile("s_waitcnt lgkmcnt(" #n ")" ::: "memory")
; #define PG8_BAR __builtin_amdgcn_s_barrier()
; #define PG8_SCHED __builtin_amdgcn_sched_barrier(0)
; template <int K, int LDA, int LDB, class Epi, class Sched>
; __device__ __forceinline__ void gemm_phase(LAS unsigned char* lds, const Gemm g, const Sched& S, const Epi& E, int wv) {
;     ...
;             PG8_LDA(At, 1, 1); PG8_STAGE(PG8_SB(1, 0), b3, voffB); PG8_STAGE(PG8_SB(1, 1), b3 + hstepB, voffB); PG8_STAGE(PG8_SA(1, 0), a3, voffA);
;             PG8_WAIT_V(8); PG8_WAIT_L(0); PG8_BAR; PG8_MMA(1, 0, At, B0); PG8_MMA(1, 1, At, B1); PG8_BAR; PG8_SCHED;
;         }
;         if (wr == 0) PG8_BAR;
	s_add_i32 s48, s63, s24
	v_lshl_add_u64 v[180:181], v[180:181], 0, s[20:21]
	s_mov_b32 m0, s48
	ds_read_b128 v[176:179], v187 offset:49152
	ds_read_b128 v[188:191], v187 offset:50176
	ds_read_b128 v[192:195], v187 offset:51200
	ds_read_b128 v[196:199], v187 offset:52224
	ds_read_b128 v[200:203], v187 offset:53248
	ds_read_b128 v[204:207], v187 offset:54272
	ds_read_b128 v[208:211], v187 offset:55296
	ds_read_b128 v[212:215], v187 offset:56320
	s_add_u32 s98, s46, s20
	s_addc_u32 s99, s47, s21
	global_load_lds_dwordx4 v132, s[98:99]
	s_add_i32 m0, s48, 0x2000
	s_add_u32 s46, s46, 0x80080
	v_lshl_add_u64 v[180:181], v[216:217], 0, s[20:21]
	s_addc_u32 s47, s47, 0
	s_add_i32 s48, s64, s24
	global_load_lds_dwordx4 v[180:181], off
	v_lshl_add_u64 v[180:181], s[46:47], 0, v[132:133]
	s_mov_b32 m0, s48
	s_nop 0
	global_load_lds_dwordx4 v132, s[46:47]
	v_lshl_add_u64 v[180:181], s[46:47], 0, v[128:129]
	s_add_i32 m0, s48, 0x2000
	s_nop 0
	global_load_lds_dwordx4 v128, s[46:47]
	v_lshl_add_u64 v[180:181], v[218:219], 0, s[20:21]
	s_mov_b32 m0, s53
	s_nop 0
	global_load_lds_dwordx4 v[180:181], off
	v_lshl_add_u64 v[180:181], v[220:221], 0, s[20:21]
	s_mov_b32 m0, s54
	s_nop 0
	global_load_lds_dwordx4 v[180:181], off
	s_waitcnt vmcnt(8)
	s_waitcnt lgkmcnt(0)
	s_barrier
	s_setprio 1
	s_waitcnt lgkmcnt(0)
	v_mfma_f32_16x16x32_bf16 v[60:63], v[144:147], v[176:179], v[60:63]
	v_mfma_f32_16x16x32_bf16 v[56:59], v[152:155], v[176:179], v[56:59]
	v_mfma_f32_16x16x32_bf16 v[48:51], v[144:147], v[192:195], v[48:51]
	v_mfma_f32_16x16x32_bf16 v[40:43], v[152:155], v[192:195], v[40:43]
	v_mfma_f32_16x16x32_bf16 v[28:31], v[144:147], v[200:203], v[28:31]
	v_mfma_f32_16x16x32_bf16 v[24:27], v[152:155], v[200:203], v[24:27]
	v_mfma_f32_16x16x32_bf16 v[16:19], v[144:147], v[208:211], v[16:19]
	v_mfma_f32_16x16x32_bf16 v[8:11], v[152:155], v[208:211], v[8:11]
	v_mfma_f32_16x16x32_bf16 v[60:63], v[148:151], v[188:191], v[60:63]
	v_mfma_f32_16x16x32_bf16 v[56:59], v[156:159], v[188:191], v[56:59]
	v_mfma_f32_16x16x32_bf16 v[48:51], v[148:151], v[196:199], v[48:51]
	v_mfma_f32_16x16x32_bf16 v[40:43], v[156:159], v[196:199], v[40:43]
	v_mfma_f32_16x16x32_bf16 v[28:31], v[148:151], v[204:207], v[28:31]
	v_mfma_f32_16x16x32_bf16 v[24:27], v[156:159], v[204:207], v[24:27]
	v_mfma_f32_16x16x32_bf16 v[16:19], v[148:151], v[212:215], v[16:19]
	v_mfma_f32_16x16x32_bf16 v[8:11], v[156:159], v[212:215], v[8:11]
	s_setprio 0
	s_setprio 1
	v_mfma_f32_16x16x32_bf16 v[52:55], v[160:163], v[176:179], v[52:55]
	v_mfma_f32_16x16x32_bf16 v[44:47], v[168:171], v[176:179], v[44:47]
	v_mfma_f32_16x16x32_bf16 v[36:39], v[160:163], v[192:195], v[36:39]
	v_mfma_f32_16x16x32_bf16 v[32:35], v[168:171], v[192:195], v[32:35]
	v_mfma_f32_16x16x32_bf16 v[20:23], v[160:163], v[200:203], v[20:23]
	v_mfma_f32_16x16x32_bf16 v[12:15], v[168:171], v[200:203], v[12:15]
	v_mfma_f32_16x16x32_bf16 v[4:7], v[160:163], v[208:211], v[4:7]
	v_mfma_f32_16x16x32_bf16 v[0:3], v[168:171], v[208:211], v[0:3]
	v_mfma_f32_16x16x32_bf16 v[52:55], v[164:167], v[188:191], v[52:55]
	v_mfma_f32_16x16x32_bf16 v[44:47], v[172:175], v[188:191], v[44:47]
	v_mfma_f32_16x16x32_bf16 v[36:39], v[164:167], v[196:199], v[36:39]
	v_mfma_f32_16x16x32_bf16 v[32:35], v[172:175], v[196:199], v[32:35]
	v_mfma_f32_16x16x32_bf16 v[20:23], v[164:167], v[204:207], v[20:23]
	v_mfma_f32_16x16x32_bf16 v[12:15], v[172:175], v[204:207], v[12:15]
	v_mfma_f32_16x16x32_bf16 v[4:7], v[164:167], v[212:215], v[4:7]
	v_mfma_f32_16x16x32_bf16 v[0:3], v[172:175], v[212:215], v[0:3]
	s_setprio 0
	s_barrier
	s_add_i32 s62, s62, 2
	s_add_u32 s44, s44, 0x100
	s_addc_u32 s45, s45, 0
	s_add_u32 s60, s60, 0x100
	s_addc_u32 s61, s61, 0
	s_cmp_gt_u32 s62, 29
	s_cbranch_scc0 .LBB0_1265
	s_and_b64 vcc, exec, s[28:29]
	s_cbranch_vccz .LBB0_1268
	s_barrier
